# loop-edge/branch edit (asm guide 7.12): solver row tails test the wave-uniform mask with s_cmp_eq_u64 + s_cbranch_scc1 instead of saving and restoring exec
# speedup vs baseline: 1.0002x; 1.0002x over previous
.LBB0_807:
	s_or_b64 exec, exec, s[0:1]
	v_lshl_add_u32 v11, v1, 2, s76
	v_and_b32_e32 v255, 3, v180
	v_lshl_add_u32 v255, v255, 2, v11
	ds_read_u16 v238, v18 offset:544
	ds_read_b32 v239, v16 offset:8
	ds_read_b32 v254, v15 offset:8
	ds_read_b32 v240, v255 offset:256
	s_waitcnt lgkmcnt(0)
	v_mul_f32_dpp v4, v240, v2 quad_perm:[0,0,0,0] row_mask:0xf bank_mask:0xf
	ds_read_b32 v240, v255 offset:512
	v_sub_f32_e32 v3, v3, v4
	v_lshlrev_b32_e32 v4, 16, v238
	v_mul_f32_e32 v4, v239, v4
	s_cmp_eq_u64 s[16:17], 0
	s_cbranch_scc1 .LBB0_809
	v_mul_f32_e32 v4, v4, v254
.LBB0_809:
	ds_read_u16 v238, v18 offset:816
	ds_read_b32 v239, v16 offset:12
	ds_read_b32 v254, v15 offset:12
	s_waitcnt lgkmcnt(3)
	v_mul_f32_dpp v5, v240, v2 quad_perm:[0,0,0,0] row_mask:0xf bank_mask:0xf
	v_mul_f32_dpp v6, v240, v3 quad_perm:[1,1,1,1] row_mask:0xf bank_mask:0xf
	ds_read_b32 v240, v255 offset:768
	v_add_f32_e32 v5, v5, v6
	v_sub_f32_e32 v4, v4, v5
	s_waitcnt lgkmcnt(1)
	v_lshlrev_b32_e32 v5, 16, v238
	v_mul_f32_e32 v5, v239, v5
	s_cmp_eq_u64 s[16:17], 0
	s_cbranch_scc1 .LBB0_811
	v_mul_f32_e32 v5, v5, v254
.LBB0_811:
	ds_read_u16 v238, v18 offset:1088
	ds_read_b32 v239, v16 offset:16
	ds_read_b32 v254, v15 offset:16
	s_waitcnt lgkmcnt(3)
	v_mul_f32_dpp v6, v240, v2 quad_perm:[0,0,0,0] row_mask:0xf bank_mask:0xf
	v_mul_f32_dpp v7, v240, v3 quad_perm:[1,1,1,1] row_mask:0xf bank_mask:0xf
	v_mul_f32_dpp v8, v240, v4 quad_perm:[2,2,2,2] row_mask:0xf bank_mask:0xf
	ds_read_b32 v240, v255 offset:1024
	v_add_f32_e32 v6, v6, v7
	v_add_f32_e32 v6, v8, v6
	v_sub_f32_e32 v5, v5, v6
	s_waitcnt lgkmcnt(1)
	v_lshlrev_b32_e32 v6, 16, v238
	v_mul_f32_e32 v6, v239, v6
	s_cmp_eq_u64 s[16:17], 0
	s_cbranch_scc1 .LBB0_813
	v_mul_f32_e32 v6, v6, v254
.LBB0_813:
	ds_read_u16 v238, v18 offset:1360
	ds_read_b32 v239, v16 offset:20
	ds_read_b32 v254, v15 offset:20
	s_waitcnt lgkmcnt(3)
	v_mul_f32_dpp v7, v240, v2 quad_perm:[0,0,0,0] row_mask:0xf bank_mask:0xf
	v_mul_f32_dpp v8, v240, v3 quad_perm:[1,1,1,1] row_mask:0xf bank_mask:0xf
	v_mul_f32_dpp v9, v240, v4 quad_perm:[2,2,2,2] row_mask:0xf bank_mask:0xf
	v_mul_f32_dpp v10, v240, v5 quad_perm:[3,3,3,3] row_mask:0xf bank_mask:0xf
	ds_read_b32 v240, v255 offset:1280
	ds_read_b32 v241, v255 offset:1296
	v_add_f32_e32 v7, v7, v8
	v_add_f32_e32 v8, v9, v10
	v_add_f32_e32 v7, v7, v8
	v_sub_f32_e32 v6, v6, v7
	s_waitcnt lgkmcnt(2)
	v_lshlrev_b32_e32 v7, 16, v238
	v_mul_f32_e32 v7, v239, v7
	s_cmp_eq_u64 s[16:17], 0
	s_cbranch_scc1 .LBB0_815
	v_mul_f32_e32 v7, v7, v254
.LBB0_815:
	ds_read_u16 v238, v18 offset:1632
	ds_read_b32 v239, v16 offset:24
	ds_read_b32 v254, v15 offset:24
	s_waitcnt lgkmcnt(4)
	v_mul_f32_dpp v8, v240, v2 quad_perm:[0,0,0,0] row_mask:0xf bank_mask:0xf
	v_mul_f32_dpp v9, v240, v3 quad_perm:[1,1,1,1] row_mask:0xf bank_mask:0xf
	v_mul_f32_dpp v10, v240, v4 quad_perm:[2,2,2,2] row_mask:0xf bank_mask:0xf
	v_mul_f32_dpp v12, v240, v5 quad_perm:[3,3,3,3] row_mask:0xf bank_mask:0xf
	s_waitcnt lgkmcnt(3)
	v_fmac_f32_dpp v8, v241, v6 quad_perm:[0,0,0,0] row_mask:0xf bank_mask:0xf
	ds_read_b32 v240, v255 offset:1536
	ds_read_b32 v241, v255 offset:1552
	v_add_f32_e32 v8, v9, v8
	v_add_f32_e32 v9, v10, v12
	v_add_f32_e32 v8, v9, v8
	v_sub_f32_e32 v7, v7, v8
	s_waitcnt lgkmcnt(2)
	v_lshlrev_b32_e32 v8, 16, v238
	v_mul_f32_e32 v8, v239, v8
	s_cmp_eq_u64 s[16:17], 0
	s_cbranch_scc1 .LBB0_817
	v_mul_f32_e32 v8, v8, v254
.LBB0_817:
	ds_read_u16 v238, v18 offset:1904
	ds_read_b32 v239, v16 offset:28
	ds_read_b32 v254, v15 offset:28
	s_waitcnt lgkmcnt(4)
	v_mul_f32_dpp v9, v240, v2 quad_perm:[0,0,0,0] row_mask:0xf bank_mask:0xf
	v_mul_f32_dpp v10, v240, v3 quad_perm:[1,1,1,1] row_mask:0xf bank_mask:0xf
	v_mul_f32_dpp v12, v240, v4 quad_perm:[2,2,2,2] row_mask:0xf bank_mask:0xf
	v_mul_f32_dpp v13, v240, v5 quad_perm:[3,3,3,3] row_mask:0xf bank_mask:0xf
	s_waitcnt lgkmcnt(3)
	v_fmac_f32_dpp v9, v241, v6 quad_perm:[0,0,0,0] row_mask:0xf bank_mask:0xf
	v_fmac_f32_dpp v10, v241, v7 quad_perm:[1,1,1,1] row_mask:0xf bank_mask:0xf
	ds_read_b32 v240, v255 offset:1792
	ds_read_b32 v241, v255 offset:1808
	v_add_f32_e32 v9, v9, v10
	v_add_f32_e32 v10, v12, v13
	v_add_f32_e32 v9, v10, v9
	v_sub_f32_e32 v8, v8, v9
	s_waitcnt lgkmcnt(2)
	v_lshlrev_b32_e32 v9, 16, v238
	v_mul_f32_e32 v9, v239, v9
	s_cmp_eq_u64 s[16:17], 0
	s_cbranch_scc1 .LBB0_819
	v_mul_f32_e32 v9, v9, v254
.LBB0_819:
	ds_read_u16 v238, v18 offset:2176
	ds_read_b32 v239, v16 offset:32
	ds_read_b32 v254, v15 offset:32
	s_waitcnt lgkmcnt(4)
	v_mul_f32_dpp v10, v240, v2 quad_perm:[0,0,0,0] row_mask:0xf bank_mask:0xf
	v_mul_f32_dpp v12, v240, v3 quad_perm:[1,1,1,1] row_mask:0xf bank_mask:0xf
	v_mul_f32_dpp v13, v240, v4 quad_perm:[2,2,2,2] row_mask:0xf bank_mask:0xf
	v_mul_f32_dpp v14, v240, v5 quad_perm:[3,3,3,3] row_mask:0xf bank_mask:0xf
	s_waitcnt lgkmcnt(3)
	v_fmac_f32_dpp v10, v241, v6 quad_perm:[0,0,0,0] row_mask:0xf bank_mask:0xf
	v_fmac_f32_dpp v12, v241, v7 quad_perm:[1,1,1,1] row_mask:0xf bank_mask:0xf
	v_fmac_f32_dpp v13, v241, v8 quad_perm:[2,2,2,2] row_mask:0xf bank_mask:0xf
	ds_read_b32 v240, v255 offset:2048
	ds_read_b32 v241, v255 offset:2064
	v_add_f32_e32 v10, v10, v12
	v_add_f32_e32 v12, v14, v13
	v_add_f32_e32 v10, v10, v12
	v_sub_f32_e32 v9, v9, v10
	s_waitcnt lgkmcnt(2)
	v_lshlrev_b32_e32 v10, 16, v238
	v_mul_f32_e32 v10, v239, v10
	s_cmp_eq_u64 s[16:17], 0
	s_cbranch_scc1 .LBB0_821
	v_mul_f32_e32 v10, v10, v254
.LBB0_821:
	ds_read_u16 v238, v18 offset:2448
	ds_read_b32 v239, v16 offset:36
	ds_read_b32 v254, v15 offset:36
	s_waitcnt lgkmcnt(4)
	v_mul_f32_dpp v12, v240, v2 quad_perm:[0,0,0,0] row_mask:0xf bank_mask:0xf
	v_mul_f32_dpp v13, v240, v3 quad_perm:[1,1,1,1] row_mask:0xf bank_mask:0xf
	v_mul_f32_dpp v14, v240, v4 quad_perm:[2,2,2,2] row_mask:0xf bank_mask:0xf
	v_mul_f32_dpp v17, v240, v5 quad_perm:[3,3,3,3] row_mask:0xf bank_mask:0xf
	s_waitcnt lgkmcnt(3)
	v_fmac_f32_dpp v12, v241, v6 quad_perm:[0,0,0,0] row_mask:0xf bank_mask:0xf
	v_fmac_f32_dpp v13, v241, v7 quad_perm:[1,1,1,1] row_mask:0xf bank_mask:0xf
	v_fmac_f32_dpp v14, v241, v8 quad_perm:[2,2,2,2] row_mask:0xf bank_mask:0xf
	v_fmac_f32_dpp v17, v241, v9 quad_perm:[3,3,3,3] row_mask:0xf bank_mask:0xf
	ds_read_b32 v240, v255 offset:2304
	ds_read_b32 v241, v255 offset:2320
	ds_read_b32 v242, v255 offset:2336
	v_add_f32_e32 v12, v12, v13
	v_add_f32_e32 v13, v14, v17
	v_add_f32_e32 v12, v12, v13
	v_sub_f32_e32 v10, v10, v12
	s_waitcnt lgkmcnt(3)
	v_lshlrev_b32_e32 v12, 16, v238
	v_mul_f32_e32 v12, v239, v12
	s_cmp_eq_u64 s[16:17], 0
	s_cbranch_scc1 .LBB0_823
	v_mul_f32_e32 v12, v12, v254
.LBB0_823:
	ds_read_u16 v238, v18 offset:2720
	ds_read_b32 v239, v16 offset:40
	ds_read_b32 v254, v15 offset:40
	s_waitcnt lgkmcnt(5)
	v_mul_f32_dpp v13, v240, v2 quad_perm:[0,0,0,0] row_mask:0xf bank_mask:0xf
	v_mul_f32_dpp v14, v240, v3 quad_perm:[1,1,1,1] row_mask:0xf bank_mask:0xf
	v_mul_f32_dpp v17, v240, v4 quad_perm:[2,2,2,2] row_mask:0xf bank_mask:0xf
	v_mul_f32_dpp v19, v240, v5 quad_perm:[3,3,3,3] row_mask:0xf bank_mask:0xf
	s_waitcnt lgkmcnt(4)
	v_fmac_f32_dpp v13, v241, v6 quad_perm:[0,0,0,0] row_mask:0xf bank_mask:0xf
	v_fmac_f32_dpp v14, v241, v7 quad_perm:[1,1,1,1] row_mask:0xf bank_mask:0xf
	v_fmac_f32_dpp v17, v241, v8 quad_perm:[2,2,2,2] row_mask:0xf bank_mask:0xf
	v_fmac_f32_dpp v19, v241, v9 quad_perm:[3,3,3,3] row_mask:0xf bank_mask:0xf
	s_waitcnt lgkmcnt(3)
	v_fmac_f32_dpp v13, v242, v10 quad_perm:[0,0,0,0] row_mask:0xf bank_mask:0xf
	ds_read_b32 v240, v255 offset:2560
	ds_read_b32 v241, v255 offset:2576
	ds_read_b32 v242, v255 offset:2592
	v_add_f32_e32 v13, v14, v13
	v_add_f32_e32 v14, v17, v19
	v_add_f32_e32 v13, v14, v13
	v_sub_f32_e32 v12, v12, v13
	s_waitcnt lgkmcnt(3)
	v_lshlrev_b32_e32 v13, 16, v238
	v_mul_f32_e32 v13, v239, v13
	s_cmp_eq_u64 s[16:17], 0
	s_cbranch_scc1 .LBB0_825
	v_mul_f32_e32 v13, v13, v254
.LBB0_825:
	ds_read_u16 v238, v18 offset:2992
	ds_read_b32 v239, v16 offset:44
	ds_read_b32 v254, v15 offset:44
	s_waitcnt lgkmcnt(5)
	v_mul_f32_dpp v14, v240, v2 quad_perm:[0,0,0,0] row_mask:0xf bank_mask:0xf
	v_mul_f32_dpp v17, v240, v3 quad_perm:[1,1,1,1] row_mask:0xf bank_mask:0xf
	v_mul_f32_dpp v19, v240, v4 quad_perm:[2,2,2,2] row_mask:0xf bank_mask:0xf
	v_mul_f32_dpp v28, v240, v5 quad_perm:[3,3,3,3] row_mask:0xf bank_mask:0xf
	s_waitcnt lgkmcnt(4)
	v_fmac_f32_dpp v14, v241, v6 quad_perm:[0,0,0,0] row_mask:0xf bank_mask:0xf
	v_fmac_f32_dpp v17, v241, v7 quad_perm:[1,1,1,1] row_mask:0xf bank_mask:0xf
	v_fmac_f32_dpp v19, v241, v8 quad_perm:[2,2,2,2] row_mask:0xf bank_mask:0xf
	v_fmac_f32_dpp v28, v241, v9 quad_perm:[3,3,3,3] row_mask:0xf bank_mask:0xf
	s_waitcnt lgkmcnt(3)
	v_fmac_f32_dpp v14, v242, v10 quad_perm:[0,0,0,0] row_mask:0xf bank_mask:0xf
	v_fmac_f32_dpp v17, v242, v12 quad_perm:[1,1,1,1] row_mask:0xf bank_mask:0xf
	ds_read_b32 v240, v255 offset:2816
	ds_read_b32 v241, v255 offset:2832
	ds_read_b32 v242, v255 offset:2848
	v_add_f32_e32 v14, v14, v17
	v_add_f32_e32 v17, v19, v28
	v_add_f32_e32 v14, v17, v14
	v_sub_f32_e32 v13, v13, v14
	s_waitcnt lgkmcnt(3)
	v_lshlrev_b32_e32 v14, 16, v238
	v_mul_f32_e32 v14, v239, v14
	s_cmp_eq_u64 s[16:17], 0
	s_cbranch_scc1 .LBB0_827
	v_mul_f32_e32 v14, v14, v254
.LBB0_827:
	ds_read_u16 v238, v18 offset:3264
	ds_read_b32 v239, v16 offset:48
	ds_read_b32 v254, v15 offset:48
	s_waitcnt lgkmcnt(5)
	v_mul_f32_dpp v17, v240, v2 quad_perm:[0,0,0,0] row_mask:0xf bank_mask:0xf
	v_mul_f32_dpp v19, v240, v3 quad_perm:[1,1,1,1] row_mask:0xf bank_mask:0xf
	v_mul_f32_dpp v28, v240, v4 quad_perm:[2,2,2,2] row_mask:0xf bank_mask:0xf
	v_mul_f32_dpp v35, v240, v5 quad_perm:[3,3,3,3] row_mask:0xf bank_mask:0xf
	s_waitcnt lgkmcnt(4)
	v_fmac_f32_dpp v17, v241, v6 quad_perm:[0,0,0,0] row_mask:0xf bank_mask:0xf
	v_fmac_f32_dpp v19, v241, v7 quad_perm:[1,1,1,1] row_mask:0xf bank_mask:0xf
	v_fmac_f32_dpp v28, v241, v8 quad_perm:[2,2,2,2] row_mask:0xf bank_mask:0xf
	v_fmac_f32_dpp v35, v241, v9 quad_perm:[3,3,3,3] row_mask:0xf bank_mask:0xf
	s_waitcnt lgkmcnt(3)
	v_fmac_f32_dpp v17, v242, v10 quad_perm:[0,0,0,0] row_mask:0xf bank_mask:0xf
	v_fmac_f32_dpp v19, v242, v12 quad_perm:[1,1,1,1] row_mask:0xf bank_mask:0xf
	v_fmac_f32_dpp v28, v242, v13 quad_perm:[2,2,2,2] row_mask:0xf bank_mask:0xf
	ds_read_b32 v240, v255 offset:3072
	ds_read_b32 v241, v255 offset:3088
	ds_read_b32 v242, v255 offset:3104
	v_add_f32_e32 v17, v17, v19
	v_add_f32_e32 v19, v35, v28
	v_add_f32_e32 v17, v17, v19
	v_sub_f32_e32 v14, v14, v17
	s_waitcnt lgkmcnt(3)
	v_lshlrev_b32_e32 v17, 16, v238
	v_mul_f32_e32 v17, v239, v17
	s_cmp_eq_u64 s[16:17], 0
	s_cbranch_scc1 .LBB0_829
	v_mul_f32_e32 v17, v17, v254
.LBB0_829:
	ds_read_u16 v238, v18 offset:3536
	ds_read_b32 v239, v16 offset:52
	ds_read_b32 v254, v15 offset:52
	s_waitcnt lgkmcnt(5)
	v_mul_f32_dpp v19, v240, v2 quad_perm:[0,0,0,0] row_mask:0xf bank_mask:0xf
	v_mul_f32_dpp v28, v240, v3 quad_perm:[1,1,1,1] row_mask:0xf bank_mask:0xf
	v_mul_f32_dpp v35, v240, v4 quad_perm:[2,2,2,2] row_mask:0xf bank_mask:0xf
	v_mul_f32_dpp v36, v240, v5 quad_perm:[3,3,3,3] row_mask:0xf bank_mask:0xf
	s_waitcnt lgkmcnt(4)
	v_fmac_f32_dpp v19, v241, v6 quad_perm:[0,0,0,0] row_mask:0xf bank_mask:0xf
	v_fmac_f32_dpp v28, v241, v7 quad_perm:[1,1,1,1] row_mask:0xf bank_mask:0xf
	v_fmac_f32_dpp v35, v241, v8 quad_perm:[2,2,2,2] row_mask:0xf bank_mask:0xf
	v_fmac_f32_dpp v36, v241, v9 quad_perm:[3,3,3,3] row_mask:0xf bank_mask:0xf
	s_waitcnt lgkmcnt(3)
	v_fmac_f32_dpp v19, v242, v10 quad_perm:[0,0,0,0] row_mask:0xf bank_mask:0xf
	v_fmac_f32_dpp v28, v242, v12 quad_perm:[1,1,1,1] row_mask:0xf bank_mask:0xf
	v_fmac_f32_dpp v35, v242, v13 quad_perm:[2,2,2,2] row_mask:0xf bank_mask:0xf
	v_fmac_f32_dpp v36, v242, v14 quad_perm:[3,3,3,3] row_mask:0xf bank_mask:0xf
	ds_read_b32 v240, v255 offset:3328
	ds_read_b32 v241, v255 offset:3344
	ds_read_b32 v242, v255 offset:3360
	ds_read_b32 v243, v255 offset:3376
	v_add_f32_e32 v19, v19, v28
	v_add_f32_e32 v28, v35, v36
	v_add_f32_e32 v19, v19, v28
	v_sub_f32_e32 v17, v17, v19
	s_waitcnt lgkmcnt(4)
	v_lshlrev_b32_e32 v19, 16, v238
	v_mul_f32_e32 v19, v239, v19
	s_cmp_eq_u64 s[16:17], 0
	s_cbranch_scc1 .LBB0_831
	v_mul_f32_e32 v19, v19, v254
.LBB0_831:
	ds_read_u16 v238, v18 offset:3808
	ds_read_b32 v239, v16 offset:56
	ds_read_b32 v254, v15 offset:56
	s_waitcnt lgkmcnt(6)
	v_mul_f32_dpp v28, v240, v2 quad_perm:[0,0,0,0] row_mask:0xf bank_mask:0xf
	v_mul_f32_dpp v35, v240, v3 quad_perm:[1,1,1,1] row_mask:0xf bank_mask:0xf
	v_mul_f32_dpp v36, v240, v4 quad_perm:[2,2,2,2] row_mask:0xf bank_mask:0xf
	v_mul_f32_dpp v37, v240, v5 quad_perm:[3,3,3,3] row_mask:0xf bank_mask:0xf
	s_waitcnt lgkmcnt(5)
	v_fmac_f32_dpp v28, v241, v6 quad_perm:[0,0,0,0] row_mask:0xf bank_mask:0xf
	v_fmac_f32_dpp v35, v241, v7 quad_perm:[1,1,1,1] row_mask:0xf bank_mask:0xf
	v_fmac_f32_dpp v36, v241, v8 quad_perm:[2,2,2,2] row_mask:0xf bank_mask:0xf
	v_fmac_f32_dpp v37, v241, v9 quad_perm:[3,3,3,3] row_mask:0xf bank_mask:0xf
	s_waitcnt lgkmcnt(4)
	v_fmac_f32_dpp v28, v242, v10 quad_perm:[0,0,0,0] row_mask:0xf bank_mask:0xf
	v_fmac_f32_dpp v35, v242, v12 quad_perm:[1,1,1,1] row_mask:0xf bank_mask:0xf
	v_fmac_f32_dpp v36, v242, v13 quad_perm:[2,2,2,2] row_mask:0xf bank_mask:0xf
	v_fmac_f32_dpp v37, v242, v14 quad_perm:[3,3,3,3] row_mask:0xf bank_mask:0xf
	s_waitcnt lgkmcnt(3)
	v_fmac_f32_dpp v28, v243, v17 quad_perm:[0,0,0,0] row_mask:0xf bank_mask:0xf
	ds_read_b32 v240, v255 offset:3584
	ds_read_b32 v241, v255 offset:3600
	ds_read_b32 v242, v255 offset:3616
	ds_read_b32 v243, v255 offset:3632
	v_add_f32_e32 v28, v35, v28
	v_add_f32_e32 v35, v36, v37
	v_add_f32_e32 v28, v35, v28
	v_sub_f32_e32 v19, v19, v28
	s_waitcnt lgkmcnt(4)
	v_lshlrev_b32_e32 v28, 16, v238
	v_mul_f32_e32 v28, v239, v28
	s_cmp_eq_u64 s[16:17], 0
	s_cbranch_scc1 .LBB0_833
	v_mul_f32_e32 v28, v28, v254
.LBB0_833:
	ds_read_u16 v238, v18 offset:4080
	ds_read_b32 v239, v16 offset:60
	ds_read_b32 v254, v15 offset:60
	s_waitcnt lgkmcnt(6)
	v_mul_f32_dpp v35, v240, v2 quad_perm:[0,0,0,0] row_mask:0xf bank_mask:0xf
	v_mul_f32_dpp v36, v240, v3 quad_perm:[1,1,1,1] row_mask:0xf bank_mask:0xf
	v_mul_f32_dpp v37, v240, v4 quad_perm:[2,2,2,2] row_mask:0xf bank_mask:0xf
	v_mul_f32_dpp v38, v240, v5 quad_perm:[3,3,3,3] row_mask:0xf bank_mask:0xf
	s_waitcnt lgkmcnt(5)
	v_fmac_f32_dpp v35, v241, v6 quad_perm:[0,0,0,0] row_mask:0xf bank_mask:0xf
	v_fmac_f32_dpp v36, v241, v7 quad_perm:[1,1,1,1] row_mask:0xf bank_mask:0xf
	v_fmac_f32_dpp v37, v241, v8 quad_perm:[2,2,2,2] row_mask:0xf bank_mask:0xf
	v_fmac_f32_dpp v38, v241, v9 quad_perm:[3,3,3,3] row_mask:0xf bank_mask:0xf
	s_waitcnt lgkmcnt(4)
	v_fmac_f32_dpp v35, v242, v10 quad_perm:[0,0,0,0] row_mask:0xf bank_mask:0xf
	v_fmac_f32_dpp v36, v242, v12 quad_perm:[1,1,1,1] row_mask:0xf bank_mask:0xf
	v_fmac_f32_dpp v37, v242, v13 quad_perm:[2,2,2,2] row_mask:0xf bank_mask:0xf
	v_fmac_f32_dpp v38, v242, v14 quad_perm:[3,3,3,3] row_mask:0xf bank_mask:0xf
	s_waitcnt lgkmcnt(3)
	v_fmac_f32_dpp v35, v243, v17 quad_perm:[0,0,0,0] row_mask:0xf bank_mask:0xf
	v_fmac_f32_dpp v36, v243, v19 quad_perm:[1,1,1,1] row_mask:0xf bank_mask:0xf
	ds_read_b32 v240, v255 offset:3840
	ds_read_b32 v241, v255 offset:3856
	ds_read_b32 v242, v255 offset:3872
	ds_read_b32 v243, v255 offset:3888
	v_add_f32_e32 v35, v35, v36
	v_add_f32_e32 v36, v37, v38
	v_add_f32_e32 v35, v36, v35
	v_sub_f32_e32 v28, v28, v35
	s_waitcnt lgkmcnt(4)
	v_lshlrev_b32_e32 v35, 16, v238
	v_mul_f32_e32 v35, v239, v35
	s_cmp_eq_u64 s[16:17], 0
	s_cbranch_scc1 .LBB0_835
	v_mul_f32_e32 v35, v35, v254
.LBB0_835:
	ds_read_u16 v238, v18 offset:4352
	ds_read_b32 v239, v16 offset:64
	ds_read_b32 v254, v15 offset:64
	s_waitcnt lgkmcnt(6)
	v_mul_f32_dpp v36, v240, v2 quad_perm:[0,0,0,0] row_mask:0xf bank_mask:0xf
	v_mul_f32_dpp v37, v240, v3 quad_perm:[1,1,1,1] row_mask:0xf bank_mask:0xf
	v_mul_f32_dpp v38, v240, v4 quad_perm:[2,2,2,2] row_mask:0xf bank_mask:0xf
	v_mul_f32_dpp v39, v240, v5 quad_perm:[3,3,3,3] row_mask:0xf bank_mask:0xf
	s_waitcnt lgkmcnt(5)
	v_fmac_f32_dpp v36, v241, v6 quad_perm:[0,0,0,0] row_mask:0xf bank_mask:0xf
	v_fmac_f32_dpp v37, v241, v7 quad_perm:[1,1,1,1] row_mask:0xf bank_mask:0xf
	v_fmac_f32_dpp v38, v241, v8 quad_perm:[2,2,2,2] row_mask:0xf bank_mask:0xf
	v_fmac_f32_dpp v39, v241, v9 quad_perm:[3,3,3,3] row_mask:0xf bank_mask:0xf
	s_waitcnt lgkmcnt(4)
	v_fmac_f32_dpp v36, v242, v10 quad_perm:[0,0,0,0] row_mask:0xf bank_mask:0xf
	v_fmac_f32_dpp v37, v242, v12 quad_perm:[1,1,1,1] row_mask:0xf bank_mask:0xf
	v_fmac_f32_dpp v38, v242, v13 quad_perm:[2,2,2,2] row_mask:0xf bank_mask:0xf
	v_fmac_f32_dpp v39, v242, v14 quad_perm:[3,3,3,3] row_mask:0xf bank_mask:0xf
	s_waitcnt lgkmcnt(3)
	v_fmac_f32_dpp v36, v243, v17 quad_perm:[0,0,0,0] row_mask:0xf bank_mask:0xf
	v_fmac_f32_dpp v37, v243, v19 quad_perm:[1,1,1,1] row_mask:0xf bank_mask:0xf
	v_fmac_f32_dpp v38, v243, v28 quad_perm:[2,2,2,2] row_mask:0xf bank_mask:0xf
	ds_read_b32 v240, v255 offset:4096
	ds_read_b32 v241, v255 offset:4112
	ds_read_b32 v242, v255 offset:4128
	ds_read_b32 v243, v255 offset:4144
	v_add_f32_e32 v36, v36, v37
	v_add_f32_e32 v37, v39, v38
	v_add_f32_e32 v36, v36, v37
	v_sub_f32_e32 v35, v35, v36
	s_waitcnt lgkmcnt(4)
	v_lshlrev_b32_e32 v36, 16, v238
	v_mul_f32_e32 v36, v239, v36
	s_cmp_eq_u64 s[16:17], 0
	s_cbranch_scc1 .LBB0_837
	v_mul_f32_e32 v36, v36, v254
.LBB0_837:
	ds_read_u16 v238, v18 offset:4624
	ds_read_b32 v239, v16 offset:68
	ds_read_b32 v254, v15 offset:68
	s_waitcnt lgkmcnt(6)
	v_mul_f32_dpp v37, v240, v2 quad_perm:[0,0,0,0] row_mask:0xf bank_mask:0xf
	v_mul_f32_dpp v38, v240, v3 quad_perm:[1,1,1,1] row_mask:0xf bank_mask:0xf
	v_mul_f32_dpp v39, v240, v4 quad_perm:[2,2,2,2] row_mask:0xf bank_mask:0xf
	v_mul_f32_dpp v40, v240, v5 quad_perm:[3,3,3,3] row_mask:0xf bank_mask:0xf
	s_waitcnt lgkmcnt(5)
	v_fmac_f32_dpp v37, v241, v6 quad_perm:[0,0,0,0] row_mask:0xf bank_mask:0xf
	v_fmac_f32_dpp v38, v241, v7 quad_perm:[1,1,1,1] row_mask:0xf bank_mask:0xf
	v_fmac_f32_dpp v39, v241, v8 quad_perm:[2,2,2,2] row_mask:0xf bank_mask:0xf
	v_fmac_f32_dpp v40, v241, v9 quad_perm:[3,3,3,3] row_mask:0xf bank_mask:0xf
	s_waitcnt lgkmcnt(4)
	v_fmac_f32_dpp v37, v242, v10 quad_perm:[0,0,0,0] row_mask:0xf bank_mask:0xf
	v_fmac_f32_dpp v38, v242, v12 quad_perm:[1,1,1,1] row_mask:0xf bank_mask:0xf
	v_fmac_f32_dpp v39, v242, v13 quad_perm:[2,2,2,2] row_mask:0xf bank_mask:0xf
	v_fmac_f32_dpp v40, v242, v14 quad_perm:[3,3,3,3] row_mask:0xf bank_mask:0xf
	s_waitcnt lgkmcnt(3)
	v_fmac_f32_dpp v37, v243, v17 quad_perm:[0,0,0,0] row_mask:0xf bank_mask:0xf
	v_fmac_f32_dpp v38, v243, v19 quad_perm:[1,1,1,1] row_mask:0xf bank_mask:0xf
	v_fmac_f32_dpp v39, v243, v28 quad_perm:[2,2,2,2] row_mask:0xf bank_mask:0xf
	v_fmac_f32_dpp v40, v243, v35 quad_perm:[3,3,3,3] row_mask:0xf bank_mask:0xf
	ds_read_b32 v240, v255 offset:4352
	ds_read_b32 v241, v255 offset:4368
	ds_read_b32 v242, v255 offset:4384
	ds_read_b32 v243, v255 offset:4400
	ds_read_b32 v244, v255 offset:4416
	v_add_f32_e32 v37, v37, v38
	v_add_f32_e32 v38, v39, v40
	v_add_f32_e32 v37, v37, v38
	v_sub_f32_e32 v36, v36, v37
	s_waitcnt lgkmcnt(5)
	v_lshlrev_b32_e32 v37, 16, v238
	v_mul_f32_e32 v37, v239, v37
	s_cmp_eq_u64 s[16:17], 0
	s_cbranch_scc1 .LBB0_839
	v_mul_f32_e32 v37, v37, v254
.LBB0_839:
	ds_read_u16 v238, v18 offset:4896
	ds_read_b32 v239, v16 offset:72
	ds_read_b32 v254, v15 offset:72
	s_waitcnt lgkmcnt(7)
	v_mul_f32_dpp v54, v240, v2 quad_perm:[0,0,0,0] row_mask:0xf bank_mask:0xf
	v_mul_f32_dpp v55, v240, v3 quad_perm:[1,1,1,1] row_mask:0xf bank_mask:0xf
	v_mul_f32_dpp v56, v240, v4 quad_perm:[2,2,2,2] row_mask:0xf bank_mask:0xf
	v_mul_f32_dpp v57, v240, v5 quad_perm:[3,3,3,3] row_mask:0xf bank_mask:0xf
	s_waitcnt lgkmcnt(6)
	v_fmac_f32_dpp v54, v241, v6 quad_perm:[0,0,0,0] row_mask:0xf bank_mask:0xf
	v_fmac_f32_dpp v55, v241, v7 quad_perm:[1,1,1,1] row_mask:0xf bank_mask:0xf
	v_fmac_f32_dpp v56, v241, v8 quad_perm:[2,2,2,2] row_mask:0xf bank_mask:0xf
	v_fmac_f32_dpp v57, v241, v9 quad_perm:[3,3,3,3] row_mask:0xf bank_mask:0xf
	s_waitcnt lgkmcnt(5)
	v_fmac_f32_dpp v54, v242, v10 quad_perm:[0,0,0,0] row_mask:0xf bank_mask:0xf
	v_fmac_f32_dpp v55, v242, v12 quad_perm:[1,1,1,1] row_mask:0xf bank_mask:0xf
	v_fmac_f32_dpp v56, v242, v13 quad_perm:[2,2,2,2] row_mask:0xf bank_mask:0xf
	v_fmac_f32_dpp v57, v242, v14 quad_perm:[3,3,3,3] row_mask:0xf bank_mask:0xf
	s_waitcnt lgkmcnt(4)
	v_fmac_f32_dpp v54, v243, v17 quad_perm:[0,0,0,0] row_mask:0xf bank_mask:0xf
	v_fmac_f32_dpp v55, v243, v19 quad_perm:[1,1,1,1] row_mask:0xf bank_mask:0xf
	v_fmac_f32_dpp v56, v243, v28 quad_perm:[2,2,2,2] row_mask:0xf bank_mask:0xf
	v_fmac_f32_dpp v57, v243, v35 quad_perm:[3,3,3,3] row_mask:0xf bank_mask:0xf
	s_waitcnt lgkmcnt(3)
	v_fmac_f32_dpp v54, v244, v36 quad_perm:[0,0,0,0] row_mask:0xf bank_mask:0xf
	ds_read_b32 v240, v255 offset:4608
	ds_read_b32 v241, v255 offset:4624
	ds_read_b32 v242, v255 offset:4640
	ds_read_b32 v243, v255 offset:4656
	ds_read_b32 v244, v255 offset:4672
	v_add_f32_e32 v38, v55, v54
	v_add_f32_e32 v39, v56, v57
	v_add_f32_e32 v38, v39, v38
	v_sub_f32_e32 v37, v37, v38
	s_waitcnt lgkmcnt(5)
	v_lshlrev_b32_e32 v38, 16, v238
	v_mul_f32_e32 v38, v239, v38
	s_cmp_eq_u64 s[16:17], 0
	s_cbranch_scc1 .LBB0_841
	v_mul_f32_e32 v38, v38, v254
.LBB0_841:
	ds_read_u16 v238, v18 offset:5168
	ds_read_b32 v239, v16 offset:76
	ds_read_b32 v254, v15 offset:76
	s_waitcnt lgkmcnt(7)
	v_mul_f32_dpp v39, v240, v2 quad_perm:[0,0,0,0] row_mask:0xf bank_mask:0xf
	v_mul_f32_dpp v56, v240, v3 quad_perm:[1,1,1,1] row_mask:0xf bank_mask:0xf
	v_mul_f32_dpp v57, v240, v4 quad_perm:[2,2,2,2] row_mask:0xf bank_mask:0xf
	v_mul_f32_dpp v58, v240, v5 quad_perm:[3,3,3,3] row_mask:0xf bank_mask:0xf
	s_waitcnt lgkmcnt(6)
	v_fmac_f32_dpp v39, v241, v6 quad_perm:[0,0,0,0] row_mask:0xf bank_mask:0xf
	v_fmac_f32_dpp v56, v241, v7 quad_perm:[1,1,1,1] row_mask:0xf bank_mask:0xf
	v_fmac_f32_dpp v57, v241, v8 quad_perm:[2,2,2,2] row_mask:0xf bank_mask:0xf
	v_fmac_f32_dpp v58, v241, v9 quad_perm:[3,3,3,3] row_mask:0xf bank_mask:0xf
	s_waitcnt lgkmcnt(5)
	v_fmac_f32_dpp v39, v242, v10 quad_perm:[0,0,0,0] row_mask:0xf bank_mask:0xf
	v_fmac_f32_dpp v56, v242, v12 quad_perm:[1,1,1,1] row_mask:0xf bank_mask:0xf
	v_fmac_f32_dpp v57, v242, v13 quad_perm:[2,2,2,2] row_mask:0xf bank_mask:0xf
	v_fmac_f32_dpp v58, v242, v14 quad_perm:[3,3,3,3] row_mask:0xf bank_mask:0xf
	s_waitcnt lgkmcnt(4)
	v_fmac_f32_dpp v39, v243, v17 quad_perm:[0,0,0,0] row_mask:0xf bank_mask:0xf
	v_fmac_f32_dpp v56, v243, v19 quad_perm:[1,1,1,1] row_mask:0xf bank_mask:0xf
	v_fmac_f32_dpp v57, v243, v28 quad_perm:[2,2,2,2] row_mask:0xf bank_mask:0xf
	v_fmac_f32_dpp v58, v243, v35 quad_perm:[3,3,3,3] row_mask:0xf bank_mask:0xf
	s_waitcnt lgkmcnt(3)
	v_fmac_f32_dpp v39, v244, v36 quad_perm:[0,0,0,0] row_mask:0xf bank_mask:0xf
	v_fmac_f32_dpp v56, v244, v37 quad_perm:[1,1,1,1] row_mask:0xf bank_mask:0xf
	ds_read_b32 v240, v255 offset:4864
	ds_read_b32 v241, v255 offset:4880
	ds_read_b32 v242, v255 offset:4896
	ds_read_b32 v243, v255 offset:4912
	ds_read_b32 v244, v255 offset:4928
	v_add_f32_e32 v39, v39, v56
	v_add_f32_e32 v40, v57, v58
	v_add_f32_e32 v39, v40, v39
	v_sub_f32_e32 v38, v38, v39
	s_waitcnt lgkmcnt(5)
	v_lshlrev_b32_e32 v39, 16, v238
	v_mul_f32_e32 v39, v239, v39
	s_cmp_eq_u64 s[16:17], 0
	s_cbranch_scc1 .LBB0_843
	v_mul_f32_e32 v39, v39, v254
.LBB0_843:
	ds_read_u16 v238, v18 offset:5440
	ds_read_b32 v239, v16 offset:80
	ds_read_b32 v254, v15 offset:80
	s_waitcnt lgkmcnt(7)
	v_mul_f32_dpp v56, v240, v2 quad_perm:[0,0,0,0] row_mask:0xf bank_mask:0xf
	v_mul_f32_dpp v57, v240, v3 quad_perm:[1,1,1,1] row_mask:0xf bank_mask:0xf
	v_mul_f32_dpp v58, v240, v4 quad_perm:[2,2,2,2] row_mask:0xf bank_mask:0xf
	v_mul_f32_dpp v59, v240, v5 quad_perm:[3,3,3,3] row_mask:0xf bank_mask:0xf
	s_waitcnt lgkmcnt(6)
	v_fmac_f32_dpp v56, v241, v6 quad_perm:[0,0,0,0] row_mask:0xf bank_mask:0xf
	v_fmac_f32_dpp v57, v241, v7 quad_perm:[1,1,1,1] row_mask:0xf bank_mask:0xf
	v_fmac_f32_dpp v58, v241, v8 quad_perm:[2,2,2,2] row_mask:0xf bank_mask:0xf
	v_fmac_f32_dpp v59, v241, v9 quad_perm:[3,3,3,3] row_mask:0xf bank_mask:0xf
	s_waitcnt lgkmcnt(5)
	v_fmac_f32_dpp v56, v242, v10 quad_perm:[0,0,0,0] row_mask:0xf bank_mask:0xf
	v_fmac_f32_dpp v57, v242, v12 quad_perm:[1,1,1,1] row_mask:0xf bank_mask:0xf
	v_fmac_f32_dpp v58, v242, v13 quad_perm:[2,2,2,2] row_mask:0xf bank_mask:0xf
	v_fmac_f32_dpp v59, v242, v14 quad_perm:[3,3,3,3] row_mask:0xf bank_mask:0xf
	s_waitcnt lgkmcnt(4)
	v_fmac_f32_dpp v56, v243, v17 quad_perm:[0,0,0,0] row_mask:0xf bank_mask:0xf
	v_fmac_f32_dpp v57, v243, v19 quad_perm:[1,1,1,1] row_mask:0xf bank_mask:0xf
	v_fmac_f32_dpp v58, v243, v28 quad_perm:[2,2,2,2] row_mask:0xf bank_mask:0xf
	v_fmac_f32_dpp v59, v243, v35 quad_perm:[3,3,3,3] row_mask:0xf bank_mask:0xf
	s_waitcnt lgkmcnt(3)
	v_fmac_f32_dpp v56, v244, v36 quad_perm:[0,0,0,0] row_mask:0xf bank_mask:0xf
	v_fmac_f32_dpp v57, v244, v37 quad_perm:[1,1,1,1] row_mask:0xf bank_mask:0xf
	v_fmac_f32_dpp v58, v244, v38 quad_perm:[2,2,2,2] row_mask:0xf bank_mask:0xf
	ds_read_b32 v240, v255 offset:5120
	ds_read_b32 v241, v255 offset:5136
	ds_read_b32 v242, v255 offset:5152
	ds_read_b32 v243, v255 offset:5168
	ds_read_b32 v244, v255 offset:5184
	v_add_f32_e32 v40, v56, v57
	v_add_f32_e32 v41, v59, v58
	v_add_f32_e32 v40, v40, v41
	v_sub_f32_e32 v39, v39, v40
	s_waitcnt lgkmcnt(5)
	v_lshlrev_b32_e32 v40, 16, v238
	v_mul_f32_e32 v40, v239, v40
	s_cmp_eq_u64 s[16:17], 0
	s_cbranch_scc1 .LBB0_845
	v_mul_f32_e32 v40, v40, v254
.LBB0_845:
	ds_read_u16 v238, v18 offset:5712
	ds_read_b32 v239, v16 offset:84
	ds_read_b32 v254, v15 offset:84
	s_waitcnt lgkmcnt(7)
	v_mul_f32_dpp v41, v240, v2 quad_perm:[0,0,0,0] row_mask:0xf bank_mask:0xf
	v_mul_f32_dpp v58, v240, v3 quad_perm:[1,1,1,1] row_mask:0xf bank_mask:0xf
	v_mul_f32_dpp v59, v240, v4 quad_perm:[2,2,2,2] row_mask:0xf bank_mask:0xf
	v_mul_f32_dpp v60, v240, v5 quad_perm:[3,3,3,3] row_mask:0xf bank_mask:0xf
	s_waitcnt lgkmcnt(6)
	v_fmac_f32_dpp v41, v241, v6 quad_perm:[0,0,0,0] row_mask:0xf bank_mask:0xf
	v_fmac_f32_dpp v58, v241, v7 quad_perm:[1,1,1,1] row_mask:0xf bank_mask:0xf
	v_fmac_f32_dpp v59, v241, v8 quad_perm:[2,2,2,2] row_mask:0xf bank_mask:0xf
	v_fmac_f32_dpp v60, v241, v9 quad_perm:[3,3,3,3] row_mask:0xf bank_mask:0xf
	s_waitcnt lgkmcnt(5)
	v_fmac_f32_dpp v41, v242, v10 quad_perm:[0,0,0,0] row_mask:0xf bank_mask:0xf
	v_fmac_f32_dpp v58, v242, v12 quad_perm:[1,1,1,1] row_mask:0xf bank_mask:0xf
	v_fmac_f32_dpp v59, v242, v13 quad_perm:[2,2,2,2] row_mask:0xf bank_mask:0xf
	v_fmac_f32_dpp v60, v242, v14 quad_perm:[3,3,3,3] row_mask:0xf bank_mask:0xf
	s_waitcnt lgkmcnt(4)
	v_fmac_f32_dpp v41, v243, v17 quad_perm:[0,0,0,0] row_mask:0xf bank_mask:0xf
	v_fmac_f32_dpp v58, v243, v19 quad_perm:[1,1,1,1] row_mask:0xf bank_mask:0xf
	v_fmac_f32_dpp v59, v243, v28 quad_perm:[2,2,2,2] row_mask:0xf bank_mask:0xf
	v_fmac_f32_dpp v60, v243, v35 quad_perm:[3,3,3,3] row_mask:0xf bank_mask:0xf
	s_waitcnt lgkmcnt(3)
	v_fmac_f32_dpp v41, v244, v36 quad_perm:[0,0,0,0] row_mask:0xf bank_mask:0xf
	v_fmac_f32_dpp v58, v244, v37 quad_perm:[1,1,1,1] row_mask:0xf bank_mask:0xf
	v_fmac_f32_dpp v59, v244, v38 quad_perm:[2,2,2,2] row_mask:0xf bank_mask:0xf
	v_fmac_f32_dpp v60, v244, v39 quad_perm:[3,3,3,3] row_mask:0xf bank_mask:0xf
	ds_read_b32 v240, v255 offset:5376
	ds_read_b32 v241, v255 offset:5392
	ds_read_b32 v242, v255 offset:5408
	ds_read_b32 v243, v255 offset:5424
	ds_read_b32 v244, v255 offset:5440
	ds_read_b32 v245, v255 offset:5456
	v_add_f32_e32 v41, v41, v58
	v_add_f32_e32 v42, v59, v60
	v_add_f32_e32 v41, v41, v42
	v_sub_f32_e32 v40, v40, v41
	s_waitcnt lgkmcnt(6)
	v_lshlrev_b32_e32 v41, 16, v238
	v_mul_f32_e32 v41, v239, v41
	s_cmp_eq_u64 s[16:17], 0
	s_cbranch_scc1 .LBB0_847
	v_mul_f32_e32 v41, v41, v254
.LBB0_847:
	ds_read_u16 v238, v18 offset:5984
	ds_read_b32 v239, v16 offset:88
	ds_read_b32 v254, v15 offset:88
	s_waitcnt lgkmcnt(8)
	v_mul_f32_dpp v58, v240, v2 quad_perm:[0,0,0,0] row_mask:0xf bank_mask:0xf
	v_mul_f32_dpp v59, v240, v3 quad_perm:[1,1,1,1] row_mask:0xf bank_mask:0xf
	v_mul_f32_dpp v60, v240, v4 quad_perm:[2,2,2,2] row_mask:0xf bank_mask:0xf
	v_mul_f32_dpp v61, v240, v5 quad_perm:[3,3,3,3] row_mask:0xf bank_mask:0xf
	s_waitcnt lgkmcnt(7)
	v_fmac_f32_dpp v58, v241, v6 quad_perm:[0,0,0,0] row_mask:0xf bank_mask:0xf
	v_fmac_f32_dpp v59, v241, v7 quad_perm:[1,1,1,1] row_mask:0xf bank_mask:0xf
	v_fmac_f32_dpp v60, v241, v8 quad_perm:[2,2,2,2] row_mask:0xf bank_mask:0xf
	v_fmac_f32_dpp v61, v241, v9 quad_perm:[3,3,3,3] row_mask:0xf bank_mask:0xf
	s_waitcnt lgkmcnt(6)
	v_fmac_f32_dpp v58, v242, v10 quad_perm:[0,0,0,0] row_mask:0xf bank_mask:0xf
	v_fmac_f32_dpp v59, v242, v12 quad_perm:[1,1,1,1] row_mask:0xf bank_mask:0xf
	v_fmac_f32_dpp v60, v242, v13 quad_perm:[2,2,2,2] row_mask:0xf bank_mask:0xf
	v_fmac_f32_dpp v61, v242, v14 quad_perm:[3,3,3,3] row_mask:0xf bank_mask:0xf
	s_waitcnt lgkmcnt(5)
	v_fmac_f32_dpp v58, v243, v17 quad_perm:[0,0,0,0] row_mask:0xf bank_mask:0xf
	v_fmac_f32_dpp v59, v243, v19 quad_perm:[1,1,1,1] row_mask:0xf bank_mask:0xf
	v_fmac_f32_dpp v60, v243, v28 quad_perm:[2,2,2,2] row_mask:0xf bank_mask:0xf
	v_fmac_f32_dpp v61, v243, v35 quad_perm:[3,3,3,3] row_mask:0xf bank_mask:0xf
	s_waitcnt lgkmcnt(4)
	v_fmac_f32_dpp v58, v244, v36 quad_perm:[0,0,0,0] row_mask:0xf bank_mask:0xf
	v_fmac_f32_dpp v59, v244, v37 quad_perm:[1,1,1,1] row_mask:0xf bank_mask:0xf
	v_fmac_f32_dpp v60, v244, v38 quad_perm:[2,2,2,2] row_mask:0xf bank_mask:0xf
	v_fmac_f32_dpp v61, v244, v39 quad_perm:[3,3,3,3] row_mask:0xf bank_mask:0xf
	s_waitcnt lgkmcnt(3)
	v_fmac_f32_dpp v58, v245, v40 quad_perm:[0,0,0,0] row_mask:0xf bank_mask:0xf
	ds_read_b32 v240, v255 offset:5632
	ds_read_b32 v241, v255 offset:5648
	ds_read_b32 v242, v255 offset:5664
	ds_read_b32 v243, v255 offset:5680
	ds_read_b32 v244, v255 offset:5696
	ds_read_b32 v245, v255 offset:5712
	v_add_f32_e32 v42, v59, v58
	v_add_f32_e32 v43, v60, v61
	v_add_f32_e32 v42, v43, v42
	v_sub_f32_e32 v41, v41, v42
	s_waitcnt lgkmcnt(6)
	v_lshlrev_b32_e32 v42, 16, v238
	v_mul_f32_e32 v42, v239, v42
	s_cmp_eq_u64 s[16:17], 0
	s_cbranch_scc1 .LBB0_849
	v_mul_f32_e32 v42, v42, v254
.LBB0_849:
	ds_read_u16 v238, v18 offset:6256
	ds_read_b32 v239, v16 offset:92
	ds_read_b32 v254, v15 offset:92
	s_waitcnt lgkmcnt(8)
	v_mul_f32_dpp v43, v240, v2 quad_perm:[0,0,0,0] row_mask:0xf bank_mask:0xf
	v_mul_f32_dpp v60, v240, v3 quad_perm:[1,1,1,1] row_mask:0xf bank_mask:0xf
	v_mul_f32_dpp v61, v240, v4 quad_perm:[2,2,2,2] row_mask:0xf bank_mask:0xf
	v_mul_f32_dpp v62, v240, v5 quad_perm:[3,3,3,3] row_mask:0xf bank_mask:0xf
	s_waitcnt lgkmcnt(7)
	v_fmac_f32_dpp v43, v241, v6 quad_perm:[0,0,0,0] row_mask:0xf bank_mask:0xf
	v_fmac_f32_dpp v60, v241, v7 quad_perm:[1,1,1,1] row_mask:0xf bank_mask:0xf
	v_fmac_f32_dpp v61, v241, v8 quad_perm:[2,2,2,2] row_mask:0xf bank_mask:0xf
	v_fmac_f32_dpp v62, v241, v9 quad_perm:[3,3,3,3] row_mask:0xf bank_mask:0xf
	s_waitcnt lgkmcnt(6)
	v_fmac_f32_dpp v43, v242, v10 quad_perm:[0,0,0,0] row_mask:0xf bank_mask:0xf
	v_fmac_f32_dpp v60, v242, v12 quad_perm:[1,1,1,1] row_mask:0xf bank_mask:0xf
	v_fmac_f32_dpp v61, v242, v13 quad_perm:[2,2,2,2] row_mask:0xf bank_mask:0xf
	v_fmac_f32_dpp v62, v242, v14 quad_perm:[3,3,3,3] row_mask:0xf bank_mask:0xf
	s_waitcnt lgkmcnt(5)
	v_fmac_f32_dpp v43, v243, v17 quad_perm:[0,0,0,0] row_mask:0xf bank_mask:0xf
	v_fmac_f32_dpp v60, v243, v19 quad_perm:[1,1,1,1] row_mask:0xf bank_mask:0xf
	v_fmac_f32_dpp v61, v243, v28 quad_perm:[2,2,2,2] row_mask:0xf bank_mask:0xf
	v_fmac_f32_dpp v62, v243, v35 quad_perm:[3,3,3,3] row_mask:0xf bank_mask:0xf
	s_waitcnt lgkmcnt(4)
	v_fmac_f32_dpp v43, v244, v36 quad_perm:[0,0,0,0] row_mask:0xf bank_mask:0xf
	v_fmac_f32_dpp v60, v244, v37 quad_perm:[1,1,1,1] row_mask:0xf bank_mask:0xf
	v_fmac_f32_dpp v61, v244, v38 quad_perm:[2,2,2,2] row_mask:0xf bank_mask:0xf
	v_fmac_f32_dpp v62, v244, v39 quad_perm:[3,3,3,3] row_mask:0xf bank_mask:0xf
	s_waitcnt lgkmcnt(3)
	v_fmac_f32_dpp v43, v245, v40 quad_perm:[0,0,0,0] row_mask:0xf bank_mask:0xf
	v_fmac_f32_dpp v60, v245, v41 quad_perm:[1,1,1,1] row_mask:0xf bank_mask:0xf
	ds_read_b32 v240, v255 offset:5888
	ds_read_b32 v241, v255 offset:5904
	ds_read_b32 v242, v255 offset:5920
	ds_read_b32 v243, v255 offset:5936
	ds_read_b32 v244, v255 offset:5952
	ds_read_b32 v245, v255 offset:5968
	v_add_f32_e32 v43, v43, v60
	v_add_f32_e32 v44, v61, v62
	v_add_f32_e32 v43, v44, v43
	v_sub_f32_e32 v42, v42, v43
	s_waitcnt lgkmcnt(6)
	v_lshlrev_b32_e32 v43, 16, v238
	v_mul_f32_e32 v43, v239, v43
	s_cmp_eq_u64 s[16:17], 0
	s_cbranch_scc1 .LBB0_851
	v_mul_f32_e32 v43, v43, v254
.LBB0_851:
	ds_read_u16 v238, v18 offset:6528
	ds_read_b32 v239, v16 offset:96
	ds_read_b32 v254, v15 offset:96
	s_waitcnt lgkmcnt(8)
	v_mul_f32_dpp v60, v240, v2 quad_perm:[0,0,0,0] row_mask:0xf bank_mask:0xf
	v_mul_f32_dpp v61, v240, v3 quad_perm:[1,1,1,1] row_mask:0xf bank_mask:0xf
	v_mul_f32_dpp v62, v240, v4 quad_perm:[2,2,2,2] row_mask:0xf bank_mask:0xf
	v_mul_f32_dpp v63, v240, v5 quad_perm:[3,3,3,3] row_mask:0xf bank_mask:0xf
	s_waitcnt lgkmcnt(7)
	v_fmac_f32_dpp v60, v241, v6 quad_perm:[0,0,0,0] row_mask:0xf bank_mask:0xf
	v_fmac_f32_dpp v61, v241, v7 quad_perm:[1,1,1,1] row_mask:0xf bank_mask:0xf
	v_fmac_f32_dpp v62, v241, v8 quad_perm:[2,2,2,2] row_mask:0xf bank_mask:0xf
	v_fmac_f32_dpp v63, v241, v9 quad_perm:[3,3,3,3] row_mask:0xf bank_mask:0xf
	s_waitcnt lgkmcnt(6)
	v_fmac_f32_dpp v60, v242, v10 quad_perm:[0,0,0,0] row_mask:0xf bank_mask:0xf
	v_fmac_f32_dpp v61, v242, v12 quad_perm:[1,1,1,1] row_mask:0xf bank_mask:0xf
	v_fmac_f32_dpp v62, v242, v13 quad_perm:[2,2,2,2] row_mask:0xf bank_mask:0xf
	v_fmac_f32_dpp v63, v242, v14 quad_perm:[3,3,3,3] row_mask:0xf bank_mask:0xf
	s_waitcnt lgkmcnt(5)
	v_fmac_f32_dpp v60, v243, v17 quad_perm:[0,0,0,0] row_mask:0xf bank_mask:0xf
	v_fmac_f32_dpp v61, v243, v19 quad_perm:[1,1,1,1] row_mask:0xf bank_mask:0xf
	v_fmac_f32_dpp v62, v243, v28 quad_perm:[2,2,2,2] row_mask:0xf bank_mask:0xf
	v_fmac_f32_dpp v63, v243, v35 quad_perm:[3,3,3,3] row_mask:0xf bank_mask:0xf
	s_waitcnt lgkmcnt(4)
	v_fmac_f32_dpp v60, v244, v36 quad_perm:[0,0,0,0] row_mask:0xf bank_mask:0xf
	v_fmac_f32_dpp v61, v244, v37 quad_perm:[1,1,1,1] row_mask:0xf bank_mask:0xf
	v_fmac_f32_dpp v62, v244, v38 quad_perm:[2,2,2,2] row_mask:0xf bank_mask:0xf
	v_fmac_f32_dpp v63, v244, v39 quad_perm:[3,3,3,3] row_mask:0xf bank_mask:0xf
	s_waitcnt lgkmcnt(3)
	v_fmac_f32_dpp v60, v245, v40 quad_perm:[0,0,0,0] row_mask:0xf bank_mask:0xf
	v_fmac_f32_dpp v61, v245, v41 quad_perm:[1,1,1,1] row_mask:0xf bank_mask:0xf
	v_fmac_f32_dpp v62, v245, v42 quad_perm:[2,2,2,2] row_mask:0xf bank_mask:0xf
	ds_read_b32 v240, v255 offset:6144
	ds_read_b32 v241, v255 offset:6160
	ds_read_b32 v242, v255 offset:6176
	ds_read_b32 v243, v255 offset:6192
	ds_read_b32 v244, v255 offset:6208
	ds_read_b32 v245, v255 offset:6224
	v_add_f32_e32 v44, v60, v61
	v_add_f32_e32 v45, v63, v62
	v_add_f32_e32 v44, v44, v45
	v_sub_f32_e32 v43, v43, v44
	s_waitcnt lgkmcnt(6)
	v_lshlrev_b32_e32 v44, 16, v238
	v_mul_f32_e32 v44, v239, v44
	s_cmp_eq_u64 s[16:17], 0
	s_cbranch_scc1 .LBB0_853
	v_mul_f32_e32 v44, v44, v254
.LBB0_853:
	ds_read_u16 v238, v18 offset:6800
	ds_read_b32 v239, v16 offset:100
	ds_read_b32 v254, v15 offset:100
	s_waitcnt lgkmcnt(8)
	v_mul_f32_dpp v45, v240, v2 quad_perm:[0,0,0,0] row_mask:0xf bank_mask:0xf
	v_mul_f32_dpp v62, v240, v3 quad_perm:[1,1,1,1] row_mask:0xf bank_mask:0xf
	v_mul_f32_dpp v63, v240, v4 quad_perm:[2,2,2,2] row_mask:0xf bank_mask:0xf
	v_mul_f32_dpp v64, v240, v5 quad_perm:[3,3,3,3] row_mask:0xf bank_mask:0xf
	s_waitcnt lgkmcnt(7)
	v_fmac_f32_dpp v45, v241, v6 quad_perm:[0,0,0,0] row_mask:0xf bank_mask:0xf
	v_fmac_f32_dpp v62, v241, v7 quad_perm:[1,1,1,1] row_mask:0xf bank_mask:0xf
	v_fmac_f32_dpp v63, v241, v8 quad_perm:[2,2,2,2] row_mask:0xf bank_mask:0xf
	v_fmac_f32_dpp v64, v241, v9 quad_perm:[3,3,3,3] row_mask:0xf bank_mask:0xf
	s_waitcnt lgkmcnt(6)
	v_fmac_f32_dpp v45, v242, v10 quad_perm:[0,0,0,0] row_mask:0xf bank_mask:0xf
	v_fmac_f32_dpp v62, v242, v12 quad_perm:[1,1,1,1] row_mask:0xf bank_mask:0xf
	v_fmac_f32_dpp v63, v242, v13 quad_perm:[2,2,2,2] row_mask:0xf bank_mask:0xf
	v_fmac_f32_dpp v64, v242, v14 quad_perm:[3,3,3,3] row_mask:0xf bank_mask:0xf
	s_waitcnt lgkmcnt(5)
	v_fmac_f32_dpp v45, v243, v17 quad_perm:[0,0,0,0] row_mask:0xf bank_mask:0xf
	v_fmac_f32_dpp v62, v243, v19 quad_perm:[1,1,1,1] row_mask:0xf bank_mask:0xf
	v_fmac_f32_dpp v63, v243, v28 quad_perm:[2,2,2,2] row_mask:0xf bank_mask:0xf
	v_fmac_f32_dpp v64, v243, v35 quad_perm:[3,3,3,3] row_mask:0xf bank_mask:0xf
	s_waitcnt lgkmcnt(4)
	v_fmac_f32_dpp v45, v244, v36 quad_perm:[0,0,0,0] row_mask:0xf bank_mask:0xf
	v_fmac_f32_dpp v62, v244, v37 quad_perm:[1,1,1,1] row_mask:0xf bank_mask:0xf
	v_fmac_f32_dpp v63, v244, v38 quad_perm:[2,2,2,2] row_mask:0xf bank_mask:0xf
	v_fmac_f32_dpp v64, v244, v39 quad_perm:[3,3,3,3] row_mask:0xf bank_mask:0xf
	s_waitcnt lgkmcnt(3)
	v_fmac_f32_dpp v45, v245, v40 quad_perm:[0,0,0,0] row_mask:0xf bank_mask:0xf
	v_fmac_f32_dpp v62, v245, v41 quad_perm:[1,1,1,1] row_mask:0xf bank_mask:0xf
	v_fmac_f32_dpp v63, v245, v42 quad_perm:[2,2,2,2] row_mask:0xf bank_mask:0xf
	v_fmac_f32_dpp v64, v245, v43 quad_perm:[3,3,3,3] row_mask:0xf bank_mask:0xf
	ds_read_b32 v240, v255 offset:6400
	ds_read_b32 v241, v255 offset:6416
	ds_read_b32 v242, v255 offset:6432
	ds_read_b32 v243, v255 offset:6448
	ds_read_b32 v244, v255 offset:6464
	ds_read_b32 v245, v255 offset:6480
	ds_read_b32 v246, v255 offset:6496
	v_add_f32_e32 v45, v45, v62
	v_add_f32_e32 v46, v63, v64
	v_add_f32_e32 v45, v45, v46
	v_sub_f32_e32 v44, v44, v45
	s_waitcnt lgkmcnt(7)
	v_lshlrev_b32_e32 v45, 16, v238
	v_mul_f32_e32 v45, v239, v45
	s_cmp_eq_u64 s[16:17], 0
	s_cbranch_scc1 .LBB0_855
	v_mul_f32_e32 v45, v45, v254
.LBB0_855:
	ds_read_u16 v238, v18 offset:7072
	ds_read_b32 v239, v16 offset:104
	ds_read_b32 v254, v15 offset:104
	s_waitcnt lgkmcnt(9)
	v_mul_f32_dpp v62, v240, v2 quad_perm:[0,0,0,0] row_mask:0xf bank_mask:0xf
	v_mul_f32_dpp v63, v240, v3 quad_perm:[1,1,1,1] row_mask:0xf bank_mask:0xf
	v_mul_f32_dpp v64, v240, v4 quad_perm:[2,2,2,2] row_mask:0xf bank_mask:0xf
	v_mul_f32_dpp v65, v240, v5 quad_perm:[3,3,3,3] row_mask:0xf bank_mask:0xf
	s_waitcnt lgkmcnt(8)
	v_fmac_f32_dpp v62, v241, v6 quad_perm:[0,0,0,0] row_mask:0xf bank_mask:0xf
	v_fmac_f32_dpp v63, v241, v7 quad_perm:[1,1,1,1] row_mask:0xf bank_mask:0xf
	v_fmac_f32_dpp v64, v241, v8 quad_perm:[2,2,2,2] row_mask:0xf bank_mask:0xf
	v_fmac_f32_dpp v65, v241, v9 quad_perm:[3,3,3,3] row_mask:0xf bank_mask:0xf
	s_waitcnt lgkmcnt(7)
	v_fmac_f32_dpp v62, v242, v10 quad_perm:[0,0,0,0] row_mask:0xf bank_mask:0xf
	v_fmac_f32_dpp v63, v242, v12 quad_perm:[1,1,1,1] row_mask:0xf bank_mask:0xf
	v_fmac_f32_dpp v64, v242, v13 quad_perm:[2,2,2,2] row_mask:0xf bank_mask:0xf
	v_fmac_f32_dpp v65, v242, v14 quad_perm:[3,3,3,3] row_mask:0xf bank_mask:0xf
	s_waitcnt lgkmcnt(6)
	v_fmac_f32_dpp v62, v243, v17 quad_perm:[0,0,0,0] row_mask:0xf bank_mask:0xf
	v_fmac_f32_dpp v63, v243, v19 quad_perm:[1,1,1,1] row_mask:0xf bank_mask:0xf
	v_fmac_f32_dpp v64, v243, v28 quad_perm:[2,2,2,2] row_mask:0xf bank_mask:0xf
	v_fmac_f32_dpp v65, v243, v35 quad_perm:[3,3,3,3] row_mask:0xf bank_mask:0xf
	s_waitcnt lgkmcnt(5)
	v_fmac_f32_dpp v62, v244, v36 quad_perm:[0,0,0,0] row_mask:0xf bank_mask:0xf
	v_fmac_f32_dpp v63, v244, v37 quad_perm:[1,1,1,1] row_mask:0xf bank_mask:0xf
	v_fmac_f32_dpp v64, v244, v38 quad_perm:[2,2,2,2] row_mask:0xf bank_mask:0xf
	v_fmac_f32_dpp v65, v244, v39 quad_perm:[3,3,3,3] row_mask:0xf bank_mask:0xf
	s_waitcnt lgkmcnt(4)
	v_fmac_f32_dpp v62, v245, v40 quad_perm:[0,0,0,0] row_mask:0xf bank_mask:0xf
	v_fmac_f32_dpp v63, v245, v41 quad_perm:[1,1,1,1] row_mask:0xf bank_mask:0xf
	v_fmac_f32_dpp v64, v245, v42 quad_perm:[2,2,2,2] row_mask:0xf bank_mask:0xf
	v_fmac_f32_dpp v65, v245, v43 quad_perm:[3,3,3,3] row_mask:0xf bank_mask:0xf
	s_waitcnt lgkmcnt(3)
	v_fmac_f32_dpp v62, v246, v44 quad_perm:[0,0,0,0] row_mask:0xf bank_mask:0xf
	ds_read_b32 v240, v255 offset:6656
	ds_read_b32 v241, v255 offset:6672
	ds_read_b32 v242, v255 offset:6688
	ds_read_b32 v243, v255 offset:6704
	ds_read_b32 v244, v255 offset:6720
	ds_read_b32 v245, v255 offset:6736
	ds_read_b32 v246, v255 offset:6752
	v_add_f32_e32 v46, v63, v62
	v_add_f32_e32 v47, v64, v65
	v_add_f32_e32 v46, v47, v46
	v_sub_f32_e32 v45, v45, v46
	s_waitcnt lgkmcnt(7)
	v_lshlrev_b32_e32 v46, 16, v238
	v_mul_f32_e32 v46, v239, v46
	s_cmp_eq_u64 s[16:17], 0
	s_cbranch_scc1 .LBB0_857
	v_mul_f32_e32 v46, v46, v254
.LBB0_857:
	ds_read_u16 v238, v18 offset:7344
	ds_read_b32 v239, v16 offset:108
	ds_read_b32 v254, v15 offset:108
	s_waitcnt lgkmcnt(9)
	v_mul_f32_dpp v47, v240, v2 quad_perm:[0,0,0,0] row_mask:0xf bank_mask:0xf
	v_mul_f32_dpp v64, v240, v3 quad_perm:[1,1,1,1] row_mask:0xf bank_mask:0xf
	v_mul_f32_dpp v65, v240, v4 quad_perm:[2,2,2,2] row_mask:0xf bank_mask:0xf
	v_mul_f32_dpp v66, v240, v5 quad_perm:[3,3,3,3] row_mask:0xf bank_mask:0xf
	s_waitcnt lgkmcnt(8)
	v_fmac_f32_dpp v47, v241, v6 quad_perm:[0,0,0,0] row_mask:0xf bank_mask:0xf
	v_fmac_f32_dpp v64, v241, v7 quad_perm:[1,1,1,1] row_mask:0xf bank_mask:0xf
	v_fmac_f32_dpp v65, v241, v8 quad_perm:[2,2,2,2] row_mask:0xf bank_mask:0xf
	v_fmac_f32_dpp v66, v241, v9 quad_perm:[3,3,3,3] row_mask:0xf bank_mask:0xf
	s_waitcnt lgkmcnt(7)
	v_fmac_f32_dpp v47, v242, v10 quad_perm:[0,0,0,0] row_mask:0xf bank_mask:0xf
	v_fmac_f32_dpp v64, v242, v12 quad_perm:[1,1,1,1] row_mask:0xf bank_mask:0xf
	v_fmac_f32_dpp v65, v242, v13 quad_perm:[2,2,2,2] row_mask:0xf bank_mask:0xf
	v_fmac_f32_dpp v66, v242, v14 quad_perm:[3,3,3,3] row_mask:0xf bank_mask:0xf
	s_waitcnt lgkmcnt(6)
	v_fmac_f32_dpp v47, v243, v17 quad_perm:[0,0,0,0] row_mask:0xf bank_mask:0xf
	v_fmac_f32_dpp v64, v243, v19 quad_perm:[1,1,1,1] row_mask:0xf bank_mask:0xf
	v_fmac_f32_dpp v65, v243, v28 quad_perm:[2,2,2,2] row_mask:0xf bank_mask:0xf
	v_fmac_f32_dpp v66, v243, v35 quad_perm:[3,3,3,3] row_mask:0xf bank_mask:0xf
	s_waitcnt lgkmcnt(5)
	v_fmac_f32_dpp v47, v244, v36 quad_perm:[0,0,0,0] row_mask:0xf bank_mask:0xf
	v_fmac_f32_dpp v64, v244, v37 quad_perm:[1,1,1,1] row_mask:0xf bank_mask:0xf
	v_fmac_f32_dpp v65, v244, v38 quad_perm:[2,2,2,2] row_mask:0xf bank_mask:0xf
	v_fmac_f32_dpp v66, v244, v39 quad_perm:[3,3,3,3] row_mask:0xf bank_mask:0xf
	s_waitcnt lgkmcnt(4)
	v_fmac_f32_dpp v47, v245, v40 quad_perm:[0,0,0,0] row_mask:0xf bank_mask:0xf
	v_fmac_f32_dpp v64, v245, v41 quad_perm:[1,1,1,1] row_mask:0xf bank_mask:0xf
	v_fmac_f32_dpp v65, v245, v42 quad_perm:[2,2,2,2] row_mask:0xf bank_mask:0xf
	v_fmac_f32_dpp v66, v245, v43 quad_perm:[3,3,3,3] row_mask:0xf bank_mask:0xf
	s_waitcnt lgkmcnt(3)
	v_fmac_f32_dpp v47, v246, v44 quad_perm:[0,0,0,0] row_mask:0xf bank_mask:0xf
	v_fmac_f32_dpp v64, v246, v45 quad_perm:[1,1,1,1] row_mask:0xf bank_mask:0xf
	ds_read_b32 v240, v255 offset:6912
	ds_read_b32 v241, v255 offset:6928
	ds_read_b32 v242, v255 offset:6944
	ds_read_b32 v243, v255 offset:6960
	ds_read_b32 v244, v255 offset:6976
	ds_read_b32 v245, v255 offset:6992
	ds_read_b32 v246, v255 offset:7008
	v_add_f32_e32 v47, v47, v64
	v_add_f32_e32 v48, v65, v66
	v_add_f32_e32 v47, v48, v47
	v_sub_f32_e32 v46, v46, v47
	s_waitcnt lgkmcnt(7)
	v_lshlrev_b32_e32 v47, 16, v238
	v_mul_f32_e32 v47, v239, v47
	s_cmp_eq_u64 s[16:17], 0
	s_cbranch_scc1 .LBB0_859
	v_mul_f32_e32 v47, v47, v254
.LBB0_859:
	ds_read_u16 v238, v18 offset:7616
	ds_read_b32 v239, v16 offset:112
	ds_read_b32 v254, v15 offset:112
	s_waitcnt lgkmcnt(9)
	v_mul_f32_dpp v64, v240, v2 quad_perm:[0,0,0,0] row_mask:0xf bank_mask:0xf
	v_mul_f32_dpp v65, v240, v3 quad_perm:[1,1,1,1] row_mask:0xf bank_mask:0xf
	v_mul_f32_dpp v66, v240, v4 quad_perm:[2,2,2,2] row_mask:0xf bank_mask:0xf
	v_mul_f32_dpp v67, v240, v5 quad_perm:[3,3,3,3] row_mask:0xf bank_mask:0xf
	s_waitcnt lgkmcnt(8)
	v_fmac_f32_dpp v64, v241, v6 quad_perm:[0,0,0,0] row_mask:0xf bank_mask:0xf
	v_fmac_f32_dpp v65, v241, v7 quad_perm:[1,1,1,1] row_mask:0xf bank_mask:0xf
	v_fmac_f32_dpp v66, v241, v8 quad_perm:[2,2,2,2] row_mask:0xf bank_mask:0xf
	v_fmac_f32_dpp v67, v241, v9 quad_perm:[3,3,3,3] row_mask:0xf bank_mask:0xf
	s_waitcnt lgkmcnt(7)
	v_fmac_f32_dpp v64, v242, v10 quad_perm:[0,0,0,0] row_mask:0xf bank_mask:0xf
	v_fmac_f32_dpp v65, v242, v12 quad_perm:[1,1,1,1] row_mask:0xf bank_mask:0xf
	v_fmac_f32_dpp v66, v242, v13 quad_perm:[2,2,2,2] row_mask:0xf bank_mask:0xf
	v_fmac_f32_dpp v67, v242, v14 quad_perm:[3,3,3,3] row_mask:0xf bank_mask:0xf
	s_waitcnt lgkmcnt(6)
	v_fmac_f32_dpp v64, v243, v17 quad_perm:[0,0,0,0] row_mask:0xf bank_mask:0xf
	v_fmac_f32_dpp v65, v243, v19 quad_perm:[1,1,1,1] row_mask:0xf bank_mask:0xf
	v_fmac_f32_dpp v66, v243, v28 quad_perm:[2,2,2,2] row_mask:0xf bank_mask:0xf
	v_fmac_f32_dpp v67, v243, v35 quad_perm:[3,3,3,3] row_mask:0xf bank_mask:0xf
	s_waitcnt lgkmcnt(5)
	v_fmac_f32_dpp v64, v244, v36 quad_perm:[0,0,0,0] row_mask:0xf bank_mask:0xf
	v_fmac_f32_dpp v65, v244, v37 quad_perm:[1,1,1,1] row_mask:0xf bank_mask:0xf
	v_fmac_f32_dpp v66, v244, v38 quad_perm:[2,2,2,2] row_mask:0xf bank_mask:0xf
	v_fmac_f32_dpp v67, v244, v39 quad_perm:[3,3,3,3] row_mask:0xf bank_mask:0xf
	s_waitcnt lgkmcnt(4)
	v_fmac_f32_dpp v64, v245, v40 quad_perm:[0,0,0,0] row_mask:0xf bank_mask:0xf
	v_fmac_f32_dpp v65, v245, v41 quad_perm:[1,1,1,1] row_mask:0xf bank_mask:0xf
	v_fmac_f32_dpp v66, v245, v42 quad_perm:[2,2,2,2] row_mask:0xf bank_mask:0xf
	v_fmac_f32_dpp v67, v245, v43 quad_perm:[3,3,3,3] row_mask:0xf bank_mask:0xf
	s_waitcnt lgkmcnt(3)
	v_fmac_f32_dpp v64, v246, v44 quad_perm:[0,0,0,0] row_mask:0xf bank_mask:0xf
	v_fmac_f32_dpp v65, v246, v45 quad_perm:[1,1,1,1] row_mask:0xf bank_mask:0xf
	v_fmac_f32_dpp v66, v246, v46 quad_perm:[2,2,2,2] row_mask:0xf bank_mask:0xf
	ds_read_b32 v240, v255 offset:7168
	ds_read_b32 v241, v255 offset:7184
	ds_read_b32 v242, v255 offset:7200
	ds_read_b32 v243, v255 offset:7216
	ds_read_b32 v244, v255 offset:7232
	ds_read_b32 v245, v255 offset:7248
	ds_read_b32 v246, v255 offset:7264
	v_add_f32_e32 v48, v64, v65
	v_add_f32_e32 v49, v67, v66
	v_add_f32_e32 v48, v48, v49
	v_sub_f32_e32 v47, v47, v48
	s_waitcnt lgkmcnt(7)
	v_lshlrev_b32_e32 v48, 16, v238
	v_mul_f32_e32 v48, v239, v48
	s_cmp_eq_u64 s[16:17], 0
	s_cbranch_scc1 .LBB0_861
	v_mul_f32_e32 v48, v48, v254
.LBB0_861:
	ds_read_u16 v238, v18 offset:7888
	ds_read_b32 v239, v16 offset:116
	ds_read_b32 v254, v15 offset:116
	s_waitcnt lgkmcnt(9)
	v_mul_f32_dpp v49, v240, v2 quad_perm:[0,0,0,0] row_mask:0xf bank_mask:0xf
	v_mul_f32_dpp v66, v240, v3 quad_perm:[1,1,1,1] row_mask:0xf bank_mask:0xf
	v_mul_f32_dpp v67, v240, v4 quad_perm:[2,2,2,2] row_mask:0xf bank_mask:0xf
	v_mul_f32_dpp v68, v240, v5 quad_perm:[3,3,3,3] row_mask:0xf bank_mask:0xf
	s_waitcnt lgkmcnt(8)
	v_fmac_f32_dpp v49, v241, v6 quad_perm:[0,0,0,0] row_mask:0xf bank_mask:0xf
	v_fmac_f32_dpp v66, v241, v7 quad_perm:[1,1,1,1] row_mask:0xf bank_mask:0xf
	v_fmac_f32_dpp v67, v241, v8 quad_perm:[2,2,2,2] row_mask:0xf bank_mask:0xf
	v_fmac_f32_dpp v68, v241, v9 quad_perm:[3,3,3,3] row_mask:0xf bank_mask:0xf
	s_waitcnt lgkmcnt(7)
	v_fmac_f32_dpp v49, v242, v10 quad_perm:[0,0,0,0] row_mask:0xf bank_mask:0xf
	v_fmac_f32_dpp v66, v242, v12 quad_perm:[1,1,1,1] row_mask:0xf bank_mask:0xf
	v_fmac_f32_dpp v67, v242, v13 quad_perm:[2,2,2,2] row_mask:0xf bank_mask:0xf
	v_fmac_f32_dpp v68, v242, v14 quad_perm:[3,3,3,3] row_mask:0xf bank_mask:0xf
	s_waitcnt lgkmcnt(6)
	v_fmac_f32_dpp v49, v243, v17 quad_perm:[0,0,0,0] row_mask:0xf bank_mask:0xf
	v_fmac_f32_dpp v66, v243, v19 quad_perm:[1,1,1,1] row_mask:0xf bank_mask:0xf
	v_fmac_f32_dpp v67, v243, v28 quad_perm:[2,2,2,2] row_mask:0xf bank_mask:0xf
	v_fmac_f32_dpp v68, v243, v35 quad_perm:[3,3,3,3] row_mask:0xf bank_mask:0xf
	s_waitcnt lgkmcnt(5)
	v_fmac_f32_dpp v49, v244, v36 quad_perm:[0,0,0,0] row_mask:0xf bank_mask:0xf
	v_fmac_f32_dpp v66, v244, v37 quad_perm:[1,1,1,1] row_mask:0xf bank_mask:0xf
	v_fmac_f32_dpp v67, v244, v38 quad_perm:[2,2,2,2] row_mask:0xf bank_mask:0xf
	v_fmac_f32_dpp v68, v244, v39 quad_perm:[3,3,3,3] row_mask:0xf bank_mask:0xf
	s_waitcnt lgkmcnt(4)
	v_fmac_f32_dpp v49, v245, v40 quad_perm:[0,0,0,0] row_mask:0xf bank_mask:0xf
	v_fmac_f32_dpp v66, v245, v41 quad_perm:[1,1,1,1] row_mask:0xf bank_mask:0xf
	v_fmac_f32_dpp v67, v245, v42 quad_perm:[2,2,2,2] row_mask:0xf bank_mask:0xf
	v_fmac_f32_dpp v68, v245, v43 quad_perm:[3,3,3,3] row_mask:0xf bank_mask:0xf
	s_waitcnt lgkmcnt(3)
	v_fmac_f32_dpp v49, v246, v44 quad_perm:[0,0,0,0] row_mask:0xf bank_mask:0xf
	v_fmac_f32_dpp v66, v246, v45 quad_perm:[1,1,1,1] row_mask:0xf bank_mask:0xf
	v_fmac_f32_dpp v67, v246, v46 quad_perm:[2,2,2,2] row_mask:0xf bank_mask:0xf
	v_fmac_f32_dpp v68, v246, v47 quad_perm:[3,3,3,3] row_mask:0xf bank_mask:0xf
	ds_read_b32 v240, v255 offset:7424
	ds_read_b32 v241, v255 offset:7440
	ds_read_b32 v242, v255 offset:7456
	ds_read_b32 v243, v255 offset:7472
	ds_read_b32 v244, v255 offset:7488
	ds_read_b32 v245, v255 offset:7504
	ds_read_b32 v246, v255 offset:7520
	ds_read_b32 v247, v255 offset:7536
	v_add_f32_e32 v49, v49, v66
	v_add_f32_e32 v50, v67, v68
	v_add_f32_e32 v49, v49, v50
	v_sub_f32_e32 v48, v48, v49
	s_waitcnt lgkmcnt(8)
	v_lshlrev_b32_e32 v49, 16, v238
	v_mul_f32_e32 v49, v239, v49
	s_cmp_eq_u64 s[16:17], 0
	s_cbranch_scc1 .LBB0_863
	v_mul_f32_e32 v49, v49, v254
.LBB0_863:
	ds_read_u16 v238, v18 offset:8160
	ds_read_b32 v239, v16 offset:120
	ds_read_b32 v254, v15 offset:120
	s_waitcnt lgkmcnt(10)
	v_mul_f32_dpp v66, v240, v2 quad_perm:[0,0,0,0] row_mask:0xf bank_mask:0xf
	v_mul_f32_dpp v67, v240, v3 quad_perm:[1,1,1,1] row_mask:0xf bank_mask:0xf
	v_mul_f32_dpp v68, v240, v4 quad_perm:[2,2,2,2] row_mask:0xf bank_mask:0xf
	v_mul_f32_dpp v69, v240, v5 quad_perm:[3,3,3,3] row_mask:0xf bank_mask:0xf
	s_waitcnt lgkmcnt(9)
	v_fmac_f32_dpp v66, v241, v6 quad_perm:[0,0,0,0] row_mask:0xf bank_mask:0xf
	v_fmac_f32_dpp v67, v241, v7 quad_perm:[1,1,1,1] row_mask:0xf bank_mask:0xf
	v_fmac_f32_dpp v68, v241, v8 quad_perm:[2,2,2,2] row_mask:0xf bank_mask:0xf
	v_fmac_f32_dpp v69, v241, v9 quad_perm:[3,3,3,3] row_mask:0xf bank_mask:0xf
	s_waitcnt lgkmcnt(8)
	v_fmac_f32_dpp v66, v242, v10 quad_perm:[0,0,0,0] row_mask:0xf bank_mask:0xf
	v_fmac_f32_dpp v67, v242, v12 quad_perm:[1,1,1,1] row_mask:0xf bank_mask:0xf
	v_fmac_f32_dpp v68, v242, v13 quad_perm:[2,2,2,2] row_mask:0xf bank_mask:0xf
	v_fmac_f32_dpp v69, v242, v14 quad_perm:[3,3,3,3] row_mask:0xf bank_mask:0xf
	s_waitcnt lgkmcnt(7)
	v_fmac_f32_dpp v66, v243, v17 quad_perm:[0,0,0,0] row_mask:0xf bank_mask:0xf
	v_fmac_f32_dpp v67, v243, v19 quad_perm:[1,1,1,1] row_mask:0xf bank_mask:0xf
	v_fmac_f32_dpp v68, v243, v28 quad_perm:[2,2,2,2] row_mask:0xf bank_mask:0xf
	v_fmac_f32_dpp v69, v243, v35 quad_perm:[3,3,3,3] row_mask:0xf bank_mask:0xf
	s_waitcnt lgkmcnt(6)
	v_fmac_f32_dpp v66, v244, v36 quad_perm:[0,0,0,0] row_mask:0xf bank_mask:0xf
	v_fmac_f32_dpp v67, v244, v37 quad_perm:[1,1,1,1] row_mask:0xf bank_mask:0xf
	v_fmac_f32_dpp v68, v244, v38 quad_perm:[2,2,2,2] row_mask:0xf bank_mask:0xf
	v_fmac_f32_dpp v69, v244, v39 quad_perm:[3,3,3,3] row_mask:0xf bank_mask:0xf
	s_waitcnt lgkmcnt(5)
	v_fmac_f32_dpp v66, v245, v40 quad_perm:[0,0,0,0] row_mask:0xf bank_mask:0xf
	v_fmac_f32_dpp v67, v245, v41 quad_perm:[1,1,1,1] row_mask:0xf bank_mask:0xf
	v_fmac_f32_dpp v68, v245, v42 quad_perm:[2,2,2,2] row_mask:0xf bank_mask:0xf
	v_fmac_f32_dpp v69, v245, v43 quad_perm:[3,3,3,3] row_mask:0xf bank_mask:0xf
	s_waitcnt lgkmcnt(4)
	v_fmac_f32_dpp v66, v246, v44 quad_perm:[0,0,0,0] row_mask:0xf bank_mask:0xf
	v_fmac_f32_dpp v67, v246, v45 quad_perm:[1,1,1,1] row_mask:0xf bank_mask:0xf
	v_fmac_f32_dpp v68, v246, v46 quad_perm:[2,2,2,2] row_mask:0xf bank_mask:0xf
	v_fmac_f32_dpp v69, v246, v47 quad_perm:[3,3,3,3] row_mask:0xf bank_mask:0xf
	s_waitcnt lgkmcnt(3)
	v_fmac_f32_dpp v66, v247, v48 quad_perm:[0,0,0,0] row_mask:0xf bank_mask:0xf
	ds_read_b32 v240, v255 offset:7680
	ds_read_b32 v241, v255 offset:7696
	ds_read_b32 v242, v255 offset:7712
	ds_read_b32 v243, v255 offset:7728
	ds_read_b32 v244, v255 offset:7744
	ds_read_b32 v245, v255 offset:7760
	ds_read_b32 v246, v255 offset:7776
	ds_read_b32 v247, v255 offset:7792
	v_add_f32_e32 v50, v67, v66
	v_add_f32_e32 v51, v68, v69
	v_add_f32_e32 v50, v51, v50
	v_sub_f32_e32 v49, v49, v50
	s_waitcnt lgkmcnt(8)
	v_lshlrev_b32_e32 v50, 16, v238
	v_mul_f32_e32 v50, v239, v50
	s_cmp_eq_u64 s[16:17], 0
	s_cbranch_scc1 .LBB0_865
	v_mul_f32_e32 v50, v50, v254
.LBB0_865:
	ds_read_u16 v238, v18 offset:8432
	ds_read_b32 v239, v16 offset:124
	ds_read_b32 v254, v15 offset:124
	s_waitcnt lgkmcnt(10)
	v_mul_f32_dpp v51, v240, v2 quad_perm:[0,0,0,0] row_mask:0xf bank_mask:0xf
	v_mul_f32_dpp v68, v240, v3 quad_perm:[1,1,1,1] row_mask:0xf bank_mask:0xf
	v_mul_f32_dpp v69, v240, v4 quad_perm:[2,2,2,2] row_mask:0xf bank_mask:0xf
	v_mul_f32_dpp v70, v240, v5 quad_perm:[3,3,3,3] row_mask:0xf bank_mask:0xf
	s_waitcnt lgkmcnt(9)
	v_fmac_f32_dpp v51, v241, v6 quad_perm:[0,0,0,0] row_mask:0xf bank_mask:0xf
	v_fmac_f32_dpp v68, v241, v7 quad_perm:[1,1,1,1] row_mask:0xf bank_mask:0xf
	v_fmac_f32_dpp v69, v241, v8 quad_perm:[2,2,2,2] row_mask:0xf bank_mask:0xf
	v_fmac_f32_dpp v70, v241, v9 quad_perm:[3,3,3,3] row_mask:0xf bank_mask:0xf
	s_waitcnt lgkmcnt(8)
	v_fmac_f32_dpp v51, v242, v10 quad_perm:[0,0,0,0] row_mask:0xf bank_mask:0xf
	v_fmac_f32_dpp v68, v242, v12 quad_perm:[1,1,1,1] row_mask:0xf bank_mask:0xf
	v_fmac_f32_dpp v69, v242, v13 quad_perm:[2,2,2,2] row_mask:0xf bank_mask:0xf
	v_fmac_f32_dpp v70, v242, v14 quad_perm:[3,3,3,3] row_mask:0xf bank_mask:0xf
	s_waitcnt lgkmcnt(7)
	v_fmac_f32_dpp v51, v243, v17 quad_perm:[0,0,0,0] row_mask:0xf bank_mask:0xf
	v_fmac_f32_dpp v68, v243, v19 quad_perm:[1,1,1,1] row_mask:0xf bank_mask:0xf
	v_fmac_f32_dpp v69, v243, v28 quad_perm:[2,2,2,2] row_mask:0xf bank_mask:0xf
	v_fmac_f32_dpp v70, v243, v35 quad_perm:[3,3,3,3] row_mask:0xf bank_mask:0xf
	s_waitcnt lgkmcnt(6)
	v_fmac_f32_dpp v51, v244, v36 quad_perm:[0,0,0,0] row_mask:0xf bank_mask:0xf
	v_fmac_f32_dpp v68, v244, v37 quad_perm:[1,1,1,1] row_mask:0xf bank_mask:0xf
	v_fmac_f32_dpp v69, v244, v38 quad_perm:[2,2,2,2] row_mask:0xf bank_mask:0xf
	v_fmac_f32_dpp v70, v244, v39 quad_perm:[3,3,3,3] row_mask:0xf bank_mask:0xf
	s_waitcnt lgkmcnt(5)
	v_fmac_f32_dpp v51, v245, v40 quad_perm:[0,0,0,0] row_mask:0xf bank_mask:0xf
	v_fmac_f32_dpp v68, v245, v41 quad_perm:[1,1,1,1] row_mask:0xf bank_mask:0xf
	v_fmac_f32_dpp v69, v245, v42 quad_perm:[2,2,2,2] row_mask:0xf bank_mask:0xf
	v_fmac_f32_dpp v70, v245, v43 quad_perm:[3,3,3,3] row_mask:0xf bank_mask:0xf
	s_waitcnt lgkmcnt(4)
	v_fmac_f32_dpp v51, v246, v44 quad_perm:[0,0,0,0] row_mask:0xf bank_mask:0xf
	v_fmac_f32_dpp v68, v246, v45 quad_perm:[1,1,1,1] row_mask:0xf bank_mask:0xf
	v_fmac_f32_dpp v69, v246, v46 quad_perm:[2,2,2,2] row_mask:0xf bank_mask:0xf
	v_fmac_f32_dpp v70, v246, v47 quad_perm:[3,3,3,3] row_mask:0xf bank_mask:0xf
	s_waitcnt lgkmcnt(3)
	v_fmac_f32_dpp v51, v247, v48 quad_perm:[0,0,0,0] row_mask:0xf bank_mask:0xf
	v_fmac_f32_dpp v68, v247, v49 quad_perm:[1,1,1,1] row_mask:0xf bank_mask:0xf
	ds_read_b32 v240, v255 offset:7936
	ds_read_b32 v241, v255 offset:7952
	ds_read_b32 v242, v255 offset:7968
	ds_read_b32 v243, v255 offset:7984
	ds_read_b32 v244, v255 offset:8000
	ds_read_b32 v245, v255 offset:8016
	ds_read_b32 v246, v255 offset:8032
	ds_read_b32 v247, v255 offset:8048
	v_add_f32_e32 v51, v51, v68
	v_add_f32_e32 v52, v69, v70
	v_add_f32_e32 v51, v52, v51
	v_sub_f32_e32 v50, v50, v51
	s_waitcnt lgkmcnt(8)
	v_lshlrev_b32_e32 v51, 16, v238
	v_mul_f32_e32 v51, v239, v51
	s_cmp_eq_u64 s[16:17], 0
	s_cbranch_scc1 .LBB0_867
	v_mul_f32_e32 v51, v51, v254
.LBB0_867:
	ds_read_u16 v238, v18 offset:8704
	ds_read_b32 v239, v16 offset:128
	ds_read_b32 v254, v15 offset:128
	s_waitcnt lgkmcnt(10)
	v_mul_f32_dpp v68, v240, v2 quad_perm:[0,0,0,0] row_mask:0xf bank_mask:0xf
	v_mul_f32_dpp v69, v240, v3 quad_perm:[1,1,1,1] row_mask:0xf bank_mask:0xf
	v_mul_f32_dpp v70, v240, v4 quad_perm:[2,2,2,2] row_mask:0xf bank_mask:0xf
	v_mul_f32_dpp v71, v240, v5 quad_perm:[3,3,3,3] row_mask:0xf bank_mask:0xf
	s_waitcnt lgkmcnt(9)
	v_fmac_f32_dpp v68, v241, v6 quad_perm:[0,0,0,0] row_mask:0xf bank_mask:0xf
	v_fmac_f32_dpp v69, v241, v7 quad_perm:[1,1,1,1] row_mask:0xf bank_mask:0xf
	v_fmac_f32_dpp v70, v241, v8 quad_perm:[2,2,2,2] row_mask:0xf bank_mask:0xf
	v_fmac_f32_dpp v71, v241, v9 quad_perm:[3,3,3,3] row_mask:0xf bank_mask:0xf
	s_waitcnt lgkmcnt(8)
	v_fmac_f32_dpp v68, v242, v10 quad_perm:[0,0,0,0] row_mask:0xf bank_mask:0xf
	v_fmac_f32_dpp v69, v242, v12 quad_perm:[1,1,1,1] row_mask:0xf bank_mask:0xf
	v_fmac_f32_dpp v70, v242, v13 quad_perm:[2,2,2,2] row_mask:0xf bank_mask:0xf
	v_fmac_f32_dpp v71, v242, v14 quad_perm:[3,3,3,3] row_mask:0xf bank_mask:0xf
	s_waitcnt lgkmcnt(7)
	v_fmac_f32_dpp v68, v243, v17 quad_perm:[0,0,0,0] row_mask:0xf bank_mask:0xf
	v_fmac_f32_dpp v69, v243, v19 quad_perm:[1,1,1,1] row_mask:0xf bank_mask:0xf
	v_fmac_f32_dpp v70, v243, v28 quad_perm:[2,2,2,2] row_mask:0xf bank_mask:0xf
	v_fmac_f32_dpp v71, v243, v35 quad_perm:[3,3,3,3] row_mask:0xf bank_mask:0xf
	s_waitcnt lgkmcnt(6)
	v_fmac_f32_dpp v68, v244, v36 quad_perm:[0,0,0,0] row_mask:0xf bank_mask:0xf
	v_fmac_f32_dpp v69, v244, v37 quad_perm:[1,1,1,1] row_mask:0xf bank_mask:0xf
	v_fmac_f32_dpp v70, v244, v38 quad_perm:[2,2,2,2] row_mask:0xf bank_mask:0xf
	v_fmac_f32_dpp v71, v244, v39 quad_perm:[3,3,3,3] row_mask:0xf bank_mask:0xf
	s_waitcnt lgkmcnt(5)
	v_fmac_f32_dpp v68, v245, v40 quad_perm:[0,0,0,0] row_mask:0xf bank_mask:0xf
	v_fmac_f32_dpp v69, v245, v41 quad_perm:[1,1,1,1] row_mask:0xf bank_mask:0xf
	v_fmac_f32_dpp v70, v245, v42 quad_perm:[2,2,2,2] row_mask:0xf bank_mask:0xf
	v_fmac_f32_dpp v71, v245, v43 quad_perm:[3,3,3,3] row_mask:0xf bank_mask:0xf
	s_waitcnt lgkmcnt(4)
	v_fmac_f32_dpp v68, v246, v44 quad_perm:[0,0,0,0] row_mask:0xf bank_mask:0xf
	v_fmac_f32_dpp v69, v246, v45 quad_perm:[1,1,1,1] row_mask:0xf bank_mask:0xf
	v_fmac_f32_dpp v70, v246, v46 quad_perm:[2,2,2,2] row_mask:0xf bank_mask:0xf
	v_fmac_f32_dpp v71, v246, v47 quad_perm:[3,3,3,3] row_mask:0xf bank_mask:0xf
	s_waitcnt lgkmcnt(3)
	v_fmac_f32_dpp v68, v247, v48 quad_perm:[0,0,0,0] row_mask:0xf bank_mask:0xf
	v_fmac_f32_dpp v69, v247, v49 quad_perm:[1,1,1,1] row_mask:0xf bank_mask:0xf
	v_fmac_f32_dpp v70, v247, v50 quad_perm:[2,2,2,2] row_mask:0xf bank_mask:0xf
	ds_read_b32 v240, v255 offset:8192
	ds_read_b32 v241, v255 offset:8208
	ds_read_b32 v242, v255 offset:8224
	ds_read_b32 v243, v255 offset:8240
	ds_read_b32 v244, v255 offset:8256
	ds_read_b32 v245, v255 offset:8272
	ds_read_b32 v246, v255 offset:8288
	ds_read_b32 v247, v255 offset:8304
	v_add_f32_e32 v52, v68, v69
	v_add_f32_e32 v53, v71, v70
	v_add_f32_e32 v52, v52, v53
	v_sub_f32_e32 v51, v51, v52
	s_waitcnt lgkmcnt(8)
	v_lshlrev_b32_e32 v52, 16, v238
	v_mul_f32_e32 v52, v239, v52
	s_cmp_eq_u64 s[16:17], 0
	s_cbranch_scc1 .LBB0_869
	v_mul_f32_e32 v52, v52, v254
.LBB0_869:
	ds_read_u16 v238, v18 offset:8976
	ds_read_b32 v239, v16 offset:132
	ds_read_b32 v254, v15 offset:132
	s_waitcnt lgkmcnt(10)
	v_mul_f32_dpp v53, v240, v2 quad_perm:[0,0,0,0] row_mask:0xf bank_mask:0xf
	v_mul_f32_dpp v70, v240, v3 quad_perm:[1,1,1,1] row_mask:0xf bank_mask:0xf
	v_mul_f32_dpp v71, v240, v4 quad_perm:[2,2,2,2] row_mask:0xf bank_mask:0xf
	v_mul_f32_dpp v72, v240, v5 quad_perm:[3,3,3,3] row_mask:0xf bank_mask:0xf
	s_waitcnt lgkmcnt(9)
	v_fmac_f32_dpp v53, v241, v6 quad_perm:[0,0,0,0] row_mask:0xf bank_mask:0xf
	v_fmac_f32_dpp v70, v241, v7 quad_perm:[1,1,1,1] row_mask:0xf bank_mask:0xf
	v_fmac_f32_dpp v71, v241, v8 quad_perm:[2,2,2,2] row_mask:0xf bank_mask:0xf
	v_fmac_f32_dpp v72, v241, v9 quad_perm:[3,3,3,3] row_mask:0xf bank_mask:0xf
	s_waitcnt lgkmcnt(8)
	v_fmac_f32_dpp v53, v242, v10 quad_perm:[0,0,0,0] row_mask:0xf bank_mask:0xf
	v_fmac_f32_dpp v70, v242, v12 quad_perm:[1,1,1,1] row_mask:0xf bank_mask:0xf
	v_fmac_f32_dpp v71, v242, v13 quad_perm:[2,2,2,2] row_mask:0xf bank_mask:0xf
	v_fmac_f32_dpp v72, v242, v14 quad_perm:[3,3,3,3] row_mask:0xf bank_mask:0xf
	s_waitcnt lgkmcnt(7)
	v_fmac_f32_dpp v53, v243, v17 quad_perm:[0,0,0,0] row_mask:0xf bank_mask:0xf
	v_fmac_f32_dpp v70, v243, v19 quad_perm:[1,1,1,1] row_mask:0xf bank_mask:0xf
	v_fmac_f32_dpp v71, v243, v28 quad_perm:[2,2,2,2] row_mask:0xf bank_mask:0xf
	v_fmac_f32_dpp v72, v243, v35 quad_perm:[3,3,3,3] row_mask:0xf bank_mask:0xf
	s_waitcnt lgkmcnt(6)
	v_fmac_f32_dpp v53, v244, v36 quad_perm:[0,0,0,0] row_mask:0xf bank_mask:0xf
	v_fmac_f32_dpp v70, v244, v37 quad_perm:[1,1,1,1] row_mask:0xf bank_mask:0xf
	v_fmac_f32_dpp v71, v244, v38 quad_perm:[2,2,2,2] row_mask:0xf bank_mask:0xf
	v_fmac_f32_dpp v72, v244, v39 quad_perm:[3,3,3,3] row_mask:0xf bank_mask:0xf
	s_waitcnt lgkmcnt(5)
	v_fmac_f32_dpp v53, v245, v40 quad_perm:[0,0,0,0] row_mask:0xf bank_mask:0xf
	v_fmac_f32_dpp v70, v245, v41 quad_perm:[1,1,1,1] row_mask:0xf bank_mask:0xf
	v_fmac_f32_dpp v71, v245, v42 quad_perm:[2,2,2,2] row_mask:0xf bank_mask:0xf
	v_fmac_f32_dpp v72, v245, v43 quad_perm:[3,3,3,3] row_mask:0xf bank_mask:0xf
	s_waitcnt lgkmcnt(4)
	v_fmac_f32_dpp v53, v246, v44 quad_perm:[0,0,0,0] row_mask:0xf bank_mask:0xf
	v_fmac_f32_dpp v70, v246, v45 quad_perm:[1,1,1,1] row_mask:0xf bank_mask:0xf
	v_fmac_f32_dpp v71, v246, v46 quad_perm:[2,2,2,2] row_mask:0xf bank_mask:0xf
	v_fmac_f32_dpp v72, v246, v47 quad_perm:[3,3,3,3] row_mask:0xf bank_mask:0xf
	s_waitcnt lgkmcnt(3)
	v_fmac_f32_dpp v53, v247, v48 quad_perm:[0,0,0,0] row_mask:0xf bank_mask:0xf
	v_fmac_f32_dpp v70, v247, v49 quad_perm:[1,1,1,1] row_mask:0xf bank_mask:0xf
	v_fmac_f32_dpp v71, v247, v50 quad_perm:[2,2,2,2] row_mask:0xf bank_mask:0xf
	v_fmac_f32_dpp v72, v247, v51 quad_perm:[3,3,3,3] row_mask:0xf bank_mask:0xf
	ds_read_b32 v240, v255 offset:8448
	ds_read_b32 v241, v255 offset:8464
	ds_read_b32 v242, v255 offset:8480
	ds_read_b32 v243, v255 offset:8496
	ds_read_b32 v244, v255 offset:8512
	ds_read_b32 v245, v255 offset:8528
	ds_read_b32 v246, v255 offset:8544
	ds_read_b32 v247, v255 offset:8560
	ds_read_b32 v248, v255 offset:8576
	v_add_f32_e32 v53, v53, v70
	v_add_f32_e32 v54, v71, v72
	v_add_f32_e32 v53, v53, v54
	v_sub_f32_e32 v52, v52, v53
	s_waitcnt lgkmcnt(9)
	v_lshlrev_b32_e32 v53, 16, v238
	v_mul_f32_e32 v53, v239, v53
	s_cmp_eq_u64 s[16:17], 0
	s_cbranch_scc1 .LBB0_871
	v_mul_f32_e32 v53, v53, v254
.LBB0_871:
	ds_read_u16 v238, v18 offset:9248
	ds_read_b32 v239, v16 offset:136
	ds_read_b32 v254, v15 offset:136
	s_waitcnt lgkmcnt(11)
	v_mul_f32_dpp v70, v240, v2 quad_perm:[0,0,0,0] row_mask:0xf bank_mask:0xf
	v_mul_f32_dpp v71, v240, v3 quad_perm:[1,1,1,1] row_mask:0xf bank_mask:0xf
	v_mul_f32_dpp v72, v240, v4 quad_perm:[2,2,2,2] row_mask:0xf bank_mask:0xf
	v_mul_f32_dpp v73, v240, v5 quad_perm:[3,3,3,3] row_mask:0xf bank_mask:0xf
	s_waitcnt lgkmcnt(10)
	v_fmac_f32_dpp v70, v241, v6 quad_perm:[0,0,0,0] row_mask:0xf bank_mask:0xf
	v_fmac_f32_dpp v71, v241, v7 quad_perm:[1,1,1,1] row_mask:0xf bank_mask:0xf
	v_fmac_f32_dpp v72, v241, v8 quad_perm:[2,2,2,2] row_mask:0xf bank_mask:0xf
	v_fmac_f32_dpp v73, v241, v9 quad_perm:[3,3,3,3] row_mask:0xf bank_mask:0xf
	s_waitcnt lgkmcnt(9)
	v_fmac_f32_dpp v70, v242, v10 quad_perm:[0,0,0,0] row_mask:0xf bank_mask:0xf
	v_fmac_f32_dpp v71, v242, v12 quad_perm:[1,1,1,1] row_mask:0xf bank_mask:0xf
	v_fmac_f32_dpp v72, v242, v13 quad_perm:[2,2,2,2] row_mask:0xf bank_mask:0xf
	v_fmac_f32_dpp v73, v242, v14 quad_perm:[3,3,3,3] row_mask:0xf bank_mask:0xf
	s_waitcnt lgkmcnt(8)
	v_fmac_f32_dpp v70, v243, v17 quad_perm:[0,0,0,0] row_mask:0xf bank_mask:0xf
	v_fmac_f32_dpp v71, v243, v19 quad_perm:[1,1,1,1] row_mask:0xf bank_mask:0xf
	v_fmac_f32_dpp v72, v243, v28 quad_perm:[2,2,2,2] row_mask:0xf bank_mask:0xf
	v_fmac_f32_dpp v73, v243, v35 quad_perm:[3,3,3,3] row_mask:0xf bank_mask:0xf
	s_waitcnt lgkmcnt(7)
	v_fmac_f32_dpp v70, v244, v36 quad_perm:[0,0,0,0] row_mask:0xf bank_mask:0xf
	v_fmac_f32_dpp v71, v244, v37 quad_perm:[1,1,1,1] row_mask:0xf bank_mask:0xf
	v_fmac_f32_dpp v72, v244, v38 quad_perm:[2,2,2,2] row_mask:0xf bank_mask:0xf
	v_fmac_f32_dpp v73, v244, v39 quad_perm:[3,3,3,3] row_mask:0xf bank_mask:0xf
	s_waitcnt lgkmcnt(6)
	v_fmac_f32_dpp v70, v245, v40 quad_perm:[0,0,0,0] row_mask:0xf bank_mask:0xf
	v_fmac_f32_dpp v71, v245, v41 quad_perm:[1,1,1,1] row_mask:0xf bank_mask:0xf
	v_fmac_f32_dpp v72, v245, v42 quad_perm:[2,2,2,2] row_mask:0xf bank_mask:0xf
	v_fmac_f32_dpp v73, v245, v43 quad_perm:[3,3,3,3] row_mask:0xf bank_mask:0xf
	s_waitcnt lgkmcnt(5)
	v_fmac_f32_dpp v70, v246, v44 quad_perm:[0,0,0,0] row_mask:0xf bank_mask:0xf
	v_fmac_f32_dpp v71, v246, v45 quad_perm:[1,1,1,1] row_mask:0xf bank_mask:0xf
	v_fmac_f32_dpp v72, v246, v46 quad_perm:[2,2,2,2] row_mask:0xf bank_mask:0xf
	v_fmac_f32_dpp v73, v246, v47 quad_perm:[3,3,3,3] row_mask:0xf bank_mask:0xf
	s_waitcnt lgkmcnt(4)
	v_fmac_f32_dpp v70, v247, v48 quad_perm:[0,0,0,0] row_mask:0xf bank_mask:0xf
	v_fmac_f32_dpp v71, v247, v49 quad_perm:[1,1,1,1] row_mask:0xf bank_mask:0xf
	v_fmac_f32_dpp v72, v247, v50 quad_perm:[2,2,2,2] row_mask:0xf bank_mask:0xf
	v_fmac_f32_dpp v73, v247, v51 quad_perm:[3,3,3,3] row_mask:0xf bank_mask:0xf
	s_waitcnt lgkmcnt(3)
	v_fmac_f32_dpp v70, v248, v52 quad_perm:[0,0,0,0] row_mask:0xf bank_mask:0xf
	ds_read_b32 v240, v255 offset:8704
	ds_read_b32 v241, v255 offset:8720
	ds_read_b32 v242, v255 offset:8736
	ds_read_b32 v243, v255 offset:8752
	ds_read_b32 v244, v255 offset:8768
	ds_read_b32 v245, v255 offset:8784
	ds_read_b32 v246, v255 offset:8800
	ds_read_b32 v247, v255 offset:8816
	ds_read_b32 v248, v255 offset:8832
	v_add_f32_e32 v54, v71, v70
	v_add_f32_e32 v55, v72, v73
	v_add_f32_e32 v54, v55, v54
	v_sub_f32_e32 v53, v53, v54
	s_waitcnt lgkmcnt(9)
	v_lshlrev_b32_e32 v54, 16, v238
	v_mul_f32_e32 v54, v239, v54
	s_cmp_eq_u64 s[16:17], 0
	s_cbranch_scc1 .LBB0_873
	v_mul_f32_e32 v54, v54, v254
.LBB0_873:
	ds_read_u16 v238, v18 offset:9520
	ds_read_b32 v239, v16 offset:140
	ds_read_b32 v254, v15 offset:140
	s_waitcnt lgkmcnt(11)
	v_mul_f32_dpp v55, v240, v2 quad_perm:[0,0,0,0] row_mask:0xf bank_mask:0xf
	v_mul_f32_dpp v72, v240, v3 quad_perm:[1,1,1,1] row_mask:0xf bank_mask:0xf
	v_mul_f32_dpp v73, v240, v4 quad_perm:[2,2,2,2] row_mask:0xf bank_mask:0xf
	v_mul_f32_dpp v74, v240, v5 quad_perm:[3,3,3,3] row_mask:0xf bank_mask:0xf
	s_waitcnt lgkmcnt(10)
	v_fmac_f32_dpp v55, v241, v6 quad_perm:[0,0,0,0] row_mask:0xf bank_mask:0xf
	v_fmac_f32_dpp v72, v241, v7 quad_perm:[1,1,1,1] row_mask:0xf bank_mask:0xf
	v_fmac_f32_dpp v73, v241, v8 quad_perm:[2,2,2,2] row_mask:0xf bank_mask:0xf
	v_fmac_f32_dpp v74, v241, v9 quad_perm:[3,3,3,3] row_mask:0xf bank_mask:0xf
	s_waitcnt lgkmcnt(9)
	v_fmac_f32_dpp v55, v242, v10 quad_perm:[0,0,0,0] row_mask:0xf bank_mask:0xf
	v_fmac_f32_dpp v72, v242, v12 quad_perm:[1,1,1,1] row_mask:0xf bank_mask:0xf
	v_fmac_f32_dpp v73, v242, v13 quad_perm:[2,2,2,2] row_mask:0xf bank_mask:0xf
	v_fmac_f32_dpp v74, v242, v14 quad_perm:[3,3,3,3] row_mask:0xf bank_mask:0xf
	s_waitcnt lgkmcnt(8)
	v_fmac_f32_dpp v55, v243, v17 quad_perm:[0,0,0,0] row_mask:0xf bank_mask:0xf
	v_fmac_f32_dpp v72, v243, v19 quad_perm:[1,1,1,1] row_mask:0xf bank_mask:0xf
	v_fmac_f32_dpp v73, v243, v28 quad_perm:[2,2,2,2] row_mask:0xf bank_mask:0xf
	v_fmac_f32_dpp v74, v243, v35 quad_perm:[3,3,3,3] row_mask:0xf bank_mask:0xf
	s_waitcnt lgkmcnt(7)
	v_fmac_f32_dpp v55, v244, v36 quad_perm:[0,0,0,0] row_mask:0xf bank_mask:0xf
	v_fmac_f32_dpp v72, v244, v37 quad_perm:[1,1,1,1] row_mask:0xf bank_mask:0xf
	v_fmac_f32_dpp v73, v244, v38 quad_perm:[2,2,2,2] row_mask:0xf bank_mask:0xf
	v_fmac_f32_dpp v74, v244, v39 quad_perm:[3,3,3,3] row_mask:0xf bank_mask:0xf
	s_waitcnt lgkmcnt(6)
	v_fmac_f32_dpp v55, v245, v40 quad_perm:[0,0,0,0] row_mask:0xf bank_mask:0xf
	v_fmac_f32_dpp v72, v245, v41 quad_perm:[1,1,1,1] row_mask:0xf bank_mask:0xf
	v_fmac_f32_dpp v73, v245, v42 quad_perm:[2,2,2,2] row_mask:0xf bank_mask:0xf
	v_fmac_f32_dpp v74, v245, v43 quad_perm:[3,3,3,3] row_mask:0xf bank_mask:0xf
	s_waitcnt lgkmcnt(5)
	v_fmac_f32_dpp v55, v246, v44 quad_perm:[0,0,0,0] row_mask:0xf bank_mask:0xf
	v_fmac_f32_dpp v72, v246, v45 quad_perm:[1,1,1,1] row_mask:0xf bank_mask:0xf
	v_fmac_f32_dpp v73, v246, v46 quad_perm:[2,2,2,2] row_mask:0xf bank_mask:0xf
	v_fmac_f32_dpp v74, v246, v47 quad_perm:[3,3,3,3] row_mask:0xf bank_mask:0xf
	s_waitcnt lgkmcnt(4)
	v_fmac_f32_dpp v55, v247, v48 quad_perm:[0,0,0,0] row_mask:0xf bank_mask:0xf
	v_fmac_f32_dpp v72, v247, v49 quad_perm:[1,1,1,1] row_mask:0xf bank_mask:0xf
	v_fmac_f32_dpp v73, v247, v50 quad_perm:[2,2,2,2] row_mask:0xf bank_mask:0xf
	v_fmac_f32_dpp v74, v247, v51 quad_perm:[3,3,3,3] row_mask:0xf bank_mask:0xf
	s_waitcnt lgkmcnt(3)
	v_fmac_f32_dpp v55, v248, v52 quad_perm:[0,0,0,0] row_mask:0xf bank_mask:0xf
	v_fmac_f32_dpp v72, v248, v53 quad_perm:[1,1,1,1] row_mask:0xf bank_mask:0xf
	ds_read_b32 v240, v255 offset:8960
	ds_read_b32 v241, v255 offset:8976
	ds_read_b32 v242, v255 offset:8992
	ds_read_b32 v243, v255 offset:9008
	ds_read_b32 v244, v255 offset:9024
	ds_read_b32 v245, v255 offset:9040
	ds_read_b32 v246, v255 offset:9056
	ds_read_b32 v247, v255 offset:9072
	ds_read_b32 v248, v255 offset:9088
	v_add_f32_e32 v55, v55, v72
	v_add_f32_e32 v56, v73, v74
	v_add_f32_e32 v55, v56, v55
	v_sub_f32_e32 v54, v54, v55
	s_waitcnt lgkmcnt(9)
	v_lshlrev_b32_e32 v55, 16, v238
	v_mul_f32_e32 v55, v239, v55
	s_cmp_eq_u64 s[16:17], 0
	s_cbranch_scc1 .LBB0_875
	v_mul_f32_e32 v55, v55, v254
.LBB0_875:
	ds_read_u16 v238, v18 offset:9792
	ds_read_b32 v239, v16 offset:144
	ds_read_b32 v254, v15 offset:144
	s_waitcnt lgkmcnt(11)
	v_mul_f32_dpp v72, v240, v2 quad_perm:[0,0,0,0] row_mask:0xf bank_mask:0xf
	v_mul_f32_dpp v73, v240, v3 quad_perm:[1,1,1,1] row_mask:0xf bank_mask:0xf
	v_mul_f32_dpp v74, v240, v4 quad_perm:[2,2,2,2] row_mask:0xf bank_mask:0xf
	v_mul_f32_dpp v75, v240, v5 quad_perm:[3,3,3,3] row_mask:0xf bank_mask:0xf
	s_waitcnt lgkmcnt(10)
	v_fmac_f32_dpp v72, v241, v6 quad_perm:[0,0,0,0] row_mask:0xf bank_mask:0xf
	v_fmac_f32_dpp v73, v241, v7 quad_perm:[1,1,1,1] row_mask:0xf bank_mask:0xf
	v_fmac_f32_dpp v74, v241, v8 quad_perm:[2,2,2,2] row_mask:0xf bank_mask:0xf
	v_fmac_f32_dpp v75, v241, v9 quad_perm:[3,3,3,3] row_mask:0xf bank_mask:0xf
	s_waitcnt lgkmcnt(9)
	v_fmac_f32_dpp v72, v242, v10 quad_perm:[0,0,0,0] row_mask:0xf bank_mask:0xf
	v_fmac_f32_dpp v73, v242, v12 quad_perm:[1,1,1,1] row_mask:0xf bank_mask:0xf
	v_fmac_f32_dpp v74, v242, v13 quad_perm:[2,2,2,2] row_mask:0xf bank_mask:0xf
	v_fmac_f32_dpp v75, v242, v14 quad_perm:[3,3,3,3] row_mask:0xf bank_mask:0xf
	s_waitcnt lgkmcnt(8)
	v_fmac_f32_dpp v72, v243, v17 quad_perm:[0,0,0,0] row_mask:0xf bank_mask:0xf
	v_fmac_f32_dpp v73, v243, v19 quad_perm:[1,1,1,1] row_mask:0xf bank_mask:0xf
	v_fmac_f32_dpp v74, v243, v28 quad_perm:[2,2,2,2] row_mask:0xf bank_mask:0xf
	v_fmac_f32_dpp v75, v243, v35 quad_perm:[3,3,3,3] row_mask:0xf bank_mask:0xf
	s_waitcnt lgkmcnt(7)
	v_fmac_f32_dpp v72, v244, v36 quad_perm:[0,0,0,0] row_mask:0xf bank_mask:0xf
	v_fmac_f32_dpp v73, v244, v37 quad_perm:[1,1,1,1] row_mask:0xf bank_mask:0xf
	v_fmac_f32_dpp v74, v244, v38 quad_perm:[2,2,2,2] row_mask:0xf bank_mask:0xf
	v_fmac_f32_dpp v75, v244, v39 quad_perm:[3,3,3,3] row_mask:0xf bank_mask:0xf
	s_waitcnt lgkmcnt(6)
	v_fmac_f32_dpp v72, v245, v40 quad_perm:[0,0,0,0] row_mask:0xf bank_mask:0xf
	v_fmac_f32_dpp v73, v245, v41 quad_perm:[1,1,1,1] row_mask:0xf bank_mask:0xf
	v_fmac_f32_dpp v74, v245, v42 quad_perm:[2,2,2,2] row_mask:0xf bank_mask:0xf
	v_fmac_f32_dpp v75, v245, v43 quad_perm:[3,3,3,3] row_mask:0xf bank_mask:0xf
	s_waitcnt lgkmcnt(5)
	v_fmac_f32_dpp v72, v246, v44 quad_perm:[0,0,0,0] row_mask:0xf bank_mask:0xf
	v_fmac_f32_dpp v73, v246, v45 quad_perm:[1,1,1,1] row_mask:0xf bank_mask:0xf
	v_fmac_f32_dpp v74, v246, v46 quad_perm:[2,2,2,2] row_mask:0xf bank_mask:0xf
	v_fmac_f32_dpp v75, v246, v47 quad_perm:[3,3,3,3] row_mask:0xf bank_mask:0xf
	s_waitcnt lgkmcnt(4)
	v_fmac_f32_dpp v72, v247, v48 quad_perm:[0,0,0,0] row_mask:0xf bank_mask:0xf
	v_fmac_f32_dpp v73, v247, v49 quad_perm:[1,1,1,1] row_mask:0xf bank_mask:0xf
	v_fmac_f32_dpp v74, v247, v50 quad_perm:[2,2,2,2] row_mask:0xf bank_mask:0xf
	v_fmac_f32_dpp v75, v247, v51 quad_perm:[3,3,3,3] row_mask:0xf bank_mask:0xf
	s_waitcnt lgkmcnt(3)
	v_fmac_f32_dpp v72, v248, v52 quad_perm:[0,0,0,0] row_mask:0xf bank_mask:0xf
	v_fmac_f32_dpp v73, v248, v53 quad_perm:[1,1,1,1] row_mask:0xf bank_mask:0xf
	v_fmac_f32_dpp v74, v248, v54 quad_perm:[2,2,2,2] row_mask:0xf bank_mask:0xf
	ds_read_b32 v240, v255 offset:9216
	ds_read_b32 v241, v255 offset:9232
	ds_read_b32 v242, v255 offset:9248
	ds_read_b32 v243, v255 offset:9264
	ds_read_b32 v244, v255 offset:9280
	ds_read_b32 v245, v255 offset:9296
	ds_read_b32 v246, v255 offset:9312
	ds_read_b32 v247, v255 offset:9328
	ds_read_b32 v248, v255 offset:9344
	v_add_f32_e32 v56, v72, v73
	v_add_f32_e32 v57, v75, v74
	v_add_f32_e32 v56, v56, v57
	v_sub_f32_e32 v55, v55, v56
	s_waitcnt lgkmcnt(9)
	v_lshlrev_b32_e32 v56, 16, v238
	v_mul_f32_e32 v56, v239, v56
	s_cmp_eq_u64 s[16:17], 0
	s_cbranch_scc1 .LBB0_877
	v_mul_f32_e32 v56, v56, v254
.LBB0_877:
	ds_read_u16 v238, v18 offset:10064
	ds_read_b32 v239, v16 offset:148
	ds_read_b32 v254, v15 offset:148
	s_waitcnt lgkmcnt(11)
	v_mul_f32_dpp v57, v240, v2 quad_perm:[0,0,0,0] row_mask:0xf bank_mask:0xf
	v_mul_f32_dpp v74, v240, v3 quad_perm:[1,1,1,1] row_mask:0xf bank_mask:0xf
	v_mul_f32_dpp v75, v240, v4 quad_perm:[2,2,2,2] row_mask:0xf bank_mask:0xf
	v_mul_f32_dpp v76, v240, v5 quad_perm:[3,3,3,3] row_mask:0xf bank_mask:0xf
	s_waitcnt lgkmcnt(10)
	v_fmac_f32_dpp v57, v241, v6 quad_perm:[0,0,0,0] row_mask:0xf bank_mask:0xf
	v_fmac_f32_dpp v74, v241, v7 quad_perm:[1,1,1,1] row_mask:0xf bank_mask:0xf
	v_fmac_f32_dpp v75, v241, v8 quad_perm:[2,2,2,2] row_mask:0xf bank_mask:0xf
	v_fmac_f32_dpp v76, v241, v9 quad_perm:[3,3,3,3] row_mask:0xf bank_mask:0xf
	s_waitcnt lgkmcnt(9)
	v_fmac_f32_dpp v57, v242, v10 quad_perm:[0,0,0,0] row_mask:0xf bank_mask:0xf
	v_fmac_f32_dpp v74, v242, v12 quad_perm:[1,1,1,1] row_mask:0xf bank_mask:0xf
	v_fmac_f32_dpp v75, v242, v13 quad_perm:[2,2,2,2] row_mask:0xf bank_mask:0xf
	v_fmac_f32_dpp v76, v242, v14 quad_perm:[3,3,3,3] row_mask:0xf bank_mask:0xf
	s_waitcnt lgkmcnt(8)
	v_fmac_f32_dpp v57, v243, v17 quad_perm:[0,0,0,0] row_mask:0xf bank_mask:0xf
	v_fmac_f32_dpp v74, v243, v19 quad_perm:[1,1,1,1] row_mask:0xf bank_mask:0xf
	v_fmac_f32_dpp v75, v243, v28 quad_perm:[2,2,2,2] row_mask:0xf bank_mask:0xf
	v_fmac_f32_dpp v76, v243, v35 quad_perm:[3,3,3,3] row_mask:0xf bank_mask:0xf
	s_waitcnt lgkmcnt(7)
	v_fmac_f32_dpp v57, v244, v36 quad_perm:[0,0,0,0] row_mask:0xf bank_mask:0xf
	v_fmac_f32_dpp v74, v244, v37 quad_perm:[1,1,1,1] row_mask:0xf bank_mask:0xf
	v_fmac_f32_dpp v75, v244, v38 quad_perm:[2,2,2,2] row_mask:0xf bank_mask:0xf
	v_fmac_f32_dpp v76, v244, v39 quad_perm:[3,3,3,3] row_mask:0xf bank_mask:0xf
	s_waitcnt lgkmcnt(6)
	v_fmac_f32_dpp v57, v245, v40 quad_perm:[0,0,0,0] row_mask:0xf bank_mask:0xf
	v_fmac_f32_dpp v74, v245, v41 quad_perm:[1,1,1,1] row_mask:0xf bank_mask:0xf
	v_fmac_f32_dpp v75, v245, v42 quad_perm:[2,2,2,2] row_mask:0xf bank_mask:0xf
	v_fmac_f32_dpp v76, v245, v43 quad_perm:[3,3,3,3] row_mask:0xf bank_mask:0xf
	s_waitcnt lgkmcnt(5)
	v_fmac_f32_dpp v57, v246, v44 quad_perm:[0,0,0,0] row_mask:0xf bank_mask:0xf
	v_fmac_f32_dpp v74, v246, v45 quad_perm:[1,1,1,1] row_mask:0xf bank_mask:0xf
	v_fmac_f32_dpp v75, v246, v46 quad_perm:[2,2,2,2] row_mask:0xf bank_mask:0xf
	v_fmac_f32_dpp v76, v246, v47 quad_perm:[3,3,3,3] row_mask:0xf bank_mask:0xf
	s_waitcnt lgkmcnt(4)
	v_fmac_f32_dpp v57, v247, v48 quad_perm:[0,0,0,0] row_mask:0xf bank_mask:0xf
	v_fmac_f32_dpp v74, v247, v49 quad_perm:[1,1,1,1] row_mask:0xf bank_mask:0xf
	v_fmac_f32_dpp v75, v247, v50 quad_perm:[2,2,2,2] row_mask:0xf bank_mask:0xf
	v_fmac_f32_dpp v76, v247, v51 quad_perm:[3,3,3,3] row_mask:0xf bank_mask:0xf
	s_waitcnt lgkmcnt(3)
	v_fmac_f32_dpp v57, v248, v52 quad_perm:[0,0,0,0] row_mask:0xf bank_mask:0xf
	v_fmac_f32_dpp v74, v248, v53 quad_perm:[1,1,1,1] row_mask:0xf bank_mask:0xf
	v_fmac_f32_dpp v75, v248, v54 quad_perm:[2,2,2,2] row_mask:0xf bank_mask:0xf
	v_fmac_f32_dpp v76, v248, v55 quad_perm:[3,3,3,3] row_mask:0xf bank_mask:0xf
	ds_read_b32 v240, v255 offset:9472
	ds_read_b32 v241, v255 offset:9488
	ds_read_b32 v242, v255 offset:9504
	ds_read_b32 v243, v255 offset:9520
	ds_read_b32 v244, v255 offset:9536
	ds_read_b32 v245, v255 offset:9552
	ds_read_b32 v246, v255 offset:9568
	ds_read_b32 v247, v255 offset:9584
	ds_read_b32 v248, v255 offset:9600
	ds_read_b32 v249, v255 offset:9616
	v_add_f32_e32 v57, v57, v74
	v_add_f32_e32 v58, v75, v76
	v_add_f32_e32 v57, v57, v58
	v_sub_f32_e32 v56, v56, v57
	s_waitcnt lgkmcnt(10)
	v_lshlrev_b32_e32 v57, 16, v238
	v_mul_f32_e32 v57, v239, v57
	s_cmp_eq_u64 s[16:17], 0
	s_cbranch_scc1 .LBB0_879
	v_mul_f32_e32 v57, v57, v254
.LBB0_879:
	ds_read_u16 v238, v18 offset:10336
	ds_read_b32 v239, v16 offset:152
	ds_read_b32 v254, v15 offset:152
	s_waitcnt lgkmcnt(12)
	v_mul_f32_dpp v74, v240, v2 quad_perm:[0,0,0,0] row_mask:0xf bank_mask:0xf
	v_mul_f32_dpp v75, v240, v3 quad_perm:[1,1,1,1] row_mask:0xf bank_mask:0xf
	v_mul_f32_dpp v76, v240, v4 quad_perm:[2,2,2,2] row_mask:0xf bank_mask:0xf
	v_mul_f32_dpp v77, v240, v5 quad_perm:[3,3,3,3] row_mask:0xf bank_mask:0xf
	s_waitcnt lgkmcnt(11)
	v_fmac_f32_dpp v74, v241, v6 quad_perm:[0,0,0,0] row_mask:0xf bank_mask:0xf
	v_fmac_f32_dpp v75, v241, v7 quad_perm:[1,1,1,1] row_mask:0xf bank_mask:0xf
	v_fmac_f32_dpp v76, v241, v8 quad_perm:[2,2,2,2] row_mask:0xf bank_mask:0xf
	v_fmac_f32_dpp v77, v241, v9 quad_perm:[3,3,3,3] row_mask:0xf bank_mask:0xf
	s_waitcnt lgkmcnt(10)
	v_fmac_f32_dpp v74, v242, v10 quad_perm:[0,0,0,0] row_mask:0xf bank_mask:0xf
	v_fmac_f32_dpp v75, v242, v12 quad_perm:[1,1,1,1] row_mask:0xf bank_mask:0xf
	v_fmac_f32_dpp v76, v242, v13 quad_perm:[2,2,2,2] row_mask:0xf bank_mask:0xf
	v_fmac_f32_dpp v77, v242, v14 quad_perm:[3,3,3,3] row_mask:0xf bank_mask:0xf
	s_waitcnt lgkmcnt(9)
	v_fmac_f32_dpp v74, v243, v17 quad_perm:[0,0,0,0] row_mask:0xf bank_mask:0xf
	v_fmac_f32_dpp v75, v243, v19 quad_perm:[1,1,1,1] row_mask:0xf bank_mask:0xf
	v_fmac_f32_dpp v76, v243, v28 quad_perm:[2,2,2,2] row_mask:0xf bank_mask:0xf
	v_fmac_f32_dpp v77, v243, v35 quad_perm:[3,3,3,3] row_mask:0xf bank_mask:0xf
	s_waitcnt lgkmcnt(8)
	v_fmac_f32_dpp v74, v244, v36 quad_perm:[0,0,0,0] row_mask:0xf bank_mask:0xf
	v_fmac_f32_dpp v75, v244, v37 quad_perm:[1,1,1,1] row_mask:0xf bank_mask:0xf
	v_fmac_f32_dpp v76, v244, v38 quad_perm:[2,2,2,2] row_mask:0xf bank_mask:0xf
	v_fmac_f32_dpp v77, v244, v39 quad_perm:[3,3,3,3] row_mask:0xf bank_mask:0xf
	s_waitcnt lgkmcnt(7)
	v_fmac_f32_dpp v74, v245, v40 quad_perm:[0,0,0,0] row_mask:0xf bank_mask:0xf
	v_fmac_f32_dpp v75, v245, v41 quad_perm:[1,1,1,1] row_mask:0xf bank_mask:0xf
	v_fmac_f32_dpp v76, v245, v42 quad_perm:[2,2,2,2] row_mask:0xf bank_mask:0xf
	v_fmac_f32_dpp v77, v245, v43 quad_perm:[3,3,3,3] row_mask:0xf bank_mask:0xf
	s_waitcnt lgkmcnt(6)
	v_fmac_f32_dpp v74, v246, v44 quad_perm:[0,0,0,0] row_mask:0xf bank_mask:0xf
	v_fmac_f32_dpp v75, v246, v45 quad_perm:[1,1,1,1] row_mask:0xf bank_mask:0xf
	v_fmac_f32_dpp v76, v246, v46 quad_perm:[2,2,2,2] row_mask:0xf bank_mask:0xf
	v_fmac_f32_dpp v77, v246, v47 quad_perm:[3,3,3,3] row_mask:0xf bank_mask:0xf
	s_waitcnt lgkmcnt(5)
	v_fmac_f32_dpp v74, v247, v48 quad_perm:[0,0,0,0] row_mask:0xf bank_mask:0xf
	v_fmac_f32_dpp v75, v247, v49 quad_perm:[1,1,1,1] row_mask:0xf bank_mask:0xf
	v_fmac_f32_dpp v76, v247, v50 quad_perm:[2,2,2,2] row_mask:0xf bank_mask:0xf
	v_fmac_f32_dpp v77, v247, v51 quad_perm:[3,3,3,3] row_mask:0xf bank_mask:0xf
	s_waitcnt lgkmcnt(4)
	v_fmac_f32_dpp v74, v248, v52 quad_perm:[0,0,0,0] row_mask:0xf bank_mask:0xf
	v_fmac_f32_dpp v75, v248, v53 quad_perm:[1,1,1,1] row_mask:0xf bank_mask:0xf
	v_fmac_f32_dpp v76, v248, v54 quad_perm:[2,2,2,2] row_mask:0xf bank_mask:0xf
	v_fmac_f32_dpp v77, v248, v55 quad_perm:[3,3,3,3] row_mask:0xf bank_mask:0xf
	s_waitcnt lgkmcnt(3)
	v_fmac_f32_dpp v74, v249, v56 quad_perm:[0,0,0,0] row_mask:0xf bank_mask:0xf
	ds_read_b32 v240, v255 offset:9728
	ds_read_b32 v241, v255 offset:9744
	ds_read_b32 v242, v255 offset:9760
	ds_read_b32 v243, v255 offset:9776
	ds_read_b32 v244, v255 offset:9792
	ds_read_b32 v245, v255 offset:9808
	ds_read_b32 v246, v255 offset:9824
	ds_read_b32 v247, v255 offset:9840
	ds_read_b32 v248, v255 offset:9856
	ds_read_b32 v249, v255 offset:9872
	v_add_f32_e32 v58, v75, v74
	v_add_f32_e32 v59, v76, v77
	v_add_f32_e32 v58, v59, v58
	v_sub_f32_e32 v57, v57, v58
	s_waitcnt lgkmcnt(10)
	v_lshlrev_b32_e32 v58, 16, v238
	v_mul_f32_e32 v58, v239, v58
	s_cmp_eq_u64 s[16:17], 0
	s_cbranch_scc1 .LBB0_881
	v_mul_f32_e32 v58, v58, v254
.LBB0_881:
	ds_read_u16 v238, v18 offset:10608
	ds_read_b32 v239, v16 offset:156
	ds_read_b32 v254, v15 offset:156
	s_waitcnt lgkmcnt(12)
	v_mul_f32_dpp v59, v240, v2 quad_perm:[0,0,0,0] row_mask:0xf bank_mask:0xf
	v_mul_f32_dpp v76, v240, v3 quad_perm:[1,1,1,1] row_mask:0xf bank_mask:0xf
	v_mul_f32_dpp v77, v240, v4 quad_perm:[2,2,2,2] row_mask:0xf bank_mask:0xf
	v_mul_f32_dpp v78, v240, v5 quad_perm:[3,3,3,3] row_mask:0xf bank_mask:0xf
	s_waitcnt lgkmcnt(11)
	v_fmac_f32_dpp v59, v241, v6 quad_perm:[0,0,0,0] row_mask:0xf bank_mask:0xf
	v_fmac_f32_dpp v76, v241, v7 quad_perm:[1,1,1,1] row_mask:0xf bank_mask:0xf
	v_fmac_f32_dpp v77, v241, v8 quad_perm:[2,2,2,2] row_mask:0xf bank_mask:0xf
	v_fmac_f32_dpp v78, v241, v9 quad_perm:[3,3,3,3] row_mask:0xf bank_mask:0xf
	s_waitcnt lgkmcnt(10)
	v_fmac_f32_dpp v59, v242, v10 quad_perm:[0,0,0,0] row_mask:0xf bank_mask:0xf
	v_fmac_f32_dpp v76, v242, v12 quad_perm:[1,1,1,1] row_mask:0xf bank_mask:0xf
	v_fmac_f32_dpp v77, v242, v13 quad_perm:[2,2,2,2] row_mask:0xf bank_mask:0xf
	v_fmac_f32_dpp v78, v242, v14 quad_perm:[3,3,3,3] row_mask:0xf bank_mask:0xf
	s_waitcnt lgkmcnt(9)
	v_fmac_f32_dpp v59, v243, v17 quad_perm:[0,0,0,0] row_mask:0xf bank_mask:0xf
	v_fmac_f32_dpp v76, v243, v19 quad_perm:[1,1,1,1] row_mask:0xf bank_mask:0xf
	v_fmac_f32_dpp v77, v243, v28 quad_perm:[2,2,2,2] row_mask:0xf bank_mask:0xf
	v_fmac_f32_dpp v78, v243, v35 quad_perm:[3,3,3,3] row_mask:0xf bank_mask:0xf
	s_waitcnt lgkmcnt(8)
	v_fmac_f32_dpp v59, v244, v36 quad_perm:[0,0,0,0] row_mask:0xf bank_mask:0xf
	v_fmac_f32_dpp v76, v244, v37 quad_perm:[1,1,1,1] row_mask:0xf bank_mask:0xf
	v_fmac_f32_dpp v77, v244, v38 quad_perm:[2,2,2,2] row_mask:0xf bank_mask:0xf
	v_fmac_f32_dpp v78, v244, v39 quad_perm:[3,3,3,3] row_mask:0xf bank_mask:0xf
	s_waitcnt lgkmcnt(7)
	v_fmac_f32_dpp v59, v245, v40 quad_perm:[0,0,0,0] row_mask:0xf bank_mask:0xf
	v_fmac_f32_dpp v76, v245, v41 quad_perm:[1,1,1,1] row_mask:0xf bank_mask:0xf
	v_fmac_f32_dpp v77, v245, v42 quad_perm:[2,2,2,2] row_mask:0xf bank_mask:0xf
	v_fmac_f32_dpp v78, v245, v43 quad_perm:[3,3,3,3] row_mask:0xf bank_mask:0xf
	s_waitcnt lgkmcnt(6)
	v_fmac_f32_dpp v59, v246, v44 quad_perm:[0,0,0,0] row_mask:0xf bank_mask:0xf
	v_fmac_f32_dpp v76, v246, v45 quad_perm:[1,1,1,1] row_mask:0xf bank_mask:0xf
	v_fmac_f32_dpp v77, v246, v46 quad_perm:[2,2,2,2] row_mask:0xf bank_mask:0xf
	v_fmac_f32_dpp v78, v246, v47 quad_perm:[3,3,3,3] row_mask:0xf bank_mask:0xf
	s_waitcnt lgkmcnt(5)
	v_fmac_f32_dpp v59, v247, v48 quad_perm:[0,0,0,0] row_mask:0xf bank_mask:0xf
	v_fmac_f32_dpp v76, v247, v49 quad_perm:[1,1,1,1] row_mask:0xf bank_mask:0xf
	v_fmac_f32_dpp v77, v247, v50 quad_perm:[2,2,2,2] row_mask:0xf bank_mask:0xf
	v_fmac_f32_dpp v78, v247, v51 quad_perm:[3,3,3,3] row_mask:0xf bank_mask:0xf
	s_waitcnt lgkmcnt(4)
	v_fmac_f32_dpp v59, v248, v52 quad_perm:[0,0,0,0] row_mask:0xf bank_mask:0xf
	v_fmac_f32_dpp v76, v248, v53 quad_perm:[1,1,1,1] row_mask:0xf bank_mask:0xf
	v_fmac_f32_dpp v77, v248, v54 quad_perm:[2,2,2,2] row_mask:0xf bank_mask:0xf
	v_fmac_f32_dpp v78, v248, v55 quad_perm:[3,3,3,3] row_mask:0xf bank_mask:0xf
	s_waitcnt lgkmcnt(3)
	v_fmac_f32_dpp v59, v249, v56 quad_perm:[0,0,0,0] row_mask:0xf bank_mask:0xf
	v_fmac_f32_dpp v76, v249, v57 quad_perm:[1,1,1,1] row_mask:0xf bank_mask:0xf
	ds_read_b32 v240, v255 offset:9984
	ds_read_b32 v241, v255 offset:10000
	ds_read_b32 v242, v255 offset:10016
	ds_read_b32 v243, v255 offset:10032
	ds_read_b32 v244, v255 offset:10048
	ds_read_b32 v245, v255 offset:10064
	ds_read_b32 v246, v255 offset:10080
	ds_read_b32 v247, v255 offset:10096
	ds_read_b32 v248, v255 offset:10112
	ds_read_b32 v249, v255 offset:10128
	v_add_f32_e32 v59, v59, v76
	v_add_f32_e32 v60, v77, v78
	v_add_f32_e32 v59, v60, v59
	v_sub_f32_e32 v58, v58, v59
	s_waitcnt lgkmcnt(10)
	v_lshlrev_b32_e32 v59, 16, v238
	v_mul_f32_e32 v59, v239, v59
	s_cmp_eq_u64 s[16:17], 0
	s_cbranch_scc1 .LBB0_883
	v_mul_f32_e32 v59, v59, v254
.LBB0_883:
	ds_read_u16 v238, v18 offset:10880
	ds_read_b32 v239, v16 offset:160
	ds_read_b32 v254, v15 offset:160
	s_waitcnt lgkmcnt(12)
	v_mul_f32_dpp v76, v240, v2 quad_perm:[0,0,0,0] row_mask:0xf bank_mask:0xf
	v_mul_f32_dpp v77, v240, v3 quad_perm:[1,1,1,1] row_mask:0xf bank_mask:0xf
	v_mul_f32_dpp v78, v240, v4 quad_perm:[2,2,2,2] row_mask:0xf bank_mask:0xf
	v_mul_f32_dpp v79, v240, v5 quad_perm:[3,3,3,3] row_mask:0xf bank_mask:0xf
	s_waitcnt lgkmcnt(11)
	v_fmac_f32_dpp v76, v241, v6 quad_perm:[0,0,0,0] row_mask:0xf bank_mask:0xf
	v_fmac_f32_dpp v77, v241, v7 quad_perm:[1,1,1,1] row_mask:0xf bank_mask:0xf
	v_fmac_f32_dpp v78, v241, v8 quad_perm:[2,2,2,2] row_mask:0xf bank_mask:0xf
	v_fmac_f32_dpp v79, v241, v9 quad_perm:[3,3,3,3] row_mask:0xf bank_mask:0xf
	s_waitcnt lgkmcnt(10)
	v_fmac_f32_dpp v76, v242, v10 quad_perm:[0,0,0,0] row_mask:0xf bank_mask:0xf
	v_fmac_f32_dpp v77, v242, v12 quad_perm:[1,1,1,1] row_mask:0xf bank_mask:0xf
	v_fmac_f32_dpp v78, v242, v13 quad_perm:[2,2,2,2] row_mask:0xf bank_mask:0xf
	v_fmac_f32_dpp v79, v242, v14 quad_perm:[3,3,3,3] row_mask:0xf bank_mask:0xf
	s_waitcnt lgkmcnt(9)
	v_fmac_f32_dpp v76, v243, v17 quad_perm:[0,0,0,0] row_mask:0xf bank_mask:0xf
	v_fmac_f32_dpp v77, v243, v19 quad_perm:[1,1,1,1] row_mask:0xf bank_mask:0xf
	v_fmac_f32_dpp v78, v243, v28 quad_perm:[2,2,2,2] row_mask:0xf bank_mask:0xf
	v_fmac_f32_dpp v79, v243, v35 quad_perm:[3,3,3,3] row_mask:0xf bank_mask:0xf
	s_waitcnt lgkmcnt(8)
	v_fmac_f32_dpp v76, v244, v36 quad_perm:[0,0,0,0] row_mask:0xf bank_mask:0xf
	v_fmac_f32_dpp v77, v244, v37 quad_perm:[1,1,1,1] row_mask:0xf bank_mask:0xf
	v_fmac_f32_dpp v78, v244, v38 quad_perm:[2,2,2,2] row_mask:0xf bank_mask:0xf
	v_fmac_f32_dpp v79, v244, v39 quad_perm:[3,3,3,3] row_mask:0xf bank_mask:0xf
	s_waitcnt lgkmcnt(7)
	v_fmac_f32_dpp v76, v245, v40 quad_perm:[0,0,0,0] row_mask:0xf bank_mask:0xf
	v_fmac_f32_dpp v77, v245, v41 quad_perm:[1,1,1,1] row_mask:0xf bank_mask:0xf
	v_fmac_f32_dpp v78, v245, v42 quad_perm:[2,2,2,2] row_mask:0xf bank_mask:0xf
	v_fmac_f32_dpp v79, v245, v43 quad_perm:[3,3,3,3] row_mask:0xf bank_mask:0xf
	s_waitcnt lgkmcnt(6)
	v_fmac_f32_dpp v76, v246, v44 quad_perm:[0,0,0,0] row_mask:0xf bank_mask:0xf
	v_fmac_f32_dpp v77, v246, v45 quad_perm:[1,1,1,1] row_mask:0xf bank_mask:0xf
	v_fmac_f32_dpp v78, v246, v46 quad_perm:[2,2,2,2] row_mask:0xf bank_mask:0xf
	v_fmac_f32_dpp v79, v246, v47 quad_perm:[3,3,3,3] row_mask:0xf bank_mask:0xf
	s_waitcnt lgkmcnt(5)
	v_fmac_f32_dpp v76, v247, v48 quad_perm:[0,0,0,0] row_mask:0xf bank_mask:0xf
	v_fmac_f32_dpp v77, v247, v49 quad_perm:[1,1,1,1] row_mask:0xf bank_mask:0xf
	v_fmac_f32_dpp v78, v247, v50 quad_perm:[2,2,2,2] row_mask:0xf bank_mask:0xf
	v_fmac_f32_dpp v79, v247, v51 quad_perm:[3,3,3,3] row_mask:0xf bank_mask:0xf
	s_waitcnt lgkmcnt(4)
	v_fmac_f32_dpp v76, v248, v52 quad_perm:[0,0,0,0] row_mask:0xf bank_mask:0xf
	v_fmac_f32_dpp v77, v248, v53 quad_perm:[1,1,1,1] row_mask:0xf bank_mask:0xf
	v_fmac_f32_dpp v78, v248, v54 quad_perm:[2,2,2,2] row_mask:0xf bank_mask:0xf
	v_fmac_f32_dpp v79, v248, v55 quad_perm:[3,3,3,3] row_mask:0xf bank_mask:0xf
	s_waitcnt lgkmcnt(3)
	v_fmac_f32_dpp v76, v249, v56 quad_perm:[0,0,0,0] row_mask:0xf bank_mask:0xf
	v_fmac_f32_dpp v77, v249, v57 quad_perm:[1,1,1,1] row_mask:0xf bank_mask:0xf
	v_fmac_f32_dpp v78, v249, v58 quad_perm:[2,2,2,2] row_mask:0xf bank_mask:0xf
	ds_read_b32 v240, v255 offset:10240
	ds_read_b32 v241, v255 offset:10256
	ds_read_b32 v242, v255 offset:10272
	ds_read_b32 v243, v255 offset:10288
	ds_read_b32 v244, v255 offset:10304
	ds_read_b32 v245, v255 offset:10320
	ds_read_b32 v246, v255 offset:10336
	ds_read_b32 v247, v255 offset:10352
	ds_read_b32 v248, v255 offset:10368
	ds_read_b32 v249, v255 offset:10384
	v_add_f32_e32 v60, v76, v77
	v_add_f32_e32 v61, v79, v78
	v_add_f32_e32 v60, v60, v61
	v_sub_f32_e32 v59, v59, v60
	s_waitcnt lgkmcnt(10)
	v_lshlrev_b32_e32 v60, 16, v238
	v_mul_f32_e32 v60, v239, v60
	s_cmp_eq_u64 s[16:17], 0
	s_cbranch_scc1 .LBB0_885
	v_mul_f32_e32 v60, v60, v254
.LBB0_885:
	ds_read_u16 v238, v18 offset:11152
	ds_read_b32 v239, v16 offset:164
	ds_read_b32 v254, v15 offset:164
	s_waitcnt lgkmcnt(12)
	v_mul_f32_dpp v61, v240, v2 quad_perm:[0,0,0,0] row_mask:0xf bank_mask:0xf
	v_mul_f32_dpp v78, v240, v3 quad_perm:[1,1,1,1] row_mask:0xf bank_mask:0xf
	v_mul_f32_dpp v79, v240, v4 quad_perm:[2,2,2,2] row_mask:0xf bank_mask:0xf
	v_mul_f32_dpp v80, v240, v5 quad_perm:[3,3,3,3] row_mask:0xf bank_mask:0xf
	s_waitcnt lgkmcnt(11)
	v_fmac_f32_dpp v61, v241, v6 quad_perm:[0,0,0,0] row_mask:0xf bank_mask:0xf
	v_fmac_f32_dpp v78, v241, v7 quad_perm:[1,1,1,1] row_mask:0xf bank_mask:0xf
	v_fmac_f32_dpp v79, v241, v8 quad_perm:[2,2,2,2] row_mask:0xf bank_mask:0xf
	v_fmac_f32_dpp v80, v241, v9 quad_perm:[3,3,3,3] row_mask:0xf bank_mask:0xf
	s_waitcnt lgkmcnt(10)
	v_fmac_f32_dpp v61, v242, v10 quad_perm:[0,0,0,0] row_mask:0xf bank_mask:0xf
	v_fmac_f32_dpp v78, v242, v12 quad_perm:[1,1,1,1] row_mask:0xf bank_mask:0xf
	v_fmac_f32_dpp v79, v242, v13 quad_perm:[2,2,2,2] row_mask:0xf bank_mask:0xf
	v_fmac_f32_dpp v80, v242, v14 quad_perm:[3,3,3,3] row_mask:0xf bank_mask:0xf
	s_waitcnt lgkmcnt(9)
	v_fmac_f32_dpp v61, v243, v17 quad_perm:[0,0,0,0] row_mask:0xf bank_mask:0xf
	v_fmac_f32_dpp v78, v243, v19 quad_perm:[1,1,1,1] row_mask:0xf bank_mask:0xf
	v_fmac_f32_dpp v79, v243, v28 quad_perm:[2,2,2,2] row_mask:0xf bank_mask:0xf
	v_fmac_f32_dpp v80, v243, v35 quad_perm:[3,3,3,3] row_mask:0xf bank_mask:0xf
	s_waitcnt lgkmcnt(8)
	v_fmac_f32_dpp v61, v244, v36 quad_perm:[0,0,0,0] row_mask:0xf bank_mask:0xf
	v_fmac_f32_dpp v78, v244, v37 quad_perm:[1,1,1,1] row_mask:0xf bank_mask:0xf
	v_fmac_f32_dpp v79, v244, v38 quad_perm:[2,2,2,2] row_mask:0xf bank_mask:0xf
	v_fmac_f32_dpp v80, v244, v39 quad_perm:[3,3,3,3] row_mask:0xf bank_mask:0xf
	s_waitcnt lgkmcnt(7)
	v_fmac_f32_dpp v61, v245, v40 quad_perm:[0,0,0,0] row_mask:0xf bank_mask:0xf
	v_fmac_f32_dpp v78, v245, v41 quad_perm:[1,1,1,1] row_mask:0xf bank_mask:0xf
	v_fmac_f32_dpp v79, v245, v42 quad_perm:[2,2,2,2] row_mask:0xf bank_mask:0xf
	v_fmac_f32_dpp v80, v245, v43 quad_perm:[3,3,3,3] row_mask:0xf bank_mask:0xf
	s_waitcnt lgkmcnt(6)
	v_fmac_f32_dpp v61, v246, v44 quad_perm:[0,0,0,0] row_mask:0xf bank_mask:0xf
	v_fmac_f32_dpp v78, v246, v45 quad_perm:[1,1,1,1] row_mask:0xf bank_mask:0xf
	v_fmac_f32_dpp v79, v246, v46 quad_perm:[2,2,2,2] row_mask:0xf bank_mask:0xf
	v_fmac_f32_dpp v80, v246, v47 quad_perm:[3,3,3,3] row_mask:0xf bank_mask:0xf
	s_waitcnt lgkmcnt(5)
	v_fmac_f32_dpp v61, v247, v48 quad_perm:[0,0,0,0] row_mask:0xf bank_mask:0xf
	v_fmac_f32_dpp v78, v247, v49 quad_perm:[1,1,1,1] row_mask:0xf bank_mask:0xf
	v_fmac_f32_dpp v79, v247, v50 quad_perm:[2,2,2,2] row_mask:0xf bank_mask:0xf
	v_fmac_f32_dpp v80, v247, v51 quad_perm:[3,3,3,3] row_mask:0xf bank_mask:0xf
	s_waitcnt lgkmcnt(4)
	v_fmac_f32_dpp v61, v248, v52 quad_perm:[0,0,0,0] row_mask:0xf bank_mask:0xf
	v_fmac_f32_dpp v78, v248, v53 quad_perm:[1,1,1,1] row_mask:0xf bank_mask:0xf
	v_fmac_f32_dpp v79, v248, v54 quad_perm:[2,2,2,2] row_mask:0xf bank_mask:0xf
	v_fmac_f32_dpp v80, v248, v55 quad_perm:[3,3,3,3] row_mask:0xf bank_mask:0xf
	s_waitcnt lgkmcnt(3)
	v_fmac_f32_dpp v61, v249, v56 quad_perm:[0,0,0,0] row_mask:0xf bank_mask:0xf
	v_fmac_f32_dpp v78, v249, v57 quad_perm:[1,1,1,1] row_mask:0xf bank_mask:0xf
	v_fmac_f32_dpp v79, v249, v58 quad_perm:[2,2,2,2] row_mask:0xf bank_mask:0xf
	v_fmac_f32_dpp v80, v249, v59 quad_perm:[3,3,3,3] row_mask:0xf bank_mask:0xf
	ds_read_b32 v240, v255 offset:10496
	ds_read_b32 v241, v255 offset:10512
	ds_read_b32 v242, v255 offset:10528
	ds_read_b32 v243, v255 offset:10544
	ds_read_b32 v244, v255 offset:10560
	ds_read_b32 v245, v255 offset:10576
	ds_read_b32 v246, v255 offset:10592
	ds_read_b32 v247, v255 offset:10608
	ds_read_b32 v248, v255 offset:10624
	ds_read_b32 v249, v255 offset:10640
	ds_read_b32 v250, v255 offset:10656
	v_add_f32_e32 v61, v61, v78
	v_add_f32_e32 v62, v79, v80
	v_add_f32_e32 v61, v61, v62
	v_sub_f32_e32 v60, v60, v61
	s_waitcnt lgkmcnt(11)
	v_lshlrev_b32_e32 v61, 16, v238
	v_mul_f32_e32 v61, v239, v61
	s_cmp_eq_u64 s[16:17], 0
	s_cbranch_scc1 .LBB0_887
	v_mul_f32_e32 v61, v61, v254
.LBB0_887:
	ds_read_u16 v238, v18 offset:11424
	ds_read_b32 v239, v16 offset:168
	ds_read_b32 v254, v15 offset:168
	s_waitcnt lgkmcnt(13)
	v_mul_f32_dpp v78, v240, v2 quad_perm:[0,0,0,0] row_mask:0xf bank_mask:0xf
	v_mul_f32_dpp v79, v240, v3 quad_perm:[1,1,1,1] row_mask:0xf bank_mask:0xf
	v_mul_f32_dpp v80, v240, v4 quad_perm:[2,2,2,2] row_mask:0xf bank_mask:0xf
	v_mul_f32_dpp v81, v240, v5 quad_perm:[3,3,3,3] row_mask:0xf bank_mask:0xf
	s_waitcnt lgkmcnt(12)
	v_fmac_f32_dpp v78, v241, v6 quad_perm:[0,0,0,0] row_mask:0xf bank_mask:0xf
	v_fmac_f32_dpp v79, v241, v7 quad_perm:[1,1,1,1] row_mask:0xf bank_mask:0xf
	v_fmac_f32_dpp v80, v241, v8 quad_perm:[2,2,2,2] row_mask:0xf bank_mask:0xf
	v_fmac_f32_dpp v81, v241, v9 quad_perm:[3,3,3,3] row_mask:0xf bank_mask:0xf
	s_waitcnt lgkmcnt(11)
	v_fmac_f32_dpp v78, v242, v10 quad_perm:[0,0,0,0] row_mask:0xf bank_mask:0xf
	v_fmac_f32_dpp v79, v242, v12 quad_perm:[1,1,1,1] row_mask:0xf bank_mask:0xf
	v_fmac_f32_dpp v80, v242, v13 quad_perm:[2,2,2,2] row_mask:0xf bank_mask:0xf
	v_fmac_f32_dpp v81, v242, v14 quad_perm:[3,3,3,3] row_mask:0xf bank_mask:0xf
	s_waitcnt lgkmcnt(10)
	v_fmac_f32_dpp v78, v243, v17 quad_perm:[0,0,0,0] row_mask:0xf bank_mask:0xf
	v_fmac_f32_dpp v79, v243, v19 quad_perm:[1,1,1,1] row_mask:0xf bank_mask:0xf
	v_fmac_f32_dpp v80, v243, v28 quad_perm:[2,2,2,2] row_mask:0xf bank_mask:0xf
	v_fmac_f32_dpp v81, v243, v35 quad_perm:[3,3,3,3] row_mask:0xf bank_mask:0xf
	s_waitcnt lgkmcnt(9)
	v_fmac_f32_dpp v78, v244, v36 quad_perm:[0,0,0,0] row_mask:0xf bank_mask:0xf
	v_fmac_f32_dpp v79, v244, v37 quad_perm:[1,1,1,1] row_mask:0xf bank_mask:0xf
	v_fmac_f32_dpp v80, v244, v38 quad_perm:[2,2,2,2] row_mask:0xf bank_mask:0xf
	v_fmac_f32_dpp v81, v244, v39 quad_perm:[3,3,3,3] row_mask:0xf bank_mask:0xf
	s_waitcnt lgkmcnt(8)
	v_fmac_f32_dpp v78, v245, v40 quad_perm:[0,0,0,0] row_mask:0xf bank_mask:0xf
	v_fmac_f32_dpp v79, v245, v41 quad_perm:[1,1,1,1] row_mask:0xf bank_mask:0xf
	v_fmac_f32_dpp v80, v245, v42 quad_perm:[2,2,2,2] row_mask:0xf bank_mask:0xf
	v_fmac_f32_dpp v81, v245, v43 quad_perm:[3,3,3,3] row_mask:0xf bank_mask:0xf
	s_waitcnt lgkmcnt(7)
	v_fmac_f32_dpp v78, v246, v44 quad_perm:[0,0,0,0] row_mask:0xf bank_mask:0xf
	v_fmac_f32_dpp v79, v246, v45 quad_perm:[1,1,1,1] row_mask:0xf bank_mask:0xf
	v_fmac_f32_dpp v80, v246, v46 quad_perm:[2,2,2,2] row_mask:0xf bank_mask:0xf
	v_fmac_f32_dpp v81, v246, v47 quad_perm:[3,3,3,3] row_mask:0xf bank_mask:0xf
	s_waitcnt lgkmcnt(6)
	v_fmac_f32_dpp v78, v247, v48 quad_perm:[0,0,0,0] row_mask:0xf bank_mask:0xf
	v_fmac_f32_dpp v79, v247, v49 quad_perm:[1,1,1,1] row_mask:0xf bank_mask:0xf
	v_fmac_f32_dpp v80, v247, v50 quad_perm:[2,2,2,2] row_mask:0xf bank_mask:0xf
	v_fmac_f32_dpp v81, v247, v51 quad_perm:[3,3,3,3] row_mask:0xf bank_mask:0xf
	s_waitcnt lgkmcnt(5)
	v_fmac_f32_dpp v78, v248, v52 quad_perm:[0,0,0,0] row_mask:0xf bank_mask:0xf
	v_fmac_f32_dpp v79, v248, v53 quad_perm:[1,1,1,1] row_mask:0xf bank_mask:0xf
	v_fmac_f32_dpp v80, v248, v54 quad_perm:[2,2,2,2] row_mask:0xf bank_mask:0xf
	v_fmac_f32_dpp v81, v248, v55 quad_perm:[3,3,3,3] row_mask:0xf bank_mask:0xf
	s_waitcnt lgkmcnt(4)
	v_fmac_f32_dpp v78, v249, v56 quad_perm:[0,0,0,0] row_mask:0xf bank_mask:0xf
	v_fmac_f32_dpp v79, v249, v57 quad_perm:[1,1,1,1] row_mask:0xf bank_mask:0xf
	v_fmac_f32_dpp v80, v249, v58 quad_perm:[2,2,2,2] row_mask:0xf bank_mask:0xf
	v_fmac_f32_dpp v81, v249, v59 quad_perm:[3,3,3,3] row_mask:0xf bank_mask:0xf
	s_waitcnt lgkmcnt(3)
	v_fmac_f32_dpp v78, v250, v60 quad_perm:[0,0,0,0] row_mask:0xf bank_mask:0xf
	ds_read_b32 v240, v255 offset:10752
	ds_read_b32 v241, v255 offset:10768
	ds_read_b32 v242, v255 offset:10784
	ds_read_b32 v243, v255 offset:10800
	ds_read_b32 v244, v255 offset:10816
	ds_read_b32 v245, v255 offset:10832
	ds_read_b32 v246, v255 offset:10848
	ds_read_b32 v247, v255 offset:10864
	ds_read_b32 v248, v255 offset:10880
	ds_read_b32 v249, v255 offset:10896
	ds_read_b32 v250, v255 offset:10912
	v_add_f32_e32 v62, v79, v78
	v_add_f32_e32 v63, v80, v81
	v_add_f32_e32 v62, v63, v62
	v_sub_f32_e32 v61, v61, v62
	s_waitcnt lgkmcnt(11)
	v_lshlrev_b32_e32 v62, 16, v238
	v_mul_f32_e32 v62, v239, v62
	s_cmp_eq_u64 s[16:17], 0
	s_cbranch_scc1 .LBB0_889
	v_mul_f32_e32 v62, v62, v254
.LBB0_889:
	ds_read_u16 v238, v18 offset:11696
	ds_read_b32 v239, v16 offset:172
	ds_read_b32 v254, v15 offset:172
	s_waitcnt lgkmcnt(13)
	v_mul_f32_dpp v63, v240, v2 quad_perm:[0,0,0,0] row_mask:0xf bank_mask:0xf
	v_mul_f32_dpp v80, v240, v3 quad_perm:[1,1,1,1] row_mask:0xf bank_mask:0xf
	v_mul_f32_dpp v81, v240, v4 quad_perm:[2,2,2,2] row_mask:0xf bank_mask:0xf
	v_mul_f32_dpp v82, v240, v5 quad_perm:[3,3,3,3] row_mask:0xf bank_mask:0xf
	s_waitcnt lgkmcnt(12)
	v_fmac_f32_dpp v63, v241, v6 quad_perm:[0,0,0,0] row_mask:0xf bank_mask:0xf
	v_fmac_f32_dpp v80, v241, v7 quad_perm:[1,1,1,1] row_mask:0xf bank_mask:0xf
	v_fmac_f32_dpp v81, v241, v8 quad_perm:[2,2,2,2] row_mask:0xf bank_mask:0xf
	v_fmac_f32_dpp v82, v241, v9 quad_perm:[3,3,3,3] row_mask:0xf bank_mask:0xf
	s_waitcnt lgkmcnt(11)
	v_fmac_f32_dpp v63, v242, v10 quad_perm:[0,0,0,0] row_mask:0xf bank_mask:0xf
	v_fmac_f32_dpp v80, v242, v12 quad_perm:[1,1,1,1] row_mask:0xf bank_mask:0xf
	v_fmac_f32_dpp v81, v242, v13 quad_perm:[2,2,2,2] row_mask:0xf bank_mask:0xf
	v_fmac_f32_dpp v82, v242, v14 quad_perm:[3,3,3,3] row_mask:0xf bank_mask:0xf
	s_waitcnt lgkmcnt(10)
	v_fmac_f32_dpp v63, v243, v17 quad_perm:[0,0,0,0] row_mask:0xf bank_mask:0xf
	v_fmac_f32_dpp v80, v243, v19 quad_perm:[1,1,1,1] row_mask:0xf bank_mask:0xf
	v_fmac_f32_dpp v81, v243, v28 quad_perm:[2,2,2,2] row_mask:0xf bank_mask:0xf
	v_fmac_f32_dpp v82, v243, v35 quad_perm:[3,3,3,3] row_mask:0xf bank_mask:0xf
	s_waitcnt lgkmcnt(9)
	v_fmac_f32_dpp v63, v244, v36 quad_perm:[0,0,0,0] row_mask:0xf bank_mask:0xf
	v_fmac_f32_dpp v80, v244, v37 quad_perm:[1,1,1,1] row_mask:0xf bank_mask:0xf
	v_fmac_f32_dpp v81, v244, v38 quad_perm:[2,2,2,2] row_mask:0xf bank_mask:0xf
	v_fmac_f32_dpp v82, v244, v39 quad_perm:[3,3,3,3] row_mask:0xf bank_mask:0xf
	s_waitcnt lgkmcnt(8)
	v_fmac_f32_dpp v63, v245, v40 quad_perm:[0,0,0,0] row_mask:0xf bank_mask:0xf
	v_fmac_f32_dpp v80, v245, v41 quad_perm:[1,1,1,1] row_mask:0xf bank_mask:0xf
	v_fmac_f32_dpp v81, v245, v42 quad_perm:[2,2,2,2] row_mask:0xf bank_mask:0xf
	v_fmac_f32_dpp v82, v245, v43 quad_perm:[3,3,3,3] row_mask:0xf bank_mask:0xf
	s_waitcnt lgkmcnt(7)
	v_fmac_f32_dpp v63, v246, v44 quad_perm:[0,0,0,0] row_mask:0xf bank_mask:0xf
	v_fmac_f32_dpp v80, v246, v45 quad_perm:[1,1,1,1] row_mask:0xf bank_mask:0xf
	v_fmac_f32_dpp v81, v246, v46 quad_perm:[2,2,2,2] row_mask:0xf bank_mask:0xf
	v_fmac_f32_dpp v82, v246, v47 quad_perm:[3,3,3,3] row_mask:0xf bank_mask:0xf
	s_waitcnt lgkmcnt(6)
	v_fmac_f32_dpp v63, v247, v48 quad_perm:[0,0,0,0] row_mask:0xf bank_mask:0xf
	v_fmac_f32_dpp v80, v247, v49 quad_perm:[1,1,1,1] row_mask:0xf bank_mask:0xf
	v_fmac_f32_dpp v81, v247, v50 quad_perm:[2,2,2,2] row_mask:0xf bank_mask:0xf
	v_fmac_f32_dpp v82, v247, v51 quad_perm:[3,3,3,3] row_mask:0xf bank_mask:0xf
	s_waitcnt lgkmcnt(5)
	v_fmac_f32_dpp v63, v248, v52 quad_perm:[0,0,0,0] row_mask:0xf bank_mask:0xf
	v_fmac_f32_dpp v80, v248, v53 quad_perm:[1,1,1,1] row_mask:0xf bank_mask:0xf
	v_fmac_f32_dpp v81, v248, v54 quad_perm:[2,2,2,2] row_mask:0xf bank_mask:0xf
	v_fmac_f32_dpp v82, v248, v55 quad_perm:[3,3,3,3] row_mask:0xf bank_mask:0xf
	s_waitcnt lgkmcnt(4)
	v_fmac_f32_dpp v63, v249, v56 quad_perm:[0,0,0,0] row_mask:0xf bank_mask:0xf
	v_fmac_f32_dpp v80, v249, v57 quad_perm:[1,1,1,1] row_mask:0xf bank_mask:0xf
	v_fmac_f32_dpp v81, v249, v58 quad_perm:[2,2,2,2] row_mask:0xf bank_mask:0xf
	v_fmac_f32_dpp v82, v249, v59 quad_perm:[3,3,3,3] row_mask:0xf bank_mask:0xf
	s_waitcnt lgkmcnt(3)
	v_fmac_f32_dpp v63, v250, v60 quad_perm:[0,0,0,0] row_mask:0xf bank_mask:0xf
	v_fmac_f32_dpp v80, v250, v61 quad_perm:[1,1,1,1] row_mask:0xf bank_mask:0xf
	ds_read_b32 v240, v255 offset:11008
	ds_read_b32 v241, v255 offset:11024
	ds_read_b32 v242, v255 offset:11040
	ds_read_b32 v243, v255 offset:11056
	ds_read_b32 v244, v255 offset:11072
	ds_read_b32 v245, v255 offset:11088
	ds_read_b32 v246, v255 offset:11104
	ds_read_b32 v247, v255 offset:11120
	ds_read_b32 v248, v255 offset:11136
	ds_read_b32 v249, v255 offset:11152
	ds_read_b32 v250, v255 offset:11168
	v_add_f32_e32 v63, v63, v80
	v_add_f32_e32 v64, v81, v82
	v_add_f32_e32 v63, v64, v63
	v_sub_f32_e32 v62, v62, v63
	s_waitcnt lgkmcnt(11)
	v_lshlrev_b32_e32 v63, 16, v238
	v_mul_f32_e32 v63, v239, v63
	s_cmp_eq_u64 s[16:17], 0
	s_cbranch_scc1 .LBB0_891
	v_mul_f32_e32 v63, v63, v254
.LBB0_891:
	ds_read_u16 v238, v18 offset:11968
	ds_read_b32 v239, v16 offset:176
	ds_read_b32 v254, v15 offset:176
	s_waitcnt lgkmcnt(13)
	v_mul_f32_dpp v80, v240, v2 quad_perm:[0,0,0,0] row_mask:0xf bank_mask:0xf
	v_mul_f32_dpp v81, v240, v3 quad_perm:[1,1,1,1] row_mask:0xf bank_mask:0xf
	v_mul_f32_dpp v82, v240, v4 quad_perm:[2,2,2,2] row_mask:0xf bank_mask:0xf
	v_mul_f32_dpp v83, v240, v5 quad_perm:[3,3,3,3] row_mask:0xf bank_mask:0xf
	s_waitcnt lgkmcnt(12)
	v_fmac_f32_dpp v80, v241, v6 quad_perm:[0,0,0,0] row_mask:0xf bank_mask:0xf
	v_fmac_f32_dpp v81, v241, v7 quad_perm:[1,1,1,1] row_mask:0xf bank_mask:0xf
	v_fmac_f32_dpp v82, v241, v8 quad_perm:[2,2,2,2] row_mask:0xf bank_mask:0xf
	v_fmac_f32_dpp v83, v241, v9 quad_perm:[3,3,3,3] row_mask:0xf bank_mask:0xf
	s_waitcnt lgkmcnt(11)
	v_fmac_f32_dpp v80, v242, v10 quad_perm:[0,0,0,0] row_mask:0xf bank_mask:0xf
	v_fmac_f32_dpp v81, v242, v12 quad_perm:[1,1,1,1] row_mask:0xf bank_mask:0xf
	v_fmac_f32_dpp v82, v242, v13 quad_perm:[2,2,2,2] row_mask:0xf bank_mask:0xf
	v_fmac_f32_dpp v83, v242, v14 quad_perm:[3,3,3,3] row_mask:0xf bank_mask:0xf
	s_waitcnt lgkmcnt(10)
	v_fmac_f32_dpp v80, v243, v17 quad_perm:[0,0,0,0] row_mask:0xf bank_mask:0xf
	v_fmac_f32_dpp v81, v243, v19 quad_perm:[1,1,1,1] row_mask:0xf bank_mask:0xf
	v_fmac_f32_dpp v82, v243, v28 quad_perm:[2,2,2,2] row_mask:0xf bank_mask:0xf
	v_fmac_f32_dpp v83, v243, v35 quad_perm:[3,3,3,3] row_mask:0xf bank_mask:0xf
	s_waitcnt lgkmcnt(9)
	v_fmac_f32_dpp v80, v244, v36 quad_perm:[0,0,0,0] row_mask:0xf bank_mask:0xf
	v_fmac_f32_dpp v81, v244, v37 quad_perm:[1,1,1,1] row_mask:0xf bank_mask:0xf
	v_fmac_f32_dpp v82, v244, v38 quad_perm:[2,2,2,2] row_mask:0xf bank_mask:0xf
	v_fmac_f32_dpp v83, v244, v39 quad_perm:[3,3,3,3] row_mask:0xf bank_mask:0xf
	s_waitcnt lgkmcnt(8)
	v_fmac_f32_dpp v80, v245, v40 quad_perm:[0,0,0,0] row_mask:0xf bank_mask:0xf
	v_fmac_f32_dpp v81, v245, v41 quad_perm:[1,1,1,1] row_mask:0xf bank_mask:0xf
	v_fmac_f32_dpp v82, v245, v42 quad_perm:[2,2,2,2] row_mask:0xf bank_mask:0xf
	v_fmac_f32_dpp v83, v245, v43 quad_perm:[3,3,3,3] row_mask:0xf bank_mask:0xf
	s_waitcnt lgkmcnt(7)
	v_fmac_f32_dpp v80, v246, v44 quad_perm:[0,0,0,0] row_mask:0xf bank_mask:0xf
	v_fmac_f32_dpp v81, v246, v45 quad_perm:[1,1,1,1] row_mask:0xf bank_mask:0xf
	v_fmac_f32_dpp v82, v246, v46 quad_perm:[2,2,2,2] row_mask:0xf bank_mask:0xf
	v_fmac_f32_dpp v83, v246, v47 quad_perm:[3,3,3,3] row_mask:0xf bank_mask:0xf
	s_waitcnt lgkmcnt(6)
	v_fmac_f32_dpp v80, v247, v48 quad_perm:[0,0,0,0] row_mask:0xf bank_mask:0xf
	v_fmac_f32_dpp v81, v247, v49 quad_perm:[1,1,1,1] row_mask:0xf bank_mask:0xf
	v_fmac_f32_dpp v82, v247, v50 quad_perm:[2,2,2,2] row_mask:0xf bank_mask:0xf
	v_fmac_f32_dpp v83, v247, v51 quad_perm:[3,3,3,3] row_mask:0xf bank_mask:0xf
	s_waitcnt lgkmcnt(5)
	v_fmac_f32_dpp v80, v248, v52 quad_perm:[0,0,0,0] row_mask:0xf bank_mask:0xf
	v_fmac_f32_dpp v81, v248, v53 quad_perm:[1,1,1,1] row_mask:0xf bank_mask:0xf
	v_fmac_f32_dpp v82, v248, v54 quad_perm:[2,2,2,2] row_mask:0xf bank_mask:0xf
	v_fmac_f32_dpp v83, v248, v55 quad_perm:[3,3,3,3] row_mask:0xf bank_mask:0xf
	s_waitcnt lgkmcnt(4)
	v_fmac_f32_dpp v80, v249, v56 quad_perm:[0,0,0,0] row_mask:0xf bank_mask:0xf
	v_fmac_f32_dpp v81, v249, v57 quad_perm:[1,1,1,1] row_mask:0xf bank_mask:0xf
	v_fmac_f32_dpp v82, v249, v58 quad_perm:[2,2,2,2] row_mask:0xf bank_mask:0xf
	v_fmac_f32_dpp v83, v249, v59 quad_perm:[3,3,3,3] row_mask:0xf bank_mask:0xf
	s_waitcnt lgkmcnt(3)
	v_fmac_f32_dpp v80, v250, v60 quad_perm:[0,0,0,0] row_mask:0xf bank_mask:0xf
	v_fmac_f32_dpp v81, v250, v61 quad_perm:[1,1,1,1] row_mask:0xf bank_mask:0xf
	v_fmac_f32_dpp v82, v250, v62 quad_perm:[2,2,2,2] row_mask:0xf bank_mask:0xf
	ds_read_b32 v240, v255 offset:11264
	ds_read_b32 v241, v255 offset:11280
	ds_read_b32 v242, v255 offset:11296
	ds_read_b32 v243, v255 offset:11312
	ds_read_b32 v244, v255 offset:11328
	ds_read_b32 v245, v255 offset:11344
	ds_read_b32 v246, v255 offset:11360
	ds_read_b32 v247, v255 offset:11376
	ds_read_b32 v248, v255 offset:11392
	ds_read_b32 v249, v255 offset:11408
	ds_read_b32 v250, v255 offset:11424
	v_add_f32_e32 v64, v80, v81
	v_add_f32_e32 v65, v83, v82
	v_add_f32_e32 v64, v64, v65
	v_sub_f32_e32 v63, v63, v64
	s_waitcnt lgkmcnt(11)
	v_lshlrev_b32_e32 v64, 16, v238
	v_mul_f32_e32 v64, v239, v64
	s_cmp_eq_u64 s[16:17], 0
	s_cbranch_scc1 .LBB0_893
	v_mul_f32_e32 v64, v64, v254
.LBB0_893:
	ds_read_u16 v238, v18 offset:12240
	ds_read_b32 v239, v16 offset:180
	ds_read_b32 v254, v15 offset:180
	s_waitcnt lgkmcnt(13)
	v_mul_f32_dpp v65, v240, v2 quad_perm:[0,0,0,0] row_mask:0xf bank_mask:0xf
	v_mul_f32_dpp v82, v240, v3 quad_perm:[1,1,1,1] row_mask:0xf bank_mask:0xf
	v_mul_f32_dpp v83, v240, v4 quad_perm:[2,2,2,2] row_mask:0xf bank_mask:0xf
	v_mul_f32_dpp v84, v240, v5 quad_perm:[3,3,3,3] row_mask:0xf bank_mask:0xf
	s_waitcnt lgkmcnt(12)
	v_fmac_f32_dpp v65, v241, v6 quad_perm:[0,0,0,0] row_mask:0xf bank_mask:0xf
	v_fmac_f32_dpp v82, v241, v7 quad_perm:[1,1,1,1] row_mask:0xf bank_mask:0xf
	v_fmac_f32_dpp v83, v241, v8 quad_perm:[2,2,2,2] row_mask:0xf bank_mask:0xf
	v_fmac_f32_dpp v84, v241, v9 quad_perm:[3,3,3,3] row_mask:0xf bank_mask:0xf
	s_waitcnt lgkmcnt(11)
	v_fmac_f32_dpp v65, v242, v10 quad_perm:[0,0,0,0] row_mask:0xf bank_mask:0xf
	v_fmac_f32_dpp v82, v242, v12 quad_perm:[1,1,1,1] row_mask:0xf bank_mask:0xf
	v_fmac_f32_dpp v83, v242, v13 quad_perm:[2,2,2,2] row_mask:0xf bank_mask:0xf
	v_fmac_f32_dpp v84, v242, v14 quad_perm:[3,3,3,3] row_mask:0xf bank_mask:0xf
	s_waitcnt lgkmcnt(10)
	v_fmac_f32_dpp v65, v243, v17 quad_perm:[0,0,0,0] row_mask:0xf bank_mask:0xf
	v_fmac_f32_dpp v82, v243, v19 quad_perm:[1,1,1,1] row_mask:0xf bank_mask:0xf
	v_fmac_f32_dpp v83, v243, v28 quad_perm:[2,2,2,2] row_mask:0xf bank_mask:0xf
	v_fmac_f32_dpp v84, v243, v35 quad_perm:[3,3,3,3] row_mask:0xf bank_mask:0xf
	s_waitcnt lgkmcnt(9)
	v_fmac_f32_dpp v65, v244, v36 quad_perm:[0,0,0,0] row_mask:0xf bank_mask:0xf
	v_fmac_f32_dpp v82, v244, v37 quad_perm:[1,1,1,1] row_mask:0xf bank_mask:0xf
	v_fmac_f32_dpp v83, v244, v38 quad_perm:[2,2,2,2] row_mask:0xf bank_mask:0xf
	v_fmac_f32_dpp v84, v244, v39 quad_perm:[3,3,3,3] row_mask:0xf bank_mask:0xf
	s_waitcnt lgkmcnt(8)
	v_fmac_f32_dpp v65, v245, v40 quad_perm:[0,0,0,0] row_mask:0xf bank_mask:0xf
	v_fmac_f32_dpp v82, v245, v41 quad_perm:[1,1,1,1] row_mask:0xf bank_mask:0xf
	v_fmac_f32_dpp v83, v245, v42 quad_perm:[2,2,2,2] row_mask:0xf bank_mask:0xf
	v_fmac_f32_dpp v84, v245, v43 quad_perm:[3,3,3,3] row_mask:0xf bank_mask:0xf
	s_waitcnt lgkmcnt(7)
	v_fmac_f32_dpp v65, v246, v44 quad_perm:[0,0,0,0] row_mask:0xf bank_mask:0xf
	v_fmac_f32_dpp v82, v246, v45 quad_perm:[1,1,1,1] row_mask:0xf bank_mask:0xf
	v_fmac_f32_dpp v83, v246, v46 quad_perm:[2,2,2,2] row_mask:0xf bank_mask:0xf
	v_fmac_f32_dpp v84, v246, v47 quad_perm:[3,3,3,3] row_mask:0xf bank_mask:0xf
	s_waitcnt lgkmcnt(6)
	v_fmac_f32_dpp v65, v247, v48 quad_perm:[0,0,0,0] row_mask:0xf bank_mask:0xf
	v_fmac_f32_dpp v82, v247, v49 quad_perm:[1,1,1,1] row_mask:0xf bank_mask:0xf
	v_fmac_f32_dpp v83, v247, v50 quad_perm:[2,2,2,2] row_mask:0xf bank_mask:0xf
	v_fmac_f32_dpp v84, v247, v51 quad_perm:[3,3,3,3] row_mask:0xf bank_mask:0xf
	s_waitcnt lgkmcnt(5)
	v_fmac_f32_dpp v65, v248, v52 quad_perm:[0,0,0,0] row_mask:0xf bank_mask:0xf
	v_fmac_f32_dpp v82, v248, v53 quad_perm:[1,1,1,1] row_mask:0xf bank_mask:0xf
	v_fmac_f32_dpp v83, v248, v54 quad_perm:[2,2,2,2] row_mask:0xf bank_mask:0xf
	v_fmac_f32_dpp v84, v248, v55 quad_perm:[3,3,3,3] row_mask:0xf bank_mask:0xf
	s_waitcnt lgkmcnt(4)
	v_fmac_f32_dpp v65, v249, v56 quad_perm:[0,0,0,0] row_mask:0xf bank_mask:0xf
	v_fmac_f32_dpp v82, v249, v57 quad_perm:[1,1,1,1] row_mask:0xf bank_mask:0xf
	v_fmac_f32_dpp v83, v249, v58 quad_perm:[2,2,2,2] row_mask:0xf bank_mask:0xf
	v_fmac_f32_dpp v84, v249, v59 quad_perm:[3,3,3,3] row_mask:0xf bank_mask:0xf
	s_waitcnt lgkmcnt(3)
	v_fmac_f32_dpp v65, v250, v60 quad_perm:[0,0,0,0] row_mask:0xf bank_mask:0xf
	v_fmac_f32_dpp v82, v250, v61 quad_perm:[1,1,1,1] row_mask:0xf bank_mask:0xf
	v_fmac_f32_dpp v83, v250, v62 quad_perm:[2,2,2,2] row_mask:0xf bank_mask:0xf
	v_fmac_f32_dpp v84, v250, v63 quad_perm:[3,3,3,3] row_mask:0xf bank_mask:0xf
	ds_read_b32 v240, v255 offset:11520
	ds_read_b32 v241, v255 offset:11536
	ds_read_b32 v242, v255 offset:11552
	ds_read_b32 v243, v255 offset:11568
	ds_read_b32 v244, v255 offset:11584
	ds_read_b32 v245, v255 offset:11600
	ds_read_b32 v246, v255 offset:11616
	ds_read_b32 v247, v255 offset:11632
	ds_read_b32 v248, v255 offset:11648
	ds_read_b32 v249, v255 offset:11664
	ds_read_b32 v250, v255 offset:11680
	ds_read_b32 v251, v255 offset:11696
	v_add_f32_e32 v65, v65, v82
	v_add_f32_e32 v66, v83, v84
	v_add_f32_e32 v65, v65, v66
	v_sub_f32_e32 v64, v64, v65
	s_waitcnt lgkmcnt(12)
	v_lshlrev_b32_e32 v65, 16, v238
	v_mul_f32_e32 v65, v239, v65
	s_cmp_eq_u64 s[16:17], 0
	s_cbranch_scc1 .LBB0_895
	v_mul_f32_e32 v65, v65, v254
.LBB0_895:
	ds_read_u16 v238, v18 offset:12512
	ds_read_b32 v239, v16 offset:184
	ds_read_b32 v254, v15 offset:184
	s_waitcnt lgkmcnt(14)
	v_mul_f32_dpp v82, v240, v2 quad_perm:[0,0,0,0] row_mask:0xf bank_mask:0xf
	v_mul_f32_dpp v83, v240, v3 quad_perm:[1,1,1,1] row_mask:0xf bank_mask:0xf
	v_mul_f32_dpp v84, v240, v4 quad_perm:[2,2,2,2] row_mask:0xf bank_mask:0xf
	v_mul_f32_dpp v85, v240, v5 quad_perm:[3,3,3,3] row_mask:0xf bank_mask:0xf
	s_waitcnt lgkmcnt(13)
	v_fmac_f32_dpp v82, v241, v6 quad_perm:[0,0,0,0] row_mask:0xf bank_mask:0xf
	v_fmac_f32_dpp v83, v241, v7 quad_perm:[1,1,1,1] row_mask:0xf bank_mask:0xf
	v_fmac_f32_dpp v84, v241, v8 quad_perm:[2,2,2,2] row_mask:0xf bank_mask:0xf
	v_fmac_f32_dpp v85, v241, v9 quad_perm:[3,3,3,3] row_mask:0xf bank_mask:0xf
	s_waitcnt lgkmcnt(12)
	v_fmac_f32_dpp v82, v242, v10 quad_perm:[0,0,0,0] row_mask:0xf bank_mask:0xf
	v_fmac_f32_dpp v83, v242, v12 quad_perm:[1,1,1,1] row_mask:0xf bank_mask:0xf
	v_fmac_f32_dpp v84, v242, v13 quad_perm:[2,2,2,2] row_mask:0xf bank_mask:0xf
	v_fmac_f32_dpp v85, v242, v14 quad_perm:[3,3,3,3] row_mask:0xf bank_mask:0xf
	s_waitcnt lgkmcnt(11)
	v_fmac_f32_dpp v82, v243, v17 quad_perm:[0,0,0,0] row_mask:0xf bank_mask:0xf
	v_fmac_f32_dpp v83, v243, v19 quad_perm:[1,1,1,1] row_mask:0xf bank_mask:0xf
	v_fmac_f32_dpp v84, v243, v28 quad_perm:[2,2,2,2] row_mask:0xf bank_mask:0xf
	v_fmac_f32_dpp v85, v243, v35 quad_perm:[3,3,3,3] row_mask:0xf bank_mask:0xf
	s_waitcnt lgkmcnt(10)
	v_fmac_f32_dpp v82, v244, v36 quad_perm:[0,0,0,0] row_mask:0xf bank_mask:0xf
	v_fmac_f32_dpp v83, v244, v37 quad_perm:[1,1,1,1] row_mask:0xf bank_mask:0xf
	v_fmac_f32_dpp v84, v244, v38 quad_perm:[2,2,2,2] row_mask:0xf bank_mask:0xf
	v_fmac_f32_dpp v85, v244, v39 quad_perm:[3,3,3,3] row_mask:0xf bank_mask:0xf
	s_waitcnt lgkmcnt(9)
	v_fmac_f32_dpp v82, v245, v40 quad_perm:[0,0,0,0] row_mask:0xf bank_mask:0xf
	v_fmac_f32_dpp v83, v245, v41 quad_perm:[1,1,1,1] row_mask:0xf bank_mask:0xf
	v_fmac_f32_dpp v84, v245, v42 quad_perm:[2,2,2,2] row_mask:0xf bank_mask:0xf
	v_fmac_f32_dpp v85, v245, v43 quad_perm:[3,3,3,3] row_mask:0xf bank_mask:0xf
	s_waitcnt lgkmcnt(8)
	v_fmac_f32_dpp v82, v246, v44 quad_perm:[0,0,0,0] row_mask:0xf bank_mask:0xf
	v_fmac_f32_dpp v83, v246, v45 quad_perm:[1,1,1,1] row_mask:0xf bank_mask:0xf
	v_fmac_f32_dpp v84, v246, v46 quad_perm:[2,2,2,2] row_mask:0xf bank_mask:0xf
	v_fmac_f32_dpp v85, v246, v47 quad_perm:[3,3,3,3] row_mask:0xf bank_mask:0xf
	s_waitcnt lgkmcnt(7)
	v_fmac_f32_dpp v82, v247, v48 quad_perm:[0,0,0,0] row_mask:0xf bank_mask:0xf
	v_fmac_f32_dpp v83, v247, v49 quad_perm:[1,1,1,1] row_mask:0xf bank_mask:0xf
	v_fmac_f32_dpp v84, v247, v50 quad_perm:[2,2,2,2] row_mask:0xf bank_mask:0xf
	v_fmac_f32_dpp v85, v247, v51 quad_perm:[3,3,3,3] row_mask:0xf bank_mask:0xf
	s_waitcnt lgkmcnt(6)
	v_fmac_f32_dpp v82, v248, v52 quad_perm:[0,0,0,0] row_mask:0xf bank_mask:0xf
	v_fmac_f32_dpp v83, v248, v53 quad_perm:[1,1,1,1] row_mask:0xf bank_mask:0xf
	v_fmac_f32_dpp v84, v248, v54 quad_perm:[2,2,2,2] row_mask:0xf bank_mask:0xf
	v_fmac_f32_dpp v85, v248, v55 quad_perm:[3,3,3,3] row_mask:0xf bank_mask:0xf
	s_waitcnt lgkmcnt(5)
	v_fmac_f32_dpp v82, v249, v56 quad_perm:[0,0,0,0] row_mask:0xf bank_mask:0xf
	v_fmac_f32_dpp v83, v249, v57 quad_perm:[1,1,1,1] row_mask:0xf bank_mask:0xf
	v_fmac_f32_dpp v84, v249, v58 quad_perm:[2,2,2,2] row_mask:0xf bank_mask:0xf
	v_fmac_f32_dpp v85, v249, v59 quad_perm:[3,3,3,3] row_mask:0xf bank_mask:0xf
	s_waitcnt lgkmcnt(4)
	v_fmac_f32_dpp v82, v250, v60 quad_perm:[0,0,0,0] row_mask:0xf bank_mask:0xf
	v_fmac_f32_dpp v83, v250, v61 quad_perm:[1,1,1,1] row_mask:0xf bank_mask:0xf
	v_fmac_f32_dpp v84, v250, v62 quad_perm:[2,2,2,2] row_mask:0xf bank_mask:0xf
	v_fmac_f32_dpp v85, v250, v63 quad_perm:[3,3,3,3] row_mask:0xf bank_mask:0xf
	s_waitcnt lgkmcnt(3)
	v_fmac_f32_dpp v82, v251, v64 quad_perm:[0,0,0,0] row_mask:0xf bank_mask:0xf
	ds_read_b32 v240, v255 offset:11776
	ds_read_b32 v241, v255 offset:11792
	ds_read_b32 v242, v255 offset:11808
	ds_read_b32 v243, v255 offset:11824
	ds_read_b32 v244, v255 offset:11840
	ds_read_b32 v245, v255 offset:11856
	ds_read_b32 v246, v255 offset:11872
	ds_read_b32 v247, v255 offset:11888
	ds_read_b32 v248, v255 offset:11904
	ds_read_b32 v249, v255 offset:11920
	ds_read_b32 v250, v255 offset:11936
	ds_read_b32 v251, v255 offset:11952
	v_add_f32_e32 v66, v83, v82
	v_add_f32_e32 v67, v84, v85
	v_add_f32_e32 v66, v67, v66
	v_sub_f32_e32 v65, v65, v66
	s_waitcnt lgkmcnt(12)
	v_lshlrev_b32_e32 v66, 16, v238
	v_mul_f32_e32 v66, v239, v66
	s_cmp_eq_u64 s[16:17], 0
	s_cbranch_scc1 .LBB0_897
	v_mul_f32_e32 v66, v66, v254
.LBB0_897:
	ds_read_u16 v238, v18 offset:12784
	ds_read_b32 v239, v16 offset:188
	ds_read_b32 v254, v15 offset:188
	s_waitcnt lgkmcnt(14)
	v_mul_f32_dpp v67, v240, v2 quad_perm:[0,0,0,0] row_mask:0xf bank_mask:0xf
	v_mul_f32_dpp v84, v240, v3 quad_perm:[1,1,1,1] row_mask:0xf bank_mask:0xf
	v_mul_f32_dpp v85, v240, v4 quad_perm:[2,2,2,2] row_mask:0xf bank_mask:0xf
	v_mul_f32_dpp v86, v240, v5 quad_perm:[3,3,3,3] row_mask:0xf bank_mask:0xf
	s_waitcnt lgkmcnt(13)
	v_fmac_f32_dpp v67, v241, v6 quad_perm:[0,0,0,0] row_mask:0xf bank_mask:0xf
	v_fmac_f32_dpp v84, v241, v7 quad_perm:[1,1,1,1] row_mask:0xf bank_mask:0xf
	v_fmac_f32_dpp v85, v241, v8 quad_perm:[2,2,2,2] row_mask:0xf bank_mask:0xf
	v_fmac_f32_dpp v86, v241, v9 quad_perm:[3,3,3,3] row_mask:0xf bank_mask:0xf
	s_waitcnt lgkmcnt(12)
	v_fmac_f32_dpp v67, v242, v10 quad_perm:[0,0,0,0] row_mask:0xf bank_mask:0xf
	v_fmac_f32_dpp v84, v242, v12 quad_perm:[1,1,1,1] row_mask:0xf bank_mask:0xf
	v_fmac_f32_dpp v85, v242, v13 quad_perm:[2,2,2,2] row_mask:0xf bank_mask:0xf
	v_fmac_f32_dpp v86, v242, v14 quad_perm:[3,3,3,3] row_mask:0xf bank_mask:0xf
	s_waitcnt lgkmcnt(11)
	v_fmac_f32_dpp v67, v243, v17 quad_perm:[0,0,0,0] row_mask:0xf bank_mask:0xf
	v_fmac_f32_dpp v84, v243, v19 quad_perm:[1,1,1,1] row_mask:0xf bank_mask:0xf
	v_fmac_f32_dpp v85, v243, v28 quad_perm:[2,2,2,2] row_mask:0xf bank_mask:0xf
	v_fmac_f32_dpp v86, v243, v35 quad_perm:[3,3,3,3] row_mask:0xf bank_mask:0xf
	s_waitcnt lgkmcnt(10)
	v_fmac_f32_dpp v67, v244, v36 quad_perm:[0,0,0,0] row_mask:0xf bank_mask:0xf
	v_fmac_f32_dpp v84, v244, v37 quad_perm:[1,1,1,1] row_mask:0xf bank_mask:0xf
	v_fmac_f32_dpp v85, v244, v38 quad_perm:[2,2,2,2] row_mask:0xf bank_mask:0xf
	v_fmac_f32_dpp v86, v244, v39 quad_perm:[3,3,3,3] row_mask:0xf bank_mask:0xf
	s_waitcnt lgkmcnt(9)
	v_fmac_f32_dpp v67, v245, v40 quad_perm:[0,0,0,0] row_mask:0xf bank_mask:0xf
	v_fmac_f32_dpp v84, v245, v41 quad_perm:[1,1,1,1] row_mask:0xf bank_mask:0xf
	v_fmac_f32_dpp v85, v245, v42 quad_perm:[2,2,2,2] row_mask:0xf bank_mask:0xf
	v_fmac_f32_dpp v86, v245, v43 quad_perm:[3,3,3,3] row_mask:0xf bank_mask:0xf
	s_waitcnt lgkmcnt(8)
	v_fmac_f32_dpp v67, v246, v44 quad_perm:[0,0,0,0] row_mask:0xf bank_mask:0xf
	v_fmac_f32_dpp v84, v246, v45 quad_perm:[1,1,1,1] row_mask:0xf bank_mask:0xf
	v_fmac_f32_dpp v85, v246, v46 quad_perm:[2,2,2,2] row_mask:0xf bank_mask:0xf
	v_fmac_f32_dpp v86, v246, v47 quad_perm:[3,3,3,3] row_mask:0xf bank_mask:0xf
	s_waitcnt lgkmcnt(7)
	v_fmac_f32_dpp v67, v247, v48 quad_perm:[0,0,0,0] row_mask:0xf bank_mask:0xf
	v_fmac_f32_dpp v84, v247, v49 quad_perm:[1,1,1,1] row_mask:0xf bank_mask:0xf
	v_fmac_f32_dpp v85, v247, v50 quad_perm:[2,2,2,2] row_mask:0xf bank_mask:0xf
	v_fmac_f32_dpp v86, v247, v51 quad_perm:[3,3,3,3] row_mask:0xf bank_mask:0xf
	s_waitcnt lgkmcnt(6)
	v_fmac_f32_dpp v67, v248, v52 quad_perm:[0,0,0,0] row_mask:0xf bank_mask:0xf
	v_fmac_f32_dpp v84, v248, v53 quad_perm:[1,1,1,1] row_mask:0xf bank_mask:0xf
	v_fmac_f32_dpp v85, v248, v54 quad_perm:[2,2,2,2] row_mask:0xf bank_mask:0xf
	v_fmac_f32_dpp v86, v248, v55 quad_perm:[3,3,3,3] row_mask:0xf bank_mask:0xf
	s_waitcnt lgkmcnt(5)
	v_fmac_f32_dpp v67, v249, v56 quad_perm:[0,0,0,0] row_mask:0xf bank_mask:0xf
	v_fmac_f32_dpp v84, v249, v57 quad_perm:[1,1,1,1] row_mask:0xf bank_mask:0xf
	v_fmac_f32_dpp v85, v249, v58 quad_perm:[2,2,2,2] row_mask:0xf bank_mask:0xf
	v_fmac_f32_dpp v86, v249, v59 quad_perm:[3,3,3,3] row_mask:0xf bank_mask:0xf
	s_waitcnt lgkmcnt(4)
	v_fmac_f32_dpp v67, v250, v60 quad_perm:[0,0,0,0] row_mask:0xf bank_mask:0xf
	v_fmac_f32_dpp v84, v250, v61 quad_perm:[1,1,1,1] row_mask:0xf bank_mask:0xf
	v_fmac_f32_dpp v85, v250, v62 quad_perm:[2,2,2,2] row_mask:0xf bank_mask:0xf
	v_fmac_f32_dpp v86, v250, v63 quad_perm:[3,3,3,3] row_mask:0xf bank_mask:0xf
	s_waitcnt lgkmcnt(3)
	v_fmac_f32_dpp v67, v251, v64 quad_perm:[0,0,0,0] row_mask:0xf bank_mask:0xf
	v_fmac_f32_dpp v84, v251, v65 quad_perm:[1,1,1,1] row_mask:0xf bank_mask:0xf
	ds_read_b32 v240, v255 offset:12032
	ds_read_b32 v241, v255 offset:12048
	ds_read_b32 v242, v255 offset:12064
	ds_read_b32 v243, v255 offset:12080
	ds_read_b32 v244, v255 offset:12096
	ds_read_b32 v245, v255 offset:12112
	ds_read_b32 v246, v255 offset:12128
	ds_read_b32 v247, v255 offset:12144
	ds_read_b32 v248, v255 offset:12160
	ds_read_b32 v249, v255 offset:12176
	ds_read_b32 v250, v255 offset:12192
	ds_read_b32 v251, v255 offset:12208
	v_add_f32_e32 v67, v67, v84
	v_add_f32_e32 v68, v85, v86
	v_add_f32_e32 v67, v68, v67
	v_sub_f32_e32 v66, v66, v67
	s_waitcnt lgkmcnt(12)
	v_lshlrev_b32_e32 v67, 16, v238
	v_mul_f32_e32 v67, v239, v67
	s_cmp_eq_u64 s[16:17], 0
	s_cbranch_scc1 .LBB0_899
	v_mul_f32_e32 v67, v67, v254
.LBB0_899:
	ds_read_u16 v238, v18 offset:13056
	ds_read_b32 v239, v16 offset:192
	ds_read_b32 v254, v15 offset:192
	s_waitcnt lgkmcnt(14)
	v_mul_f32_dpp v84, v240, v2 quad_perm:[0,0,0,0] row_mask:0xf bank_mask:0xf
	v_mul_f32_dpp v85, v240, v3 quad_perm:[1,1,1,1] row_mask:0xf bank_mask:0xf
	v_mul_f32_dpp v86, v240, v4 quad_perm:[2,2,2,2] row_mask:0xf bank_mask:0xf
	v_mul_f32_dpp v87, v240, v5 quad_perm:[3,3,3,3] row_mask:0xf bank_mask:0xf
	s_waitcnt lgkmcnt(13)
	v_fmac_f32_dpp v84, v241, v6 quad_perm:[0,0,0,0] row_mask:0xf bank_mask:0xf
	v_fmac_f32_dpp v85, v241, v7 quad_perm:[1,1,1,1] row_mask:0xf bank_mask:0xf
	v_fmac_f32_dpp v86, v241, v8 quad_perm:[2,2,2,2] row_mask:0xf bank_mask:0xf
	v_fmac_f32_dpp v87, v241, v9 quad_perm:[3,3,3,3] row_mask:0xf bank_mask:0xf
	s_waitcnt lgkmcnt(12)
	v_fmac_f32_dpp v84, v242, v10 quad_perm:[0,0,0,0] row_mask:0xf bank_mask:0xf
	v_fmac_f32_dpp v85, v242, v12 quad_perm:[1,1,1,1] row_mask:0xf bank_mask:0xf
	v_fmac_f32_dpp v86, v242, v13 quad_perm:[2,2,2,2] row_mask:0xf bank_mask:0xf
	v_fmac_f32_dpp v87, v242, v14 quad_perm:[3,3,3,3] row_mask:0xf bank_mask:0xf
	s_waitcnt lgkmcnt(11)
	v_fmac_f32_dpp v84, v243, v17 quad_perm:[0,0,0,0] row_mask:0xf bank_mask:0xf
	v_fmac_f32_dpp v85, v243, v19 quad_perm:[1,1,1,1] row_mask:0xf bank_mask:0xf
	v_fmac_f32_dpp v86, v243, v28 quad_perm:[2,2,2,2] row_mask:0xf bank_mask:0xf
	v_fmac_f32_dpp v87, v243, v35 quad_perm:[3,3,3,3] row_mask:0xf bank_mask:0xf
	s_waitcnt lgkmcnt(10)
	v_fmac_f32_dpp v84, v244, v36 quad_perm:[0,0,0,0] row_mask:0xf bank_mask:0xf
	v_fmac_f32_dpp v85, v244, v37 quad_perm:[1,1,1,1] row_mask:0xf bank_mask:0xf
	v_fmac_f32_dpp v86, v244, v38 quad_perm:[2,2,2,2] row_mask:0xf bank_mask:0xf
	v_fmac_f32_dpp v87, v244, v39 quad_perm:[3,3,3,3] row_mask:0xf bank_mask:0xf
	s_waitcnt lgkmcnt(9)
	v_fmac_f32_dpp v84, v245, v40 quad_perm:[0,0,0,0] row_mask:0xf bank_mask:0xf
	v_fmac_f32_dpp v85, v245, v41 quad_perm:[1,1,1,1] row_mask:0xf bank_mask:0xf
	v_fmac_f32_dpp v86, v245, v42 quad_perm:[2,2,2,2] row_mask:0xf bank_mask:0xf
	v_fmac_f32_dpp v87, v245, v43 quad_perm:[3,3,3,3] row_mask:0xf bank_mask:0xf
	s_waitcnt lgkmcnt(8)
	v_fmac_f32_dpp v84, v246, v44 quad_perm:[0,0,0,0] row_mask:0xf bank_mask:0xf
	v_fmac_f32_dpp v85, v246, v45 quad_perm:[1,1,1,1] row_mask:0xf bank_mask:0xf
	v_fmac_f32_dpp v86, v246, v46 quad_perm:[2,2,2,2] row_mask:0xf bank_mask:0xf
	v_fmac_f32_dpp v87, v246, v47 quad_perm:[3,3,3,3] row_mask:0xf bank_mask:0xf
	s_waitcnt lgkmcnt(7)
	v_fmac_f32_dpp v84, v247, v48 quad_perm:[0,0,0,0] row_mask:0xf bank_mask:0xf
	v_fmac_f32_dpp v85, v247, v49 quad_perm:[1,1,1,1] row_mask:0xf bank_mask:0xf
	v_fmac_f32_dpp v86, v247, v50 quad_perm:[2,2,2,2] row_mask:0xf bank_mask:0xf
	v_fmac_f32_dpp v87, v247, v51 quad_perm:[3,3,3,3] row_mask:0xf bank_mask:0xf
	s_waitcnt lgkmcnt(6)
	v_fmac_f32_dpp v84, v248, v52 quad_perm:[0,0,0,0] row_mask:0xf bank_mask:0xf
	v_fmac_f32_dpp v85, v248, v53 quad_perm:[1,1,1,1] row_mask:0xf bank_mask:0xf
	v_fmac_f32_dpp v86, v248, v54 quad_perm:[2,2,2,2] row_mask:0xf bank_mask:0xf
	v_fmac_f32_dpp v87, v248, v55 quad_perm:[3,3,3,3] row_mask:0xf bank_mask:0xf
	s_waitcnt lgkmcnt(5)
	v_fmac_f32_dpp v84, v249, v56 quad_perm:[0,0,0,0] row_mask:0xf bank_mask:0xf
	v_fmac_f32_dpp v85, v249, v57 quad_perm:[1,1,1,1] row_mask:0xf bank_mask:0xf
	v_fmac_f32_dpp v86, v249, v58 quad_perm:[2,2,2,2] row_mask:0xf bank_mask:0xf
	v_fmac_f32_dpp v87, v249, v59 quad_perm:[3,3,3,3] row_mask:0xf bank_mask:0xf
	s_waitcnt lgkmcnt(4)
	v_fmac_f32_dpp v84, v250, v60 quad_perm:[0,0,0,0] row_mask:0xf bank_mask:0xf
	v_fmac_f32_dpp v85, v250, v61 quad_perm:[1,1,1,1] row_mask:0xf bank_mask:0xf
	v_fmac_f32_dpp v86, v250, v62 quad_perm:[2,2,2,2] row_mask:0xf bank_mask:0xf
	v_fmac_f32_dpp v87, v250, v63 quad_perm:[3,3,3,3] row_mask:0xf bank_mask:0xf
	s_waitcnt lgkmcnt(3)
	v_fmac_f32_dpp v84, v251, v64 quad_perm:[0,0,0,0] row_mask:0xf bank_mask:0xf
	v_fmac_f32_dpp v85, v251, v65 quad_perm:[1,1,1,1] row_mask:0xf bank_mask:0xf
	v_fmac_f32_dpp v86, v251, v66 quad_perm:[2,2,2,2] row_mask:0xf bank_mask:0xf
	ds_read_b32 v240, v255 offset:12288
	ds_read_b32 v241, v255 offset:12304
	ds_read_b32 v242, v255 offset:12320
	ds_read_b32 v243, v255 offset:12336
	ds_read_b32 v244, v255 offset:12352
	ds_read_b32 v245, v255 offset:12368
	ds_read_b32 v246, v255 offset:12384
	ds_read_b32 v247, v255 offset:12400
	ds_read_b32 v248, v255 offset:12416
	ds_read_b32 v249, v255 offset:12432
	ds_read_b32 v250, v255 offset:12448
	ds_read_b32 v251, v255 offset:12464
	v_add_f32_e32 v68, v84, v85
	v_add_f32_e32 v69, v87, v86
	v_add_f32_e32 v68, v68, v69
	v_sub_f32_e32 v67, v67, v68
	s_waitcnt lgkmcnt(12)
	v_lshlrev_b32_e32 v68, 16, v238
	v_mul_f32_e32 v68, v239, v68
	s_cmp_eq_u64 s[16:17], 0
	s_cbranch_scc1 .LBB0_901
	v_mul_f32_e32 v68, v68, v254
.LBB0_901:
	ds_read_u16 v238, v18 offset:13328
	ds_read_b32 v239, v16 offset:196
	ds_read_b32 v254, v15 offset:196
	s_waitcnt lgkmcnt(14)
	v_mul_f32_dpp v69, v240, v2 quad_perm:[0,0,0,0] row_mask:0xf bank_mask:0xf
	v_mul_f32_dpp v86, v240, v3 quad_perm:[1,1,1,1] row_mask:0xf bank_mask:0xf
	v_mul_f32_dpp v87, v240, v4 quad_perm:[2,2,2,2] row_mask:0xf bank_mask:0xf
	v_mul_f32_dpp v88, v240, v5 quad_perm:[3,3,3,3] row_mask:0xf bank_mask:0xf
	s_waitcnt lgkmcnt(13)
	v_fmac_f32_dpp v69, v241, v6 quad_perm:[0,0,0,0] row_mask:0xf bank_mask:0xf
	v_fmac_f32_dpp v86, v241, v7 quad_perm:[1,1,1,1] row_mask:0xf bank_mask:0xf
	v_fmac_f32_dpp v87, v241, v8 quad_perm:[2,2,2,2] row_mask:0xf bank_mask:0xf
	v_fmac_f32_dpp v88, v241, v9 quad_perm:[3,3,3,3] row_mask:0xf bank_mask:0xf
	s_waitcnt lgkmcnt(12)
	v_fmac_f32_dpp v69, v242, v10 quad_perm:[0,0,0,0] row_mask:0xf bank_mask:0xf
	v_fmac_f32_dpp v86, v242, v12 quad_perm:[1,1,1,1] row_mask:0xf bank_mask:0xf
	v_fmac_f32_dpp v87, v242, v13 quad_perm:[2,2,2,2] row_mask:0xf bank_mask:0xf
	v_fmac_f32_dpp v88, v242, v14 quad_perm:[3,3,3,3] row_mask:0xf bank_mask:0xf
	s_waitcnt lgkmcnt(11)
	v_fmac_f32_dpp v69, v243, v17 quad_perm:[0,0,0,0] row_mask:0xf bank_mask:0xf
	v_fmac_f32_dpp v86, v243, v19 quad_perm:[1,1,1,1] row_mask:0xf bank_mask:0xf
	v_fmac_f32_dpp v87, v243, v28 quad_perm:[2,2,2,2] row_mask:0xf bank_mask:0xf
	v_fmac_f32_dpp v88, v243, v35 quad_perm:[3,3,3,3] row_mask:0xf bank_mask:0xf
	s_waitcnt lgkmcnt(10)
	v_fmac_f32_dpp v69, v244, v36 quad_perm:[0,0,0,0] row_mask:0xf bank_mask:0xf
	v_fmac_f32_dpp v86, v244, v37 quad_perm:[1,1,1,1] row_mask:0xf bank_mask:0xf
	v_fmac_f32_dpp v87, v244, v38 quad_perm:[2,2,2,2] row_mask:0xf bank_mask:0xf
	v_fmac_f32_dpp v88, v244, v39 quad_perm:[3,3,3,3] row_mask:0xf bank_mask:0xf
	s_waitcnt lgkmcnt(9)
	v_fmac_f32_dpp v69, v245, v40 quad_perm:[0,0,0,0] row_mask:0xf bank_mask:0xf
	v_fmac_f32_dpp v86, v245, v41 quad_perm:[1,1,1,1] row_mask:0xf bank_mask:0xf
	v_fmac_f32_dpp v87, v245, v42 quad_perm:[2,2,2,2] row_mask:0xf bank_mask:0xf
	v_fmac_f32_dpp v88, v245, v43 quad_perm:[3,3,3,3] row_mask:0xf bank_mask:0xf
	s_waitcnt lgkmcnt(8)
	v_fmac_f32_dpp v69, v246, v44 quad_perm:[0,0,0,0] row_mask:0xf bank_mask:0xf
	v_fmac_f32_dpp v86, v246, v45 quad_perm:[1,1,1,1] row_mask:0xf bank_mask:0xf
	v_fmac_f32_dpp v87, v246, v46 quad_perm:[2,2,2,2] row_mask:0xf bank_mask:0xf
	v_fmac_f32_dpp v88, v246, v47 quad_perm:[3,3,3,3] row_mask:0xf bank_mask:0xf
	s_waitcnt lgkmcnt(7)
	v_fmac_f32_dpp v69, v247, v48 quad_perm:[0,0,0,0] row_mask:0xf bank_mask:0xf
	v_fmac_f32_dpp v86, v247, v49 quad_perm:[1,1,1,1] row_mask:0xf bank_mask:0xf
	v_fmac_f32_dpp v87, v247, v50 quad_perm:[2,2,2,2] row_mask:0xf bank_mask:0xf
	v_fmac_f32_dpp v88, v247, v51 quad_perm:[3,3,3,3] row_mask:0xf bank_mask:0xf
	s_waitcnt lgkmcnt(6)
	v_fmac_f32_dpp v69, v248, v52 quad_perm:[0,0,0,0] row_mask:0xf bank_mask:0xf
	v_fmac_f32_dpp v86, v248, v53 quad_perm:[1,1,1,1] row_mask:0xf bank_mask:0xf
	v_fmac_f32_dpp v87, v248, v54 quad_perm:[2,2,2,2] row_mask:0xf bank_mask:0xf
	v_fmac_f32_dpp v88, v248, v55 quad_perm:[3,3,3,3] row_mask:0xf bank_mask:0xf
	s_waitcnt lgkmcnt(5)
	v_fmac_f32_dpp v69, v249, v56 quad_perm:[0,0,0,0] row_mask:0xf bank_mask:0xf
	v_fmac_f32_dpp v86, v249, v57 quad_perm:[1,1,1,1] row_mask:0xf bank_mask:0xf
	v_fmac_f32_dpp v87, v249, v58 quad_perm:[2,2,2,2] row_mask:0xf bank_mask:0xf
	v_fmac_f32_dpp v88, v249, v59 quad_perm:[3,3,3,3] row_mask:0xf bank_mask:0xf
	s_waitcnt lgkmcnt(4)
	v_fmac_f32_dpp v69, v250, v60 quad_perm:[0,0,0,0] row_mask:0xf bank_mask:0xf
	v_fmac_f32_dpp v86, v250, v61 quad_perm:[1,1,1,1] row_mask:0xf bank_mask:0xf
	v_fmac_f32_dpp v87, v250, v62 quad_perm:[2,2,2,2] row_mask:0xf bank_mask:0xf
	v_fmac_f32_dpp v88, v250, v63 quad_perm:[3,3,3,3] row_mask:0xf bank_mask:0xf
	s_waitcnt lgkmcnt(3)
	v_fmac_f32_dpp v69, v251, v64 quad_perm:[0,0,0,0] row_mask:0xf bank_mask:0xf
	v_fmac_f32_dpp v86, v251, v65 quad_perm:[1,1,1,1] row_mask:0xf bank_mask:0xf
	v_fmac_f32_dpp v87, v251, v66 quad_perm:[2,2,2,2] row_mask:0xf bank_mask:0xf
	v_fmac_f32_dpp v88, v251, v67 quad_perm:[3,3,3,3] row_mask:0xf bank_mask:0xf
	ds_read_b32 v240, v255 offset:12544
	ds_read_b32 v241, v255 offset:12560
	ds_read_b32 v242, v255 offset:12576
	ds_read_b32 v243, v255 offset:12592
	ds_read_b32 v244, v255 offset:12608
	ds_read_b32 v245, v255 offset:12624
	ds_read_b32 v246, v255 offset:12640
	ds_read_b32 v247, v255 offset:12656
	ds_read_b32 v248, v255 offset:12672
	ds_read_b32 v249, v255 offset:12688
	ds_read_b32 v250, v255 offset:12704
	ds_read_b32 v251, v255 offset:12720
	v_add_f32_e32 v69, v69, v86
	v_add_f32_e32 v70, v87, v88
	v_add_f32_e32 v69, v69, v70
	v_sub_f32_e32 v68, v68, v69
	s_waitcnt lgkmcnt(12)
	v_lshlrev_b32_e32 v69, 16, v238
	v_mul_f32_e32 v69, v239, v69
	s_cmp_eq_u64 s[16:17], 0
	s_cbranch_scc1 .LBB0_903
	v_mul_f32_e32 v69, v69, v254
.LBB0_903:
	ds_read_u16 v238, v18 offset:13600
	ds_read_b32 v239, v16 offset:200
	ds_read_b32 v254, v15 offset:200
	s_waitcnt lgkmcnt(14)
	v_mul_f32_dpp v86, v240, v2 quad_perm:[0,0,0,0] row_mask:0xf bank_mask:0xf
	v_mul_f32_dpp v87, v240, v3 quad_perm:[1,1,1,1] row_mask:0xf bank_mask:0xf
	v_mul_f32_dpp v88, v240, v4 quad_perm:[2,2,2,2] row_mask:0xf bank_mask:0xf
	v_mul_f32_dpp v89, v240, v5 quad_perm:[3,3,3,3] row_mask:0xf bank_mask:0xf
	ds_read_b32 v240, v255 offset:12736
	s_waitcnt lgkmcnt(14)
	v_fmac_f32_dpp v86, v241, v6 quad_perm:[0,0,0,0] row_mask:0xf bank_mask:0xf
	v_fmac_f32_dpp v87, v241, v7 quad_perm:[1,1,1,1] row_mask:0xf bank_mask:0xf
	v_fmac_f32_dpp v88, v241, v8 quad_perm:[2,2,2,2] row_mask:0xf bank_mask:0xf
	v_fmac_f32_dpp v89, v241, v9 quad_perm:[3,3,3,3] row_mask:0xf bank_mask:0xf
	s_waitcnt lgkmcnt(13)
	v_fmac_f32_dpp v86, v242, v10 quad_perm:[0,0,0,0] row_mask:0xf bank_mask:0xf
	v_fmac_f32_dpp v87, v242, v12 quad_perm:[1,1,1,1] row_mask:0xf bank_mask:0xf
	v_fmac_f32_dpp v88, v242, v13 quad_perm:[2,2,2,2] row_mask:0xf bank_mask:0xf
	v_fmac_f32_dpp v89, v242, v14 quad_perm:[3,3,3,3] row_mask:0xf bank_mask:0xf
	s_waitcnt lgkmcnt(12)
	v_fmac_f32_dpp v86, v243, v17 quad_perm:[0,0,0,0] row_mask:0xf bank_mask:0xf
	v_fmac_f32_dpp v87, v243, v19 quad_perm:[1,1,1,1] row_mask:0xf bank_mask:0xf
	v_fmac_f32_dpp v88, v243, v28 quad_perm:[2,2,2,2] row_mask:0xf bank_mask:0xf
	v_fmac_f32_dpp v89, v243, v35 quad_perm:[3,3,3,3] row_mask:0xf bank_mask:0xf
	s_waitcnt lgkmcnt(11)
	v_fmac_f32_dpp v86, v244, v36 quad_perm:[0,0,0,0] row_mask:0xf bank_mask:0xf
	v_fmac_f32_dpp v87, v244, v37 quad_perm:[1,1,1,1] row_mask:0xf bank_mask:0xf
	v_fmac_f32_dpp v88, v244, v38 quad_perm:[2,2,2,2] row_mask:0xf bank_mask:0xf
	v_fmac_f32_dpp v89, v244, v39 quad_perm:[3,3,3,3] row_mask:0xf bank_mask:0xf
	s_waitcnt lgkmcnt(10)
	v_fmac_f32_dpp v86, v245, v40 quad_perm:[0,0,0,0] row_mask:0xf bank_mask:0xf
	v_fmac_f32_dpp v87, v245, v41 quad_perm:[1,1,1,1] row_mask:0xf bank_mask:0xf
	v_fmac_f32_dpp v88, v245, v42 quad_perm:[2,2,2,2] row_mask:0xf bank_mask:0xf
	v_fmac_f32_dpp v89, v245, v43 quad_perm:[3,3,3,3] row_mask:0xf bank_mask:0xf
	s_waitcnt lgkmcnt(9)
	v_fmac_f32_dpp v86, v246, v44 quad_perm:[0,0,0,0] row_mask:0xf bank_mask:0xf
	v_fmac_f32_dpp v87, v246, v45 quad_perm:[1,1,1,1] row_mask:0xf bank_mask:0xf
	v_fmac_f32_dpp v88, v246, v46 quad_perm:[2,2,2,2] row_mask:0xf bank_mask:0xf
	v_fmac_f32_dpp v89, v246, v47 quad_perm:[3,3,3,3] row_mask:0xf bank_mask:0xf
	s_waitcnt lgkmcnt(8)
	v_fmac_f32_dpp v86, v247, v48 quad_perm:[0,0,0,0] row_mask:0xf bank_mask:0xf
	v_fmac_f32_dpp v87, v247, v49 quad_perm:[1,1,1,1] row_mask:0xf bank_mask:0xf
	v_fmac_f32_dpp v88, v247, v50 quad_perm:[2,2,2,2] row_mask:0xf bank_mask:0xf
	v_fmac_f32_dpp v89, v247, v51 quad_perm:[3,3,3,3] row_mask:0xf bank_mask:0xf
	s_waitcnt lgkmcnt(7)
	v_fmac_f32_dpp v86, v248, v52 quad_perm:[0,0,0,0] row_mask:0xf bank_mask:0xf
	v_fmac_f32_dpp v87, v248, v53 quad_perm:[1,1,1,1] row_mask:0xf bank_mask:0xf
	v_fmac_f32_dpp v88, v248, v54 quad_perm:[2,2,2,2] row_mask:0xf bank_mask:0xf
	v_fmac_f32_dpp v89, v248, v55 quad_perm:[3,3,3,3] row_mask:0xf bank_mask:0xf
	s_waitcnt lgkmcnt(6)
	v_fmac_f32_dpp v86, v249, v56 quad_perm:[0,0,0,0] row_mask:0xf bank_mask:0xf
	v_fmac_f32_dpp v87, v249, v57 quad_perm:[1,1,1,1] row_mask:0xf bank_mask:0xf
	v_fmac_f32_dpp v88, v249, v58 quad_perm:[2,2,2,2] row_mask:0xf bank_mask:0xf
	v_fmac_f32_dpp v89, v249, v59 quad_perm:[3,3,3,3] row_mask:0xf bank_mask:0xf
	s_waitcnt lgkmcnt(5)
	v_fmac_f32_dpp v86, v250, v60 quad_perm:[0,0,0,0] row_mask:0xf bank_mask:0xf
	v_fmac_f32_dpp v87, v250, v61 quad_perm:[1,1,1,1] row_mask:0xf bank_mask:0xf
	v_fmac_f32_dpp v88, v250, v62 quad_perm:[2,2,2,2] row_mask:0xf bank_mask:0xf
	v_fmac_f32_dpp v89, v250, v63 quad_perm:[3,3,3,3] row_mask:0xf bank_mask:0xf
	s_waitcnt lgkmcnt(4)
	v_fmac_f32_dpp v86, v251, v64 quad_perm:[0,0,0,0] row_mask:0xf bank_mask:0xf
	v_fmac_f32_dpp v87, v251, v65 quad_perm:[1,1,1,1] row_mask:0xf bank_mask:0xf
	v_fmac_f32_dpp v88, v251, v66 quad_perm:[2,2,2,2] row_mask:0xf bank_mask:0xf
	v_fmac_f32_dpp v89, v251, v67 quad_perm:[3,3,3,3] row_mask:0xf bank_mask:0xf
	s_waitcnt lgkmcnt(0)
	v_fmac_f32_dpp v86, v240, v68 quad_perm:[0,0,0,0] row_mask:0xf bank_mask:0xf
	ds_read_b32 v240, v255 offset:12800
	ds_read_b32 v241, v255 offset:12816
	ds_read_b32 v242, v255 offset:12832
	ds_read_b32 v243, v255 offset:12848
	ds_read_b32 v244, v255 offset:12864
	ds_read_b32 v245, v255 offset:12880
	ds_read_b32 v246, v255 offset:12896
	ds_read_b32 v247, v255 offset:12912
	ds_read_b32 v248, v255 offset:12928
	ds_read_b32 v249, v255 offset:12944
	ds_read_b32 v250, v255 offset:12960
	ds_read_b32 v251, v255 offset:12976
	v_add_f32_e32 v70, v87, v86
	v_add_f32_e32 v71, v88, v89
	v_add_f32_e32 v70, v71, v70
	v_sub_f32_e32 v69, v69, v70
	v_lshlrev_b32_e32 v70, 16, v238
	v_mul_f32_e32 v70, v239, v70
	s_cmp_eq_u64 s[16:17], 0
	s_cbranch_scc1 .LBB0_905
	v_mul_f32_e32 v70, v70, v254
.LBB0_905:
	ds_read_u16 v238, v18 offset:13872
	ds_read_b32 v239, v16 offset:204
	ds_read_b32 v254, v15 offset:204
	s_waitcnt lgkmcnt(14)
	v_mul_f32_dpp v71, v240, v2 quad_perm:[0,0,0,0] row_mask:0xf bank_mask:0xf
	v_mul_f32_dpp v88, v240, v3 quad_perm:[1,1,1,1] row_mask:0xf bank_mask:0xf
	v_mul_f32_dpp v89, v240, v4 quad_perm:[2,2,2,2] row_mask:0xf bank_mask:0xf
	v_mul_f32_dpp v90, v240, v5 quad_perm:[3,3,3,3] row_mask:0xf bank_mask:0xf
	ds_read_b32 v240, v255 offset:12992
	s_waitcnt lgkmcnt(14)
	v_fmac_f32_dpp v71, v241, v6 quad_perm:[0,0,0,0] row_mask:0xf bank_mask:0xf
	v_fmac_f32_dpp v88, v241, v7 quad_perm:[1,1,1,1] row_mask:0xf bank_mask:0xf
	v_fmac_f32_dpp v89, v241, v8 quad_perm:[2,2,2,2] row_mask:0xf bank_mask:0xf
	v_fmac_f32_dpp v90, v241, v9 quad_perm:[3,3,3,3] row_mask:0xf bank_mask:0xf
	s_waitcnt lgkmcnt(13)
	v_fmac_f32_dpp v71, v242, v10 quad_perm:[0,0,0,0] row_mask:0xf bank_mask:0xf
	v_fmac_f32_dpp v88, v242, v12 quad_perm:[1,1,1,1] row_mask:0xf bank_mask:0xf
	v_fmac_f32_dpp v89, v242, v13 quad_perm:[2,2,2,2] row_mask:0xf bank_mask:0xf
	v_fmac_f32_dpp v90, v242, v14 quad_perm:[3,3,3,3] row_mask:0xf bank_mask:0xf
	s_waitcnt lgkmcnt(12)
	v_fmac_f32_dpp v71, v243, v17 quad_perm:[0,0,0,0] row_mask:0xf bank_mask:0xf
	v_fmac_f32_dpp v88, v243, v19 quad_perm:[1,1,1,1] row_mask:0xf bank_mask:0xf
	v_fmac_f32_dpp v89, v243, v28 quad_perm:[2,2,2,2] row_mask:0xf bank_mask:0xf
	v_fmac_f32_dpp v90, v243, v35 quad_perm:[3,3,3,3] row_mask:0xf bank_mask:0xf
	s_waitcnt lgkmcnt(11)
	v_fmac_f32_dpp v71, v244, v36 quad_perm:[0,0,0,0] row_mask:0xf bank_mask:0xf
	v_fmac_f32_dpp v88, v244, v37 quad_perm:[1,1,1,1] row_mask:0xf bank_mask:0xf
	v_fmac_f32_dpp v89, v244, v38 quad_perm:[2,2,2,2] row_mask:0xf bank_mask:0xf
	v_fmac_f32_dpp v90, v244, v39 quad_perm:[3,3,3,3] row_mask:0xf bank_mask:0xf
	s_waitcnt lgkmcnt(10)
	v_fmac_f32_dpp v71, v245, v40 quad_perm:[0,0,0,0] row_mask:0xf bank_mask:0xf
	v_fmac_f32_dpp v88, v245, v41 quad_perm:[1,1,1,1] row_mask:0xf bank_mask:0xf
	v_fmac_f32_dpp v89, v245, v42 quad_perm:[2,2,2,2] row_mask:0xf bank_mask:0xf
	v_fmac_f32_dpp v90, v245, v43 quad_perm:[3,3,3,3] row_mask:0xf bank_mask:0xf
	s_waitcnt lgkmcnt(9)
	v_fmac_f32_dpp v71, v246, v44 quad_perm:[0,0,0,0] row_mask:0xf bank_mask:0xf
	v_fmac_f32_dpp v88, v246, v45 quad_perm:[1,1,1,1] row_mask:0xf bank_mask:0xf
	v_fmac_f32_dpp v89, v246, v46 quad_perm:[2,2,2,2] row_mask:0xf bank_mask:0xf
	v_fmac_f32_dpp v90, v246, v47 quad_perm:[3,3,3,3] row_mask:0xf bank_mask:0xf
	s_waitcnt lgkmcnt(8)
	v_fmac_f32_dpp v71, v247, v48 quad_perm:[0,0,0,0] row_mask:0xf bank_mask:0xf
	v_fmac_f32_dpp v88, v247, v49 quad_perm:[1,1,1,1] row_mask:0xf bank_mask:0xf
	v_fmac_f32_dpp v89, v247, v50 quad_perm:[2,2,2,2] row_mask:0xf bank_mask:0xf
	v_fmac_f32_dpp v90, v247, v51 quad_perm:[3,3,3,3] row_mask:0xf bank_mask:0xf
	s_waitcnt lgkmcnt(7)
	v_fmac_f32_dpp v71, v248, v52 quad_perm:[0,0,0,0] row_mask:0xf bank_mask:0xf
	v_fmac_f32_dpp v88, v248, v53 quad_perm:[1,1,1,1] row_mask:0xf bank_mask:0xf
	v_fmac_f32_dpp v89, v248, v54 quad_perm:[2,2,2,2] row_mask:0xf bank_mask:0xf
	v_fmac_f32_dpp v90, v248, v55 quad_perm:[3,3,3,3] row_mask:0xf bank_mask:0xf
	s_waitcnt lgkmcnt(6)
	v_fmac_f32_dpp v71, v249, v56 quad_perm:[0,0,0,0] row_mask:0xf bank_mask:0xf
	v_fmac_f32_dpp v88, v249, v57 quad_perm:[1,1,1,1] row_mask:0xf bank_mask:0xf
	v_fmac_f32_dpp v89, v249, v58 quad_perm:[2,2,2,2] row_mask:0xf bank_mask:0xf
	v_fmac_f32_dpp v90, v249, v59 quad_perm:[3,3,3,3] row_mask:0xf bank_mask:0xf
	s_waitcnt lgkmcnt(5)
	v_fmac_f32_dpp v71, v250, v60 quad_perm:[0,0,0,0] row_mask:0xf bank_mask:0xf
	v_fmac_f32_dpp v88, v250, v61 quad_perm:[1,1,1,1] row_mask:0xf bank_mask:0xf
	v_fmac_f32_dpp v89, v250, v62 quad_perm:[2,2,2,2] row_mask:0xf bank_mask:0xf
	v_fmac_f32_dpp v90, v250, v63 quad_perm:[3,3,3,3] row_mask:0xf bank_mask:0xf
	s_waitcnt lgkmcnt(4)
	v_fmac_f32_dpp v71, v251, v64 quad_perm:[0,0,0,0] row_mask:0xf bank_mask:0xf
	v_fmac_f32_dpp v88, v251, v65 quad_perm:[1,1,1,1] row_mask:0xf bank_mask:0xf
	v_fmac_f32_dpp v89, v251, v66 quad_perm:[2,2,2,2] row_mask:0xf bank_mask:0xf
	v_fmac_f32_dpp v90, v251, v67 quad_perm:[3,3,3,3] row_mask:0xf bank_mask:0xf
	s_waitcnt lgkmcnt(0)
	v_fmac_f32_dpp v71, v240, v68 quad_perm:[0,0,0,0] row_mask:0xf bank_mask:0xf
	v_fmac_f32_dpp v88, v240, v69 quad_perm:[1,1,1,1] row_mask:0xf bank_mask:0xf
	ds_read_b32 v240, v255 offset:13056
	ds_read_b32 v241, v255 offset:13072
	ds_read_b32 v242, v255 offset:13088
	ds_read_b32 v243, v255 offset:13104
	ds_read_b32 v244, v255 offset:13120
	ds_read_b32 v245, v255 offset:13136
	ds_read_b32 v246, v255 offset:13152
	ds_read_b32 v247, v255 offset:13168
	ds_read_b32 v248, v255 offset:13184
	ds_read_b32 v249, v255 offset:13200
	ds_read_b32 v250, v255 offset:13216
	ds_read_b32 v251, v255 offset:13232
	v_add_f32_e32 v71, v71, v88
	v_add_f32_e32 v72, v89, v90
	v_add_f32_e32 v71, v72, v71
	v_sub_f32_e32 v70, v70, v71
	v_lshlrev_b32_e32 v71, 16, v238
	v_mul_f32_e32 v71, v239, v71
	s_cmp_eq_u64 s[16:17], 0
	s_cbranch_scc1 .LBB0_907
	v_mul_f32_e32 v71, v71, v254
.LBB0_907:
	ds_read_u16 v238, v18 offset:14144
	ds_read_b32 v239, v16 offset:208
	ds_read_b32 v254, v15 offset:208
	s_waitcnt lgkmcnt(14)
	v_mul_f32_dpp v88, v240, v2 quad_perm:[0,0,0,0] row_mask:0xf bank_mask:0xf
	v_mul_f32_dpp v89, v240, v3 quad_perm:[1,1,1,1] row_mask:0xf bank_mask:0xf
	v_mul_f32_dpp v90, v240, v4 quad_perm:[2,2,2,2] row_mask:0xf bank_mask:0xf
	v_mul_f32_dpp v91, v240, v5 quad_perm:[3,3,3,3] row_mask:0xf bank_mask:0xf
	ds_read_b32 v240, v255 offset:13248
	s_waitcnt lgkmcnt(14)
	v_fmac_f32_dpp v88, v241, v6 quad_perm:[0,0,0,0] row_mask:0xf bank_mask:0xf
	v_fmac_f32_dpp v89, v241, v7 quad_perm:[1,1,1,1] row_mask:0xf bank_mask:0xf
	v_fmac_f32_dpp v90, v241, v8 quad_perm:[2,2,2,2] row_mask:0xf bank_mask:0xf
	v_fmac_f32_dpp v91, v241, v9 quad_perm:[3,3,3,3] row_mask:0xf bank_mask:0xf
	s_waitcnt lgkmcnt(13)
	v_fmac_f32_dpp v88, v242, v10 quad_perm:[0,0,0,0] row_mask:0xf bank_mask:0xf
	v_fmac_f32_dpp v89, v242, v12 quad_perm:[1,1,1,1] row_mask:0xf bank_mask:0xf
	v_fmac_f32_dpp v90, v242, v13 quad_perm:[2,2,2,2] row_mask:0xf bank_mask:0xf
	v_fmac_f32_dpp v91, v242, v14 quad_perm:[3,3,3,3] row_mask:0xf bank_mask:0xf
	s_waitcnt lgkmcnt(12)
	v_fmac_f32_dpp v88, v243, v17 quad_perm:[0,0,0,0] row_mask:0xf bank_mask:0xf
	v_fmac_f32_dpp v89, v243, v19 quad_perm:[1,1,1,1] row_mask:0xf bank_mask:0xf
	v_fmac_f32_dpp v90, v243, v28 quad_perm:[2,2,2,2] row_mask:0xf bank_mask:0xf
	v_fmac_f32_dpp v91, v243, v35 quad_perm:[3,3,3,3] row_mask:0xf bank_mask:0xf
	s_waitcnt lgkmcnt(11)
	v_fmac_f32_dpp v88, v244, v36 quad_perm:[0,0,0,0] row_mask:0xf bank_mask:0xf
	v_fmac_f32_dpp v89, v244, v37 quad_perm:[1,1,1,1] row_mask:0xf bank_mask:0xf
	v_fmac_f32_dpp v90, v244, v38 quad_perm:[2,2,2,2] row_mask:0xf bank_mask:0xf
	v_fmac_f32_dpp v91, v244, v39 quad_perm:[3,3,3,3] row_mask:0xf bank_mask:0xf
	s_waitcnt lgkmcnt(10)
	v_fmac_f32_dpp v88, v245, v40 quad_perm:[0,0,0,0] row_mask:0xf bank_mask:0xf
	v_fmac_f32_dpp v89, v245, v41 quad_perm:[1,1,1,1] row_mask:0xf bank_mask:0xf
	v_fmac_f32_dpp v90, v245, v42 quad_perm:[2,2,2,2] row_mask:0xf bank_mask:0xf
	v_fmac_f32_dpp v91, v245, v43 quad_perm:[3,3,3,3] row_mask:0xf bank_mask:0xf
	s_waitcnt lgkmcnt(9)
	v_fmac_f32_dpp v88, v246, v44 quad_perm:[0,0,0,0] row_mask:0xf bank_mask:0xf
	v_fmac_f32_dpp v89, v246, v45 quad_perm:[1,1,1,1] row_mask:0xf bank_mask:0xf
	v_fmac_f32_dpp v90, v246, v46 quad_perm:[2,2,2,2] row_mask:0xf bank_mask:0xf
	v_fmac_f32_dpp v91, v246, v47 quad_perm:[3,3,3,3] row_mask:0xf bank_mask:0xf
	s_waitcnt lgkmcnt(8)
	v_fmac_f32_dpp v88, v247, v48 quad_perm:[0,0,0,0] row_mask:0xf bank_mask:0xf
	v_fmac_f32_dpp v89, v247, v49 quad_perm:[1,1,1,1] row_mask:0xf bank_mask:0xf
	v_fmac_f32_dpp v90, v247, v50 quad_perm:[2,2,2,2] row_mask:0xf bank_mask:0xf
	v_fmac_f32_dpp v91, v247, v51 quad_perm:[3,3,3,3] row_mask:0xf bank_mask:0xf
	s_waitcnt lgkmcnt(7)
	v_fmac_f32_dpp v88, v248, v52 quad_perm:[0,0,0,0] row_mask:0xf bank_mask:0xf
	v_fmac_f32_dpp v89, v248, v53 quad_perm:[1,1,1,1] row_mask:0xf bank_mask:0xf
	v_fmac_f32_dpp v90, v248, v54 quad_perm:[2,2,2,2] row_mask:0xf bank_mask:0xf
	v_fmac_f32_dpp v91, v248, v55 quad_perm:[3,3,3,3] row_mask:0xf bank_mask:0xf
	s_waitcnt lgkmcnt(6)
	v_fmac_f32_dpp v88, v249, v56 quad_perm:[0,0,0,0] row_mask:0xf bank_mask:0xf
	v_fmac_f32_dpp v89, v249, v57 quad_perm:[1,1,1,1] row_mask:0xf bank_mask:0xf
	v_fmac_f32_dpp v90, v249, v58 quad_perm:[2,2,2,2] row_mask:0xf bank_mask:0xf
	v_fmac_f32_dpp v91, v249, v59 quad_perm:[3,3,3,3] row_mask:0xf bank_mask:0xf
	s_waitcnt lgkmcnt(5)
	v_fmac_f32_dpp v88, v250, v60 quad_perm:[0,0,0,0] row_mask:0xf bank_mask:0xf
	v_fmac_f32_dpp v89, v250, v61 quad_perm:[1,1,1,1] row_mask:0xf bank_mask:0xf
	v_fmac_f32_dpp v90, v250, v62 quad_perm:[2,2,2,2] row_mask:0xf bank_mask:0xf
	v_fmac_f32_dpp v91, v250, v63 quad_perm:[3,3,3,3] row_mask:0xf bank_mask:0xf
	s_waitcnt lgkmcnt(4)
	v_fmac_f32_dpp v88, v251, v64 quad_perm:[0,0,0,0] row_mask:0xf bank_mask:0xf
	v_fmac_f32_dpp v89, v251, v65 quad_perm:[1,1,1,1] row_mask:0xf bank_mask:0xf
	v_fmac_f32_dpp v90, v251, v66 quad_perm:[2,2,2,2] row_mask:0xf bank_mask:0xf
	v_fmac_f32_dpp v91, v251, v67 quad_perm:[3,3,3,3] row_mask:0xf bank_mask:0xf
	s_waitcnt lgkmcnt(0)
	v_fmac_f32_dpp v88, v240, v68 quad_perm:[0,0,0,0] row_mask:0xf bank_mask:0xf
	v_fmac_f32_dpp v89, v240, v69 quad_perm:[1,1,1,1] row_mask:0xf bank_mask:0xf
	v_fmac_f32_dpp v90, v240, v70 quad_perm:[2,2,2,2] row_mask:0xf bank_mask:0xf
	ds_read_b32 v240, v255 offset:13312
	ds_read_b32 v241, v255 offset:13328
	ds_read_b32 v242, v255 offset:13344
	ds_read_b32 v243, v255 offset:13360
	ds_read_b32 v244, v255 offset:13376
	ds_read_b32 v245, v255 offset:13392
	ds_read_b32 v246, v255 offset:13408
	ds_read_b32 v247, v255 offset:13424
	ds_read_b32 v248, v255 offset:13440
	ds_read_b32 v249, v255 offset:13456
	ds_read_b32 v250, v255 offset:13472
	ds_read_b32 v251, v255 offset:13488
	v_add_f32_e32 v72, v88, v89
	v_add_f32_e32 v73, v91, v90
	v_add_f32_e32 v72, v72, v73
	v_sub_f32_e32 v71, v71, v72
	v_lshlrev_b32_e32 v72, 16, v238
	v_mul_f32_e32 v72, v239, v72
	s_cmp_eq_u64 s[16:17], 0
	s_cbranch_scc1 .LBB0_909
	v_mul_f32_e32 v72, v72, v254
.LBB0_909:
	ds_read_u16 v238, v18 offset:14416
	ds_read_b32 v239, v16 offset:212
	ds_read_b32 v254, v15 offset:212
	s_waitcnt lgkmcnt(14)
	v_mul_f32_dpp v73, v240, v2 quad_perm:[0,0,0,0] row_mask:0xf bank_mask:0xf
	v_mul_f32_dpp v90, v240, v3 quad_perm:[1,1,1,1] row_mask:0xf bank_mask:0xf
	v_mul_f32_dpp v91, v240, v4 quad_perm:[2,2,2,2] row_mask:0xf bank_mask:0xf
	v_mul_f32_dpp v92, v240, v5 quad_perm:[3,3,3,3] row_mask:0xf bank_mask:0xf
	ds_read_b32 v240, v255 offset:13504
	s_waitcnt lgkmcnt(14)
	v_fmac_f32_dpp v73, v241, v6 quad_perm:[0,0,0,0] row_mask:0xf bank_mask:0xf
	v_fmac_f32_dpp v90, v241, v7 quad_perm:[1,1,1,1] row_mask:0xf bank_mask:0xf
	v_fmac_f32_dpp v91, v241, v8 quad_perm:[2,2,2,2] row_mask:0xf bank_mask:0xf
	v_fmac_f32_dpp v92, v241, v9 quad_perm:[3,3,3,3] row_mask:0xf bank_mask:0xf
	s_waitcnt lgkmcnt(13)
	v_fmac_f32_dpp v73, v242, v10 quad_perm:[0,0,0,0] row_mask:0xf bank_mask:0xf
	v_fmac_f32_dpp v90, v242, v12 quad_perm:[1,1,1,1] row_mask:0xf bank_mask:0xf
	v_fmac_f32_dpp v91, v242, v13 quad_perm:[2,2,2,2] row_mask:0xf bank_mask:0xf
	v_fmac_f32_dpp v92, v242, v14 quad_perm:[3,3,3,3] row_mask:0xf bank_mask:0xf
	s_waitcnt lgkmcnt(12)
	v_fmac_f32_dpp v73, v243, v17 quad_perm:[0,0,0,0] row_mask:0xf bank_mask:0xf
	v_fmac_f32_dpp v90, v243, v19 quad_perm:[1,1,1,1] row_mask:0xf bank_mask:0xf
	v_fmac_f32_dpp v91, v243, v28 quad_perm:[2,2,2,2] row_mask:0xf bank_mask:0xf
	v_fmac_f32_dpp v92, v243, v35 quad_perm:[3,3,3,3] row_mask:0xf bank_mask:0xf
	s_waitcnt lgkmcnt(11)
	v_fmac_f32_dpp v73, v244, v36 quad_perm:[0,0,0,0] row_mask:0xf bank_mask:0xf
	v_fmac_f32_dpp v90, v244, v37 quad_perm:[1,1,1,1] row_mask:0xf bank_mask:0xf
	v_fmac_f32_dpp v91, v244, v38 quad_perm:[2,2,2,2] row_mask:0xf bank_mask:0xf
	v_fmac_f32_dpp v92, v244, v39 quad_perm:[3,3,3,3] row_mask:0xf bank_mask:0xf
	s_waitcnt lgkmcnt(10)
	v_fmac_f32_dpp v73, v245, v40 quad_perm:[0,0,0,0] row_mask:0xf bank_mask:0xf
	v_fmac_f32_dpp v90, v245, v41 quad_perm:[1,1,1,1] row_mask:0xf bank_mask:0xf
	v_fmac_f32_dpp v91, v245, v42 quad_perm:[2,2,2,2] row_mask:0xf bank_mask:0xf
	v_fmac_f32_dpp v92, v245, v43 quad_perm:[3,3,3,3] row_mask:0xf bank_mask:0xf
	s_waitcnt lgkmcnt(9)
	v_fmac_f32_dpp v73, v246, v44 quad_perm:[0,0,0,0] row_mask:0xf bank_mask:0xf
	v_fmac_f32_dpp v90, v246, v45 quad_perm:[1,1,1,1] row_mask:0xf bank_mask:0xf
	v_fmac_f32_dpp v91, v246, v46 quad_perm:[2,2,2,2] row_mask:0xf bank_mask:0xf
	v_fmac_f32_dpp v92, v246, v47 quad_perm:[3,3,3,3] row_mask:0xf bank_mask:0xf
	s_waitcnt lgkmcnt(8)
	v_fmac_f32_dpp v73, v247, v48 quad_perm:[0,0,0,0] row_mask:0xf bank_mask:0xf
	v_fmac_f32_dpp v90, v247, v49 quad_perm:[1,1,1,1] row_mask:0xf bank_mask:0xf
	v_fmac_f32_dpp v91, v247, v50 quad_perm:[2,2,2,2] row_mask:0xf bank_mask:0xf
	v_fmac_f32_dpp v92, v247, v51 quad_perm:[3,3,3,3] row_mask:0xf bank_mask:0xf
	s_waitcnt lgkmcnt(7)
	v_fmac_f32_dpp v73, v248, v52 quad_perm:[0,0,0,0] row_mask:0xf bank_mask:0xf
	v_fmac_f32_dpp v90, v248, v53 quad_perm:[1,1,1,1] row_mask:0xf bank_mask:0xf
	v_fmac_f32_dpp v91, v248, v54 quad_perm:[2,2,2,2] row_mask:0xf bank_mask:0xf
	v_fmac_f32_dpp v92, v248, v55 quad_perm:[3,3,3,3] row_mask:0xf bank_mask:0xf
	s_waitcnt lgkmcnt(6)
	v_fmac_f32_dpp v73, v249, v56 quad_perm:[0,0,0,0] row_mask:0xf bank_mask:0xf
	v_fmac_f32_dpp v90, v249, v57 quad_perm:[1,1,1,1] row_mask:0xf bank_mask:0xf
	v_fmac_f32_dpp v91, v249, v58 quad_perm:[2,2,2,2] row_mask:0xf bank_mask:0xf
	v_fmac_f32_dpp v92, v249, v59 quad_perm:[3,3,3,3] row_mask:0xf bank_mask:0xf
	s_waitcnt lgkmcnt(5)
	v_fmac_f32_dpp v73, v250, v60 quad_perm:[0,0,0,0] row_mask:0xf bank_mask:0xf
	v_fmac_f32_dpp v90, v250, v61 quad_perm:[1,1,1,1] row_mask:0xf bank_mask:0xf
	v_fmac_f32_dpp v91, v250, v62 quad_perm:[2,2,2,2] row_mask:0xf bank_mask:0xf
	v_fmac_f32_dpp v92, v250, v63 quad_perm:[3,3,3,3] row_mask:0xf bank_mask:0xf
	s_waitcnt lgkmcnt(4)
	v_fmac_f32_dpp v73, v251, v64 quad_perm:[0,0,0,0] row_mask:0xf bank_mask:0xf
	v_fmac_f32_dpp v90, v251, v65 quad_perm:[1,1,1,1] row_mask:0xf bank_mask:0xf
	v_fmac_f32_dpp v91, v251, v66 quad_perm:[2,2,2,2] row_mask:0xf bank_mask:0xf
	v_fmac_f32_dpp v92, v251, v67 quad_perm:[3,3,3,3] row_mask:0xf bank_mask:0xf
	s_waitcnt lgkmcnt(0)
	v_fmac_f32_dpp v73, v240, v68 quad_perm:[0,0,0,0] row_mask:0xf bank_mask:0xf
	v_fmac_f32_dpp v90, v240, v69 quad_perm:[1,1,1,1] row_mask:0xf bank_mask:0xf
	v_fmac_f32_dpp v91, v240, v70 quad_perm:[2,2,2,2] row_mask:0xf bank_mask:0xf
	v_fmac_f32_dpp v92, v240, v71 quad_perm:[3,3,3,3] row_mask:0xf bank_mask:0xf
	ds_read_b32 v240, v255 offset:13568
	ds_read_b32 v241, v255 offset:13584
	ds_read_b32 v242, v255 offset:13600
	ds_read_b32 v243, v255 offset:13616
	ds_read_b32 v244, v255 offset:13632
	ds_read_b32 v245, v255 offset:13648
	ds_read_b32 v246, v255 offset:13664
	ds_read_b32 v247, v255 offset:13680
	ds_read_b32 v248, v255 offset:13696
	ds_read_b32 v249, v255 offset:13712
	ds_read_b32 v250, v255 offset:13728
	ds_read_b32 v251, v255 offset:13744
	v_add_f32_e32 v73, v73, v90
	v_add_f32_e32 v74, v91, v92
	v_add_f32_e32 v73, v73, v74
	v_sub_f32_e32 v72, v72, v73
	v_lshlrev_b32_e32 v73, 16, v238
	v_mul_f32_e32 v73, v239, v73
	s_cmp_eq_u64 s[16:17], 0
	s_cbranch_scc1 .LBB0_911
	v_mul_f32_e32 v73, v73, v254
.LBB0_911:
	ds_read_u16 v238, v18 offset:14688
	ds_read_b32 v239, v16 offset:216
	ds_read_b32 v254, v15 offset:216
	s_waitcnt lgkmcnt(14)
	v_mul_f32_dpp v90, v240, v2 quad_perm:[0,0,0,0] row_mask:0xf bank_mask:0xf
	v_mul_f32_dpp v91, v240, v3 quad_perm:[1,1,1,1] row_mask:0xf bank_mask:0xf
	v_mul_f32_dpp v92, v240, v4 quad_perm:[2,2,2,2] row_mask:0xf bank_mask:0xf
	v_mul_f32_dpp v93, v240, v5 quad_perm:[3,3,3,3] row_mask:0xf bank_mask:0xf
	ds_read_b32 v240, v255 offset:13760
	s_waitcnt lgkmcnt(14)
	v_fmac_f32_dpp v90, v241, v6 quad_perm:[0,0,0,0] row_mask:0xf bank_mask:0xf
	v_fmac_f32_dpp v91, v241, v7 quad_perm:[1,1,1,1] row_mask:0xf bank_mask:0xf
	v_fmac_f32_dpp v92, v241, v8 quad_perm:[2,2,2,2] row_mask:0xf bank_mask:0xf
	v_fmac_f32_dpp v93, v241, v9 quad_perm:[3,3,3,3] row_mask:0xf bank_mask:0xf
	ds_read_b32 v241, v255 offset:13776
	s_waitcnt lgkmcnt(14)
	v_fmac_f32_dpp v90, v242, v10 quad_perm:[0,0,0,0] row_mask:0xf bank_mask:0xf
	v_fmac_f32_dpp v91, v242, v12 quad_perm:[1,1,1,1] row_mask:0xf bank_mask:0xf
	v_fmac_f32_dpp v92, v242, v13 quad_perm:[2,2,2,2] row_mask:0xf bank_mask:0xf
	v_fmac_f32_dpp v93, v242, v14 quad_perm:[3,3,3,3] row_mask:0xf bank_mask:0xf
	s_waitcnt lgkmcnt(13)
	v_fmac_f32_dpp v90, v243, v17 quad_perm:[0,0,0,0] row_mask:0xf bank_mask:0xf
	v_fmac_f32_dpp v91, v243, v19 quad_perm:[1,1,1,1] row_mask:0xf bank_mask:0xf
	v_fmac_f32_dpp v92, v243, v28 quad_perm:[2,2,2,2] row_mask:0xf bank_mask:0xf
	v_fmac_f32_dpp v93, v243, v35 quad_perm:[3,3,3,3] row_mask:0xf bank_mask:0xf
	s_waitcnt lgkmcnt(12)
	v_fmac_f32_dpp v90, v244, v36 quad_perm:[0,0,0,0] row_mask:0xf bank_mask:0xf
	v_fmac_f32_dpp v91, v244, v37 quad_perm:[1,1,1,1] row_mask:0xf bank_mask:0xf
	v_fmac_f32_dpp v92, v244, v38 quad_perm:[2,2,2,2] row_mask:0xf bank_mask:0xf
	v_fmac_f32_dpp v93, v244, v39 quad_perm:[3,3,3,3] row_mask:0xf bank_mask:0xf
	s_waitcnt lgkmcnt(11)
	v_fmac_f32_dpp v90, v245, v40 quad_perm:[0,0,0,0] row_mask:0xf bank_mask:0xf
	v_fmac_f32_dpp v91, v245, v41 quad_perm:[1,1,1,1] row_mask:0xf bank_mask:0xf
	v_fmac_f32_dpp v92, v245, v42 quad_perm:[2,2,2,2] row_mask:0xf bank_mask:0xf
	v_fmac_f32_dpp v93, v245, v43 quad_perm:[3,3,3,3] row_mask:0xf bank_mask:0xf
	s_waitcnt lgkmcnt(10)
	v_fmac_f32_dpp v90, v246, v44 quad_perm:[0,0,0,0] row_mask:0xf bank_mask:0xf
	v_fmac_f32_dpp v91, v246, v45 quad_perm:[1,1,1,1] row_mask:0xf bank_mask:0xf
	v_fmac_f32_dpp v92, v246, v46 quad_perm:[2,2,2,2] row_mask:0xf bank_mask:0xf
	v_fmac_f32_dpp v93, v246, v47 quad_perm:[3,3,3,3] row_mask:0xf bank_mask:0xf
	s_waitcnt lgkmcnt(9)
	v_fmac_f32_dpp v90, v247, v48 quad_perm:[0,0,0,0] row_mask:0xf bank_mask:0xf
	v_fmac_f32_dpp v91, v247, v49 quad_perm:[1,1,1,1] row_mask:0xf bank_mask:0xf
	v_fmac_f32_dpp v92, v247, v50 quad_perm:[2,2,2,2] row_mask:0xf bank_mask:0xf
	v_fmac_f32_dpp v93, v247, v51 quad_perm:[3,3,3,3] row_mask:0xf bank_mask:0xf
	s_waitcnt lgkmcnt(8)
	v_fmac_f32_dpp v90, v248, v52 quad_perm:[0,0,0,0] row_mask:0xf bank_mask:0xf
	v_fmac_f32_dpp v91, v248, v53 quad_perm:[1,1,1,1] row_mask:0xf bank_mask:0xf
	v_fmac_f32_dpp v92, v248, v54 quad_perm:[2,2,2,2] row_mask:0xf bank_mask:0xf
	v_fmac_f32_dpp v93, v248, v55 quad_perm:[3,3,3,3] row_mask:0xf bank_mask:0xf
	s_waitcnt lgkmcnt(7)
	v_fmac_f32_dpp v90, v249, v56 quad_perm:[0,0,0,0] row_mask:0xf bank_mask:0xf
	v_fmac_f32_dpp v91, v249, v57 quad_perm:[1,1,1,1] row_mask:0xf bank_mask:0xf
	v_fmac_f32_dpp v92, v249, v58 quad_perm:[2,2,2,2] row_mask:0xf bank_mask:0xf
	v_fmac_f32_dpp v93, v249, v59 quad_perm:[3,3,3,3] row_mask:0xf bank_mask:0xf
	s_waitcnt lgkmcnt(6)
	v_fmac_f32_dpp v90, v250, v60 quad_perm:[0,0,0,0] row_mask:0xf bank_mask:0xf
	v_fmac_f32_dpp v91, v250, v61 quad_perm:[1,1,1,1] row_mask:0xf bank_mask:0xf
	v_fmac_f32_dpp v92, v250, v62 quad_perm:[2,2,2,2] row_mask:0xf bank_mask:0xf
	v_fmac_f32_dpp v93, v250, v63 quad_perm:[3,3,3,3] row_mask:0xf bank_mask:0xf
	s_waitcnt lgkmcnt(5)
	v_fmac_f32_dpp v90, v251, v64 quad_perm:[0,0,0,0] row_mask:0xf bank_mask:0xf
	v_fmac_f32_dpp v91, v251, v65 quad_perm:[1,1,1,1] row_mask:0xf bank_mask:0xf
	v_fmac_f32_dpp v92, v251, v66 quad_perm:[2,2,2,2] row_mask:0xf bank_mask:0xf
	v_fmac_f32_dpp v93, v251, v67 quad_perm:[3,3,3,3] row_mask:0xf bank_mask:0xf
	s_waitcnt lgkmcnt(1)
	v_fmac_f32_dpp v90, v240, v68 quad_perm:[0,0,0,0] row_mask:0xf bank_mask:0xf
	v_fmac_f32_dpp v91, v240, v69 quad_perm:[1,1,1,1] row_mask:0xf bank_mask:0xf
	v_fmac_f32_dpp v92, v240, v70 quad_perm:[2,2,2,2] row_mask:0xf bank_mask:0xf
	v_fmac_f32_dpp v93, v240, v71 quad_perm:[3,3,3,3] row_mask:0xf bank_mask:0xf
	s_waitcnt lgkmcnt(0)
	v_fmac_f32_dpp v90, v241, v72 quad_perm:[0,0,0,0] row_mask:0xf bank_mask:0xf
	ds_read_b32 v240, v255 offset:13824
	ds_read_b32 v241, v255 offset:13840
	ds_read_b32 v242, v255 offset:13856
	ds_read_b32 v243, v255 offset:13872
	ds_read_b32 v244, v255 offset:13888
	ds_read_b32 v245, v255 offset:13904
	ds_read_b32 v246, v255 offset:13920
	ds_read_b32 v247, v255 offset:13936
	ds_read_b32 v248, v255 offset:13952
	ds_read_b32 v249, v255 offset:13968
	ds_read_b32 v250, v255 offset:13984
	ds_read_b32 v251, v255 offset:14000
	v_add_f32_e32 v74, v91, v90
	v_add_f32_e32 v75, v92, v93
	v_add_f32_e32 v74, v75, v74
	v_sub_f32_e32 v73, v73, v74
	v_lshlrev_b32_e32 v74, 16, v238
	v_mul_f32_e32 v74, v239, v74
	s_cmp_eq_u64 s[16:17], 0
	s_cbranch_scc1 .LBB0_913
	v_mul_f32_e32 v74, v74, v254
.LBB0_913:
	ds_read_u16 v238, v18 offset:14960
	ds_read_b32 v239, v16 offset:220
	ds_read_b32 v254, v15 offset:220
	s_waitcnt lgkmcnt(14)
	v_mul_f32_dpp v75, v240, v2 quad_perm:[0,0,0,0] row_mask:0xf bank_mask:0xf
	v_mul_f32_dpp v92, v240, v3 quad_perm:[1,1,1,1] row_mask:0xf bank_mask:0xf
	v_mul_f32_dpp v93, v240, v4 quad_perm:[2,2,2,2] row_mask:0xf bank_mask:0xf
	v_mul_f32_dpp v94, v240, v5 quad_perm:[3,3,3,3] row_mask:0xf bank_mask:0xf
	ds_read_b32 v240, v255 offset:14016
	s_waitcnt lgkmcnt(14)
	v_fmac_f32_dpp v75, v241, v6 quad_perm:[0,0,0,0] row_mask:0xf bank_mask:0xf
	v_fmac_f32_dpp v92, v241, v7 quad_perm:[1,1,1,1] row_mask:0xf bank_mask:0xf
	v_fmac_f32_dpp v93, v241, v8 quad_perm:[2,2,2,2] row_mask:0xf bank_mask:0xf
	v_fmac_f32_dpp v94, v241, v9 quad_perm:[3,3,3,3] row_mask:0xf bank_mask:0xf
	ds_read_b32 v241, v255 offset:14032
	s_waitcnt lgkmcnt(14)
	v_fmac_f32_dpp v75, v242, v10 quad_perm:[0,0,0,0] row_mask:0xf bank_mask:0xf
	v_fmac_f32_dpp v92, v242, v12 quad_perm:[1,1,1,1] row_mask:0xf bank_mask:0xf
	v_fmac_f32_dpp v93, v242, v13 quad_perm:[2,2,2,2] row_mask:0xf bank_mask:0xf
	v_fmac_f32_dpp v94, v242, v14 quad_perm:[3,3,3,3] row_mask:0xf bank_mask:0xf
	s_waitcnt lgkmcnt(13)
	v_fmac_f32_dpp v75, v243, v17 quad_perm:[0,0,0,0] row_mask:0xf bank_mask:0xf
	v_fmac_f32_dpp v92, v243, v19 quad_perm:[1,1,1,1] row_mask:0xf bank_mask:0xf
	v_fmac_f32_dpp v93, v243, v28 quad_perm:[2,2,2,2] row_mask:0xf bank_mask:0xf
	v_fmac_f32_dpp v94, v243, v35 quad_perm:[3,3,3,3] row_mask:0xf bank_mask:0xf
	s_waitcnt lgkmcnt(12)
	v_fmac_f32_dpp v75, v244, v36 quad_perm:[0,0,0,0] row_mask:0xf bank_mask:0xf
	v_fmac_f32_dpp v92, v244, v37 quad_perm:[1,1,1,1] row_mask:0xf bank_mask:0xf
	v_fmac_f32_dpp v93, v244, v38 quad_perm:[2,2,2,2] row_mask:0xf bank_mask:0xf
	v_fmac_f32_dpp v94, v244, v39 quad_perm:[3,3,3,3] row_mask:0xf bank_mask:0xf
	s_waitcnt lgkmcnt(11)
	v_fmac_f32_dpp v75, v245, v40 quad_perm:[0,0,0,0] row_mask:0xf bank_mask:0xf
	v_fmac_f32_dpp v92, v245, v41 quad_perm:[1,1,1,1] row_mask:0xf bank_mask:0xf
	v_fmac_f32_dpp v93, v245, v42 quad_perm:[2,2,2,2] row_mask:0xf bank_mask:0xf
	v_fmac_f32_dpp v94, v245, v43 quad_perm:[3,3,3,3] row_mask:0xf bank_mask:0xf
	s_waitcnt lgkmcnt(10)
	v_fmac_f32_dpp v75, v246, v44 quad_perm:[0,0,0,0] row_mask:0xf bank_mask:0xf
	v_fmac_f32_dpp v92, v246, v45 quad_perm:[1,1,1,1] row_mask:0xf bank_mask:0xf
	v_fmac_f32_dpp v93, v246, v46 quad_perm:[2,2,2,2] row_mask:0xf bank_mask:0xf
	v_fmac_f32_dpp v94, v246, v47 quad_perm:[3,3,3,3] row_mask:0xf bank_mask:0xf
	s_waitcnt lgkmcnt(9)
	v_fmac_f32_dpp v75, v247, v48 quad_perm:[0,0,0,0] row_mask:0xf bank_mask:0xf
	v_fmac_f32_dpp v92, v247, v49 quad_perm:[1,1,1,1] row_mask:0xf bank_mask:0xf
	v_fmac_f32_dpp v93, v247, v50 quad_perm:[2,2,2,2] row_mask:0xf bank_mask:0xf
	v_fmac_f32_dpp v94, v247, v51 quad_perm:[3,3,3,3] row_mask:0xf bank_mask:0xf
	s_waitcnt lgkmcnt(8)
	v_fmac_f32_dpp v75, v248, v52 quad_perm:[0,0,0,0] row_mask:0xf bank_mask:0xf
	v_fmac_f32_dpp v92, v248, v53 quad_perm:[1,1,1,1] row_mask:0xf bank_mask:0xf
	v_fmac_f32_dpp v93, v248, v54 quad_perm:[2,2,2,2] row_mask:0xf bank_mask:0xf
	v_fmac_f32_dpp v94, v248, v55 quad_perm:[3,3,3,3] row_mask:0xf bank_mask:0xf
	s_waitcnt lgkmcnt(7)
	v_fmac_f32_dpp v75, v249, v56 quad_perm:[0,0,0,0] row_mask:0xf bank_mask:0xf
	v_fmac_f32_dpp v92, v249, v57 quad_perm:[1,1,1,1] row_mask:0xf bank_mask:0xf
	v_fmac_f32_dpp v93, v249, v58 quad_perm:[2,2,2,2] row_mask:0xf bank_mask:0xf
	v_fmac_f32_dpp v94, v249, v59 quad_perm:[3,3,3,3] row_mask:0xf bank_mask:0xf
	s_waitcnt lgkmcnt(6)
	v_fmac_f32_dpp v75, v250, v60 quad_perm:[0,0,0,0] row_mask:0xf bank_mask:0xf
	v_fmac_f32_dpp v92, v250, v61 quad_perm:[1,1,1,1] row_mask:0xf bank_mask:0xf
	v_fmac_f32_dpp v93, v250, v62 quad_perm:[2,2,2,2] row_mask:0xf bank_mask:0xf
	v_fmac_f32_dpp v94, v250, v63 quad_perm:[3,3,3,3] row_mask:0xf bank_mask:0xf
	s_waitcnt lgkmcnt(5)
	v_fmac_f32_dpp v75, v251, v64 quad_perm:[0,0,0,0] row_mask:0xf bank_mask:0xf
	v_fmac_f32_dpp v92, v251, v65 quad_perm:[1,1,1,1] row_mask:0xf bank_mask:0xf
	v_fmac_f32_dpp v93, v251, v66 quad_perm:[2,2,2,2] row_mask:0xf bank_mask:0xf
	v_fmac_f32_dpp v94, v251, v67 quad_perm:[3,3,3,3] row_mask:0xf bank_mask:0xf
	s_waitcnt lgkmcnt(1)
	v_fmac_f32_dpp v75, v240, v68 quad_perm:[0,0,0,0] row_mask:0xf bank_mask:0xf
	v_fmac_f32_dpp v92, v240, v69 quad_perm:[1,1,1,1] row_mask:0xf bank_mask:0xf
	v_fmac_f32_dpp v93, v240, v70 quad_perm:[2,2,2,2] row_mask:0xf bank_mask:0xf
	v_fmac_f32_dpp v94, v240, v71 quad_perm:[3,3,3,3] row_mask:0xf bank_mask:0xf
	s_waitcnt lgkmcnt(0)
	v_fmac_f32_dpp v75, v241, v72 quad_perm:[0,0,0,0] row_mask:0xf bank_mask:0xf
	v_fmac_f32_dpp v92, v241, v73 quad_perm:[1,1,1,1] row_mask:0xf bank_mask:0xf
	ds_read_b32 v240, v255 offset:14080
	ds_read_b32 v241, v255 offset:14096
	ds_read_b32 v242, v255 offset:14112
	ds_read_b32 v243, v255 offset:14128
	ds_read_b32 v244, v255 offset:14144
	ds_read_b32 v245, v255 offset:14160
	ds_read_b32 v246, v255 offset:14176
	ds_read_b32 v247, v255 offset:14192
	ds_read_b32 v248, v255 offset:14208
	ds_read_b32 v249, v255 offset:14224
	ds_read_b32 v250, v255 offset:14240
	ds_read_b32 v251, v255 offset:14256
	v_add_f32_e32 v75, v75, v92
	v_add_f32_e32 v76, v93, v94
	v_add_f32_e32 v75, v76, v75
	v_sub_f32_e32 v74, v74, v75
	v_lshlrev_b32_e32 v75, 16, v238
	v_mul_f32_e32 v75, v239, v75
	s_cmp_eq_u64 s[16:17], 0
	s_cbranch_scc1 .LBB0_915
	v_mul_f32_e32 v75, v75, v254
.LBB0_915:
	ds_read_u16 v238, v18 offset:15232
	ds_read_b32 v239, v16 offset:224
	ds_read_b32 v254, v15 offset:224
	s_waitcnt lgkmcnt(14)
	v_mul_f32_dpp v92, v240, v2 quad_perm:[0,0,0,0] row_mask:0xf bank_mask:0xf
	v_mul_f32_dpp v93, v240, v3 quad_perm:[1,1,1,1] row_mask:0xf bank_mask:0xf
	v_mul_f32_dpp v94, v240, v4 quad_perm:[2,2,2,2] row_mask:0xf bank_mask:0xf
	v_mul_f32_dpp v95, v240, v5 quad_perm:[3,3,3,3] row_mask:0xf bank_mask:0xf
	ds_read_b32 v240, v255 offset:14272
	s_waitcnt lgkmcnt(14)
	v_fmac_f32_dpp v92, v241, v6 quad_perm:[0,0,0,0] row_mask:0xf bank_mask:0xf
	v_fmac_f32_dpp v93, v241, v7 quad_perm:[1,1,1,1] row_mask:0xf bank_mask:0xf
	v_fmac_f32_dpp v94, v241, v8 quad_perm:[2,2,2,2] row_mask:0xf bank_mask:0xf
	v_fmac_f32_dpp v95, v241, v9 quad_perm:[3,3,3,3] row_mask:0xf bank_mask:0xf
	ds_read_b32 v241, v255 offset:14288
	s_waitcnt lgkmcnt(14)
	v_fmac_f32_dpp v92, v242, v10 quad_perm:[0,0,0,0] row_mask:0xf bank_mask:0xf
	v_fmac_f32_dpp v93, v242, v12 quad_perm:[1,1,1,1] row_mask:0xf bank_mask:0xf
	v_fmac_f32_dpp v94, v242, v13 quad_perm:[2,2,2,2] row_mask:0xf bank_mask:0xf
	v_fmac_f32_dpp v95, v242, v14 quad_perm:[3,3,3,3] row_mask:0xf bank_mask:0xf
	s_waitcnt lgkmcnt(13)
	v_fmac_f32_dpp v92, v243, v17 quad_perm:[0,0,0,0] row_mask:0xf bank_mask:0xf
	v_fmac_f32_dpp v93, v243, v19 quad_perm:[1,1,1,1] row_mask:0xf bank_mask:0xf
	v_fmac_f32_dpp v94, v243, v28 quad_perm:[2,2,2,2] row_mask:0xf bank_mask:0xf
	v_fmac_f32_dpp v95, v243, v35 quad_perm:[3,3,3,3] row_mask:0xf bank_mask:0xf
	s_waitcnt lgkmcnt(12)
	v_fmac_f32_dpp v92, v244, v36 quad_perm:[0,0,0,0] row_mask:0xf bank_mask:0xf
	v_fmac_f32_dpp v93, v244, v37 quad_perm:[1,1,1,1] row_mask:0xf bank_mask:0xf
	v_fmac_f32_dpp v94, v244, v38 quad_perm:[2,2,2,2] row_mask:0xf bank_mask:0xf
	v_fmac_f32_dpp v95, v244, v39 quad_perm:[3,3,3,3] row_mask:0xf bank_mask:0xf
	s_waitcnt lgkmcnt(11)
	v_fmac_f32_dpp v92, v245, v40 quad_perm:[0,0,0,0] row_mask:0xf bank_mask:0xf
	v_fmac_f32_dpp v93, v245, v41 quad_perm:[1,1,1,1] row_mask:0xf bank_mask:0xf
	v_fmac_f32_dpp v94, v245, v42 quad_perm:[2,2,2,2] row_mask:0xf bank_mask:0xf
	v_fmac_f32_dpp v95, v245, v43 quad_perm:[3,3,3,3] row_mask:0xf bank_mask:0xf
	s_waitcnt lgkmcnt(10)
	v_fmac_f32_dpp v92, v246, v44 quad_perm:[0,0,0,0] row_mask:0xf bank_mask:0xf
	v_fmac_f32_dpp v93, v246, v45 quad_perm:[1,1,1,1] row_mask:0xf bank_mask:0xf
	v_fmac_f32_dpp v94, v246, v46 quad_perm:[2,2,2,2] row_mask:0xf bank_mask:0xf
	v_fmac_f32_dpp v95, v246, v47 quad_perm:[3,3,3,3] row_mask:0xf bank_mask:0xf
	s_waitcnt lgkmcnt(9)
	v_fmac_f32_dpp v92, v247, v48 quad_perm:[0,0,0,0] row_mask:0xf bank_mask:0xf
	v_fmac_f32_dpp v93, v247, v49 quad_perm:[1,1,1,1] row_mask:0xf bank_mask:0xf
	v_fmac_f32_dpp v94, v247, v50 quad_perm:[2,2,2,2] row_mask:0xf bank_mask:0xf
	v_fmac_f32_dpp v95, v247, v51 quad_perm:[3,3,3,3] row_mask:0xf bank_mask:0xf
	s_waitcnt lgkmcnt(8)
	v_fmac_f32_dpp v92, v248, v52 quad_perm:[0,0,0,0] row_mask:0xf bank_mask:0xf
	v_fmac_f32_dpp v93, v248, v53 quad_perm:[1,1,1,1] row_mask:0xf bank_mask:0xf
	v_fmac_f32_dpp v94, v248, v54 quad_perm:[2,2,2,2] row_mask:0xf bank_mask:0xf
	v_fmac_f32_dpp v95, v248, v55 quad_perm:[3,3,3,3] row_mask:0xf bank_mask:0xf
	s_waitcnt lgkmcnt(7)
	v_fmac_f32_dpp v92, v249, v56 quad_perm:[0,0,0,0] row_mask:0xf bank_mask:0xf
	v_fmac_f32_dpp v93, v249, v57 quad_perm:[1,1,1,1] row_mask:0xf bank_mask:0xf
	v_fmac_f32_dpp v94, v249, v58 quad_perm:[2,2,2,2] row_mask:0xf bank_mask:0xf
	v_fmac_f32_dpp v95, v249, v59 quad_perm:[3,3,3,3] row_mask:0xf bank_mask:0xf
	s_waitcnt lgkmcnt(6)
	v_fmac_f32_dpp v92, v250, v60 quad_perm:[0,0,0,0] row_mask:0xf bank_mask:0xf
	v_fmac_f32_dpp v93, v250, v61 quad_perm:[1,1,1,1] row_mask:0xf bank_mask:0xf
	v_fmac_f32_dpp v94, v250, v62 quad_perm:[2,2,2,2] row_mask:0xf bank_mask:0xf
	v_fmac_f32_dpp v95, v250, v63 quad_perm:[3,3,3,3] row_mask:0xf bank_mask:0xf
	s_waitcnt lgkmcnt(5)
	v_fmac_f32_dpp v92, v251, v64 quad_perm:[0,0,0,0] row_mask:0xf bank_mask:0xf
	v_fmac_f32_dpp v93, v251, v65 quad_perm:[1,1,1,1] row_mask:0xf bank_mask:0xf
	v_fmac_f32_dpp v94, v251, v66 quad_perm:[2,2,2,2] row_mask:0xf bank_mask:0xf
	v_fmac_f32_dpp v95, v251, v67 quad_perm:[3,3,3,3] row_mask:0xf bank_mask:0xf
	s_waitcnt lgkmcnt(1)
	v_fmac_f32_dpp v92, v240, v68 quad_perm:[0,0,0,0] row_mask:0xf bank_mask:0xf
	v_fmac_f32_dpp v93, v240, v69 quad_perm:[1,1,1,1] row_mask:0xf bank_mask:0xf
	v_fmac_f32_dpp v94, v240, v70 quad_perm:[2,2,2,2] row_mask:0xf bank_mask:0xf
	v_fmac_f32_dpp v95, v240, v71 quad_perm:[3,3,3,3] row_mask:0xf bank_mask:0xf
	s_waitcnt lgkmcnt(0)
	v_fmac_f32_dpp v92, v241, v72 quad_perm:[0,0,0,0] row_mask:0xf bank_mask:0xf
	v_fmac_f32_dpp v93, v241, v73 quad_perm:[1,1,1,1] row_mask:0xf bank_mask:0xf
	v_fmac_f32_dpp v94, v241, v74 quad_perm:[2,2,2,2] row_mask:0xf bank_mask:0xf
	ds_read_b32 v240, v255 offset:14336
	ds_read_b32 v241, v255 offset:14352
	ds_read_b32 v242, v255 offset:14368
	ds_read_b32 v243, v255 offset:14384
	ds_read_b32 v244, v255 offset:14400
	ds_read_b32 v245, v255 offset:14416
	ds_read_b32 v246, v255 offset:14432
	ds_read_b32 v247, v255 offset:14448
	ds_read_b32 v248, v255 offset:14464
	ds_read_b32 v249, v255 offset:14480
	ds_read_b32 v250, v255 offset:14496
	ds_read_b32 v251, v255 offset:14512
	v_add_f32_e32 v76, v92, v93
	v_add_f32_e32 v77, v95, v94
	v_add_f32_e32 v76, v76, v77
	v_sub_f32_e32 v75, v75, v76
	v_lshlrev_b32_e32 v76, 16, v238
	v_mul_f32_e32 v76, v239, v76
	s_cmp_eq_u64 s[16:17], 0
	s_cbranch_scc1 .LBB0_917
	v_mul_f32_e32 v76, v76, v254
.LBB0_917:
	ds_read_u16 v238, v18 offset:15504
	ds_read_b32 v239, v16 offset:228
	ds_read_b32 v254, v15 offset:228
	s_waitcnt lgkmcnt(14)
	v_mul_f32_dpp v77, v240, v2 quad_perm:[0,0,0,0] row_mask:0xf bank_mask:0xf
	v_mul_f32_dpp v94, v240, v3 quad_perm:[1,1,1,1] row_mask:0xf bank_mask:0xf
	v_mul_f32_dpp v95, v240, v4 quad_perm:[2,2,2,2] row_mask:0xf bank_mask:0xf
	v_mul_f32_dpp v96, v240, v5 quad_perm:[3,3,3,3] row_mask:0xf bank_mask:0xf
	ds_read_b32 v240, v255 offset:14528
	s_waitcnt lgkmcnt(14)
	v_fmac_f32_dpp v77, v241, v6 quad_perm:[0,0,0,0] row_mask:0xf bank_mask:0xf
	v_fmac_f32_dpp v94, v241, v7 quad_perm:[1,1,1,1] row_mask:0xf bank_mask:0xf
	v_fmac_f32_dpp v95, v241, v8 quad_perm:[2,2,2,2] row_mask:0xf bank_mask:0xf
	v_fmac_f32_dpp v96, v241, v9 quad_perm:[3,3,3,3] row_mask:0xf bank_mask:0xf
	ds_read_b32 v241, v255 offset:14544
	s_waitcnt lgkmcnt(14)
	v_fmac_f32_dpp v77, v242, v10 quad_perm:[0,0,0,0] row_mask:0xf bank_mask:0xf
	v_fmac_f32_dpp v94, v242, v12 quad_perm:[1,1,1,1] row_mask:0xf bank_mask:0xf
	v_fmac_f32_dpp v95, v242, v13 quad_perm:[2,2,2,2] row_mask:0xf bank_mask:0xf
	v_fmac_f32_dpp v96, v242, v14 quad_perm:[3,3,3,3] row_mask:0xf bank_mask:0xf
	s_waitcnt lgkmcnt(13)
	v_fmac_f32_dpp v77, v243, v17 quad_perm:[0,0,0,0] row_mask:0xf bank_mask:0xf
	v_fmac_f32_dpp v94, v243, v19 quad_perm:[1,1,1,1] row_mask:0xf bank_mask:0xf
	v_fmac_f32_dpp v95, v243, v28 quad_perm:[2,2,2,2] row_mask:0xf bank_mask:0xf
	v_fmac_f32_dpp v96, v243, v35 quad_perm:[3,3,3,3] row_mask:0xf bank_mask:0xf
	s_waitcnt lgkmcnt(12)
	v_fmac_f32_dpp v77, v244, v36 quad_perm:[0,0,0,0] row_mask:0xf bank_mask:0xf
	v_fmac_f32_dpp v94, v244, v37 quad_perm:[1,1,1,1] row_mask:0xf bank_mask:0xf
	v_fmac_f32_dpp v95, v244, v38 quad_perm:[2,2,2,2] row_mask:0xf bank_mask:0xf
	v_fmac_f32_dpp v96, v244, v39 quad_perm:[3,3,3,3] row_mask:0xf bank_mask:0xf
	s_waitcnt lgkmcnt(11)
	v_fmac_f32_dpp v77, v245, v40 quad_perm:[0,0,0,0] row_mask:0xf bank_mask:0xf
	v_fmac_f32_dpp v94, v245, v41 quad_perm:[1,1,1,1] row_mask:0xf bank_mask:0xf
	v_fmac_f32_dpp v95, v245, v42 quad_perm:[2,2,2,2] row_mask:0xf bank_mask:0xf
	v_fmac_f32_dpp v96, v245, v43 quad_perm:[3,3,3,3] row_mask:0xf bank_mask:0xf
	s_waitcnt lgkmcnt(10)
	v_fmac_f32_dpp v77, v246, v44 quad_perm:[0,0,0,0] row_mask:0xf bank_mask:0xf
	v_fmac_f32_dpp v94, v246, v45 quad_perm:[1,1,1,1] row_mask:0xf bank_mask:0xf
	v_fmac_f32_dpp v95, v246, v46 quad_perm:[2,2,2,2] row_mask:0xf bank_mask:0xf
	v_fmac_f32_dpp v96, v246, v47 quad_perm:[3,3,3,3] row_mask:0xf bank_mask:0xf
	s_waitcnt lgkmcnt(9)
	v_fmac_f32_dpp v77, v247, v48 quad_perm:[0,0,0,0] row_mask:0xf bank_mask:0xf
	v_fmac_f32_dpp v94, v247, v49 quad_perm:[1,1,1,1] row_mask:0xf bank_mask:0xf
	v_fmac_f32_dpp v95, v247, v50 quad_perm:[2,2,2,2] row_mask:0xf bank_mask:0xf
	v_fmac_f32_dpp v96, v247, v51 quad_perm:[3,3,3,3] row_mask:0xf bank_mask:0xf
	s_waitcnt lgkmcnt(8)
	v_fmac_f32_dpp v77, v248, v52 quad_perm:[0,0,0,0] row_mask:0xf bank_mask:0xf
	v_fmac_f32_dpp v94, v248, v53 quad_perm:[1,1,1,1] row_mask:0xf bank_mask:0xf
	v_fmac_f32_dpp v95, v248, v54 quad_perm:[2,2,2,2] row_mask:0xf bank_mask:0xf
	v_fmac_f32_dpp v96, v248, v55 quad_perm:[3,3,3,3] row_mask:0xf bank_mask:0xf
	s_waitcnt lgkmcnt(7)
	v_fmac_f32_dpp v77, v249, v56 quad_perm:[0,0,0,0] row_mask:0xf bank_mask:0xf
	v_fmac_f32_dpp v94, v249, v57 quad_perm:[1,1,1,1] row_mask:0xf bank_mask:0xf
	v_fmac_f32_dpp v95, v249, v58 quad_perm:[2,2,2,2] row_mask:0xf bank_mask:0xf
	v_fmac_f32_dpp v96, v249, v59 quad_perm:[3,3,3,3] row_mask:0xf bank_mask:0xf
	s_waitcnt lgkmcnt(6)
	v_fmac_f32_dpp v77, v250, v60 quad_perm:[0,0,0,0] row_mask:0xf bank_mask:0xf
	v_fmac_f32_dpp v94, v250, v61 quad_perm:[1,1,1,1] row_mask:0xf bank_mask:0xf
	v_fmac_f32_dpp v95, v250, v62 quad_perm:[2,2,2,2] row_mask:0xf bank_mask:0xf
	v_fmac_f32_dpp v96, v250, v63 quad_perm:[3,3,3,3] row_mask:0xf bank_mask:0xf
	s_waitcnt lgkmcnt(5)
	v_fmac_f32_dpp v77, v251, v64 quad_perm:[0,0,0,0] row_mask:0xf bank_mask:0xf
	v_fmac_f32_dpp v94, v251, v65 quad_perm:[1,1,1,1] row_mask:0xf bank_mask:0xf
	v_fmac_f32_dpp v95, v251, v66 quad_perm:[2,2,2,2] row_mask:0xf bank_mask:0xf
	v_fmac_f32_dpp v96, v251, v67 quad_perm:[3,3,3,3] row_mask:0xf bank_mask:0xf
	s_waitcnt lgkmcnt(1)
	v_fmac_f32_dpp v77, v240, v68 quad_perm:[0,0,0,0] row_mask:0xf bank_mask:0xf
	v_fmac_f32_dpp v94, v240, v69 quad_perm:[1,1,1,1] row_mask:0xf bank_mask:0xf
	v_fmac_f32_dpp v95, v240, v70 quad_perm:[2,2,2,2] row_mask:0xf bank_mask:0xf
	v_fmac_f32_dpp v96, v240, v71 quad_perm:[3,3,3,3] row_mask:0xf bank_mask:0xf
	s_waitcnt lgkmcnt(0)
	v_fmac_f32_dpp v77, v241, v72 quad_perm:[0,0,0,0] row_mask:0xf bank_mask:0xf
	v_fmac_f32_dpp v94, v241, v73 quad_perm:[1,1,1,1] row_mask:0xf bank_mask:0xf
	v_fmac_f32_dpp v95, v241, v74 quad_perm:[2,2,2,2] row_mask:0xf bank_mask:0xf
	v_fmac_f32_dpp v96, v241, v75 quad_perm:[3,3,3,3] row_mask:0xf bank_mask:0xf
	ds_read_b32 v240, v255 offset:14592
	ds_read_b32 v241, v255 offset:14608
	ds_read_b32 v242, v255 offset:14624
	ds_read_b32 v243, v255 offset:14640
	ds_read_b32 v244, v255 offset:14656
	ds_read_b32 v245, v255 offset:14672
	ds_read_b32 v246, v255 offset:14688
	ds_read_b32 v247, v255 offset:14704
	ds_read_b32 v248, v255 offset:14720
	ds_read_b32 v249, v255 offset:14736
	ds_read_b32 v250, v255 offset:14752
	ds_read_b32 v251, v255 offset:14768
	v_add_f32_e32 v77, v77, v94
	v_add_f32_e32 v78, v95, v96
	v_add_f32_e32 v77, v77, v78
	v_sub_f32_e32 v76, v76, v77
	v_lshlrev_b32_e32 v77, 16, v238
	v_mul_f32_e32 v77, v239, v77
	s_cmp_eq_u64 s[16:17], 0
	s_cbranch_scc1 .LBB0_919
	v_mul_f32_e32 v77, v77, v254
.LBB0_919:
	ds_read_u16 v238, v18 offset:15776
	ds_read_b32 v239, v16 offset:232
	ds_read_b32 v254, v15 offset:232
	s_waitcnt lgkmcnt(14)
	v_mul_f32_dpp v94, v240, v2 quad_perm:[0,0,0,0] row_mask:0xf bank_mask:0xf
	v_mul_f32_dpp v95, v240, v3 quad_perm:[1,1,1,1] row_mask:0xf bank_mask:0xf
	v_mul_f32_dpp v96, v240, v4 quad_perm:[2,2,2,2] row_mask:0xf bank_mask:0xf
	v_mul_f32_dpp v97, v240, v5 quad_perm:[3,3,3,3] row_mask:0xf bank_mask:0xf
	ds_read_b32 v240, v255 offset:14784
	s_waitcnt lgkmcnt(14)
	v_fmac_f32_dpp v94, v241, v6 quad_perm:[0,0,0,0] row_mask:0xf bank_mask:0xf
	v_fmac_f32_dpp v95, v241, v7 quad_perm:[1,1,1,1] row_mask:0xf bank_mask:0xf
	v_fmac_f32_dpp v96, v241, v8 quad_perm:[2,2,2,2] row_mask:0xf bank_mask:0xf
	v_fmac_f32_dpp v97, v241, v9 quad_perm:[3,3,3,3] row_mask:0xf bank_mask:0xf
	ds_read_b32 v241, v255 offset:14800
	s_waitcnt lgkmcnt(14)
	v_fmac_f32_dpp v94, v242, v10 quad_perm:[0,0,0,0] row_mask:0xf bank_mask:0xf
	v_fmac_f32_dpp v95, v242, v12 quad_perm:[1,1,1,1] row_mask:0xf bank_mask:0xf
	v_fmac_f32_dpp v96, v242, v13 quad_perm:[2,2,2,2] row_mask:0xf bank_mask:0xf
	v_fmac_f32_dpp v97, v242, v14 quad_perm:[3,3,3,3] row_mask:0xf bank_mask:0xf
	ds_read_b32 v242, v255 offset:14816
	s_waitcnt lgkmcnt(14)
	v_fmac_f32_dpp v94, v243, v17 quad_perm:[0,0,0,0] row_mask:0xf bank_mask:0xf
	v_fmac_f32_dpp v95, v243, v19 quad_perm:[1,1,1,1] row_mask:0xf bank_mask:0xf
	v_fmac_f32_dpp v96, v243, v28 quad_perm:[2,2,2,2] row_mask:0xf bank_mask:0xf
	v_fmac_f32_dpp v97, v243, v35 quad_perm:[3,3,3,3] row_mask:0xf bank_mask:0xf
	s_waitcnt lgkmcnt(13)
	v_fmac_f32_dpp v94, v244, v36 quad_perm:[0,0,0,0] row_mask:0xf bank_mask:0xf
	v_fmac_f32_dpp v95, v244, v37 quad_perm:[1,1,1,1] row_mask:0xf bank_mask:0xf
	v_fmac_f32_dpp v96, v244, v38 quad_perm:[2,2,2,2] row_mask:0xf bank_mask:0xf
	v_fmac_f32_dpp v97, v244, v39 quad_perm:[3,3,3,3] row_mask:0xf bank_mask:0xf
	s_waitcnt lgkmcnt(12)
	v_fmac_f32_dpp v94, v245, v40 quad_perm:[0,0,0,0] row_mask:0xf bank_mask:0xf
	v_fmac_f32_dpp v95, v245, v41 quad_perm:[1,1,1,1] row_mask:0xf bank_mask:0xf
	v_fmac_f32_dpp v96, v245, v42 quad_perm:[2,2,2,2] row_mask:0xf bank_mask:0xf
	v_fmac_f32_dpp v97, v245, v43 quad_perm:[3,3,3,3] row_mask:0xf bank_mask:0xf
	s_waitcnt lgkmcnt(11)
	v_fmac_f32_dpp v94, v246, v44 quad_perm:[0,0,0,0] row_mask:0xf bank_mask:0xf
	v_fmac_f32_dpp v95, v246, v45 quad_perm:[1,1,1,1] row_mask:0xf bank_mask:0xf
	v_fmac_f32_dpp v96, v246, v46 quad_perm:[2,2,2,2] row_mask:0xf bank_mask:0xf
	v_fmac_f32_dpp v97, v246, v47 quad_perm:[3,3,3,3] row_mask:0xf bank_mask:0xf
	s_waitcnt lgkmcnt(10)
	v_fmac_f32_dpp v94, v247, v48 quad_perm:[0,0,0,0] row_mask:0xf bank_mask:0xf
	v_fmac_f32_dpp v95, v247, v49 quad_perm:[1,1,1,1] row_mask:0xf bank_mask:0xf
	v_fmac_f32_dpp v96, v247, v50 quad_perm:[2,2,2,2] row_mask:0xf bank_mask:0xf
	v_fmac_f32_dpp v97, v247, v51 quad_perm:[3,3,3,3] row_mask:0xf bank_mask:0xf
	s_waitcnt lgkmcnt(9)
	v_fmac_f32_dpp v94, v248, v52 quad_perm:[0,0,0,0] row_mask:0xf bank_mask:0xf
	v_fmac_f32_dpp v95, v248, v53 quad_perm:[1,1,1,1] row_mask:0xf bank_mask:0xf
	v_fmac_f32_dpp v96, v248, v54 quad_perm:[2,2,2,2] row_mask:0xf bank_mask:0xf
	v_fmac_f32_dpp v97, v248, v55 quad_perm:[3,3,3,3] row_mask:0xf bank_mask:0xf
	s_waitcnt lgkmcnt(8)
	v_fmac_f32_dpp v94, v249, v56 quad_perm:[0,0,0,0] row_mask:0xf bank_mask:0xf
	v_fmac_f32_dpp v95, v249, v57 quad_perm:[1,1,1,1] row_mask:0xf bank_mask:0xf
	v_fmac_f32_dpp v96, v249, v58 quad_perm:[2,2,2,2] row_mask:0xf bank_mask:0xf
	v_fmac_f32_dpp v97, v249, v59 quad_perm:[3,3,3,3] row_mask:0xf bank_mask:0xf
	s_waitcnt lgkmcnt(7)
	v_fmac_f32_dpp v94, v250, v60 quad_perm:[0,0,0,0] row_mask:0xf bank_mask:0xf
	v_fmac_f32_dpp v95, v250, v61 quad_perm:[1,1,1,1] row_mask:0xf bank_mask:0xf
	v_fmac_f32_dpp v96, v250, v62 quad_perm:[2,2,2,2] row_mask:0xf bank_mask:0xf
	v_fmac_f32_dpp v97, v250, v63 quad_perm:[3,3,3,3] row_mask:0xf bank_mask:0xf
	s_waitcnt lgkmcnt(6)
	v_fmac_f32_dpp v94, v251, v64 quad_perm:[0,0,0,0] row_mask:0xf bank_mask:0xf
	v_fmac_f32_dpp v95, v251, v65 quad_perm:[1,1,1,1] row_mask:0xf bank_mask:0xf
	v_fmac_f32_dpp v96, v251, v66 quad_perm:[2,2,2,2] row_mask:0xf bank_mask:0xf
	v_fmac_f32_dpp v97, v251, v67 quad_perm:[3,3,3,3] row_mask:0xf bank_mask:0xf
	s_waitcnt lgkmcnt(2)
	v_fmac_f32_dpp v94, v240, v68 quad_perm:[0,0,0,0] row_mask:0xf bank_mask:0xf
	v_fmac_f32_dpp v95, v240, v69 quad_perm:[1,1,1,1] row_mask:0xf bank_mask:0xf
	v_fmac_f32_dpp v96, v240, v70 quad_perm:[2,2,2,2] row_mask:0xf bank_mask:0xf
	v_fmac_f32_dpp v97, v240, v71 quad_perm:[3,3,3,3] row_mask:0xf bank_mask:0xf
	s_waitcnt lgkmcnt(1)
	v_fmac_f32_dpp v94, v241, v72 quad_perm:[0,0,0,0] row_mask:0xf bank_mask:0xf
	v_fmac_f32_dpp v95, v241, v73 quad_perm:[1,1,1,1] row_mask:0xf bank_mask:0xf
	v_fmac_f32_dpp v96, v241, v74 quad_perm:[2,2,2,2] row_mask:0xf bank_mask:0xf
	v_fmac_f32_dpp v97, v241, v75 quad_perm:[3,3,3,3] row_mask:0xf bank_mask:0xf
	s_waitcnt lgkmcnt(0)
	v_fmac_f32_dpp v94, v242, v76 quad_perm:[0,0,0,0] row_mask:0xf bank_mask:0xf
	ds_read_b32 v240, v255 offset:14848
	ds_read_b32 v241, v255 offset:14864
	ds_read_b32 v242, v255 offset:14880
	ds_read_b32 v243, v255 offset:14896
	ds_read_b32 v244, v255 offset:14912
	ds_read_b32 v245, v255 offset:14928
	ds_read_b32 v246, v255 offset:14944
	ds_read_b32 v247, v255 offset:14960
	ds_read_b32 v248, v255 offset:14976
	ds_read_b32 v249, v255 offset:14992
	ds_read_b32 v250, v255 offset:15008
	ds_read_b32 v251, v255 offset:15024
	v_add_f32_e32 v78, v95, v94
	v_add_f32_e32 v79, v96, v97
	v_add_f32_e32 v78, v79, v78
	v_sub_f32_e32 v77, v77, v78
	v_lshlrev_b32_e32 v78, 16, v238
	v_mul_f32_e32 v78, v239, v78
	s_cmp_eq_u64 s[16:17], 0
	s_cbranch_scc1 .LBB0_921
	v_mul_f32_e32 v78, v78, v254
.LBB0_921:
	ds_read_u16 v238, v18 offset:16048
	ds_read_b32 v239, v16 offset:236
	ds_read_b32 v254, v15 offset:236
	s_waitcnt lgkmcnt(14)
	v_mul_f32_dpp v79, v240, v2 quad_perm:[0,0,0,0] row_mask:0xf bank_mask:0xf
	v_mul_f32_dpp v96, v240, v3 quad_perm:[1,1,1,1] row_mask:0xf bank_mask:0xf
	v_mul_f32_dpp v97, v240, v4 quad_perm:[2,2,2,2] row_mask:0xf bank_mask:0xf
	v_mul_f32_dpp v98, v240, v5 quad_perm:[3,3,3,3] row_mask:0xf bank_mask:0xf
	ds_read_b32 v240, v255 offset:15040
	s_waitcnt lgkmcnt(14)
	v_fmac_f32_dpp v79, v241, v6 quad_perm:[0,0,0,0] row_mask:0xf bank_mask:0xf
	v_fmac_f32_dpp v96, v241, v7 quad_perm:[1,1,1,1] row_mask:0xf bank_mask:0xf
	v_fmac_f32_dpp v97, v241, v8 quad_perm:[2,2,2,2] row_mask:0xf bank_mask:0xf
	v_fmac_f32_dpp v98, v241, v9 quad_perm:[3,3,3,3] row_mask:0xf bank_mask:0xf
	ds_read_b32 v241, v255 offset:15056
	s_waitcnt lgkmcnt(14)
	v_fmac_f32_dpp v79, v242, v10 quad_perm:[0,0,0,0] row_mask:0xf bank_mask:0xf
	v_fmac_f32_dpp v96, v242, v12 quad_perm:[1,1,1,1] row_mask:0xf bank_mask:0xf
	v_fmac_f32_dpp v97, v242, v13 quad_perm:[2,2,2,2] row_mask:0xf bank_mask:0xf
	v_fmac_f32_dpp v98, v242, v14 quad_perm:[3,3,3,3] row_mask:0xf bank_mask:0xf
	ds_read_b32 v242, v255 offset:15072
	s_waitcnt lgkmcnt(14)
	v_fmac_f32_dpp v79, v243, v17 quad_perm:[0,0,0,0] row_mask:0xf bank_mask:0xf
	v_fmac_f32_dpp v96, v243, v19 quad_perm:[1,1,1,1] row_mask:0xf bank_mask:0xf
	v_fmac_f32_dpp v97, v243, v28 quad_perm:[2,2,2,2] row_mask:0xf bank_mask:0xf
	v_fmac_f32_dpp v98, v243, v35 quad_perm:[3,3,3,3] row_mask:0xf bank_mask:0xf
	s_waitcnt lgkmcnt(13)
	v_fmac_f32_dpp v79, v244, v36 quad_perm:[0,0,0,0] row_mask:0xf bank_mask:0xf
	v_fmac_f32_dpp v96, v244, v37 quad_perm:[1,1,1,1] row_mask:0xf bank_mask:0xf
	v_fmac_f32_dpp v97, v244, v38 quad_perm:[2,2,2,2] row_mask:0xf bank_mask:0xf
	v_fmac_f32_dpp v98, v244, v39 quad_perm:[3,3,3,3] row_mask:0xf bank_mask:0xf
	s_waitcnt lgkmcnt(12)
	v_fmac_f32_dpp v79, v245, v40 quad_perm:[0,0,0,0] row_mask:0xf bank_mask:0xf
	v_fmac_f32_dpp v96, v245, v41 quad_perm:[1,1,1,1] row_mask:0xf bank_mask:0xf
	v_fmac_f32_dpp v97, v245, v42 quad_perm:[2,2,2,2] row_mask:0xf bank_mask:0xf
	v_fmac_f32_dpp v98, v245, v43 quad_perm:[3,3,3,3] row_mask:0xf bank_mask:0xf
	s_waitcnt lgkmcnt(11)
	v_fmac_f32_dpp v79, v246, v44 quad_perm:[0,0,0,0] row_mask:0xf bank_mask:0xf
	v_fmac_f32_dpp v96, v246, v45 quad_perm:[1,1,1,1] row_mask:0xf bank_mask:0xf
	v_fmac_f32_dpp v97, v246, v46 quad_perm:[2,2,2,2] row_mask:0xf bank_mask:0xf
	v_fmac_f32_dpp v98, v246, v47 quad_perm:[3,3,3,3] row_mask:0xf bank_mask:0xf
	s_waitcnt lgkmcnt(10)
	v_fmac_f32_dpp v79, v247, v48 quad_perm:[0,0,0,0] row_mask:0xf bank_mask:0xf
	v_fmac_f32_dpp v96, v247, v49 quad_perm:[1,1,1,1] row_mask:0xf bank_mask:0xf
	v_fmac_f32_dpp v97, v247, v50 quad_perm:[2,2,2,2] row_mask:0xf bank_mask:0xf
	v_fmac_f32_dpp v98, v247, v51 quad_perm:[3,3,3,3] row_mask:0xf bank_mask:0xf
	s_waitcnt lgkmcnt(9)
	v_fmac_f32_dpp v79, v248, v52 quad_perm:[0,0,0,0] row_mask:0xf bank_mask:0xf
	v_fmac_f32_dpp v96, v248, v53 quad_perm:[1,1,1,1] row_mask:0xf bank_mask:0xf
	v_fmac_f32_dpp v97, v248, v54 quad_perm:[2,2,2,2] row_mask:0xf bank_mask:0xf
	v_fmac_f32_dpp v98, v248, v55 quad_perm:[3,3,3,3] row_mask:0xf bank_mask:0xf
	s_waitcnt lgkmcnt(8)
	v_fmac_f32_dpp v79, v249, v56 quad_perm:[0,0,0,0] row_mask:0xf bank_mask:0xf
	v_fmac_f32_dpp v96, v249, v57 quad_perm:[1,1,1,1] row_mask:0xf bank_mask:0xf
	v_fmac_f32_dpp v97, v249, v58 quad_perm:[2,2,2,2] row_mask:0xf bank_mask:0xf
	v_fmac_f32_dpp v98, v249, v59 quad_perm:[3,3,3,3] row_mask:0xf bank_mask:0xf
	s_waitcnt lgkmcnt(7)
	v_fmac_f32_dpp v79, v250, v60 quad_perm:[0,0,0,0] row_mask:0xf bank_mask:0xf
	v_fmac_f32_dpp v96, v250, v61 quad_perm:[1,1,1,1] row_mask:0xf bank_mask:0xf
	v_fmac_f32_dpp v97, v250, v62 quad_perm:[2,2,2,2] row_mask:0xf bank_mask:0xf
	v_fmac_f32_dpp v98, v250, v63 quad_perm:[3,3,3,3] row_mask:0xf bank_mask:0xf
	s_waitcnt lgkmcnt(6)
	v_fmac_f32_dpp v79, v251, v64 quad_perm:[0,0,0,0] row_mask:0xf bank_mask:0xf
	v_fmac_f32_dpp v96, v251, v65 quad_perm:[1,1,1,1] row_mask:0xf bank_mask:0xf
	v_fmac_f32_dpp v97, v251, v66 quad_perm:[2,2,2,2] row_mask:0xf bank_mask:0xf
	v_fmac_f32_dpp v98, v251, v67 quad_perm:[3,3,3,3] row_mask:0xf bank_mask:0xf
	s_waitcnt lgkmcnt(2)
	v_fmac_f32_dpp v79, v240, v68 quad_perm:[0,0,0,0] row_mask:0xf bank_mask:0xf
	v_fmac_f32_dpp v96, v240, v69 quad_perm:[1,1,1,1] row_mask:0xf bank_mask:0xf
	v_fmac_f32_dpp v97, v240, v70 quad_perm:[2,2,2,2] row_mask:0xf bank_mask:0xf
	v_fmac_f32_dpp v98, v240, v71 quad_perm:[3,3,3,3] row_mask:0xf bank_mask:0xf
	s_waitcnt lgkmcnt(1)
	v_fmac_f32_dpp v79, v241, v72 quad_perm:[0,0,0,0] row_mask:0xf bank_mask:0xf
	v_fmac_f32_dpp v96, v241, v73 quad_perm:[1,1,1,1] row_mask:0xf bank_mask:0xf
	v_fmac_f32_dpp v97, v241, v74 quad_perm:[2,2,2,2] row_mask:0xf bank_mask:0xf
	v_fmac_f32_dpp v98, v241, v75 quad_perm:[3,3,3,3] row_mask:0xf bank_mask:0xf
	s_waitcnt lgkmcnt(0)
	v_fmac_f32_dpp v79, v242, v76 quad_perm:[0,0,0,0] row_mask:0xf bank_mask:0xf
	v_fmac_f32_dpp v96, v242, v77 quad_perm:[1,1,1,1] row_mask:0xf bank_mask:0xf
	ds_read_b32 v240, v255 offset:15104
	ds_read_b32 v241, v255 offset:15120
	ds_read_b32 v242, v255 offset:15136
	ds_read_b32 v243, v255 offset:15152
	ds_read_b32 v244, v255 offset:15168
	ds_read_b32 v245, v255 offset:15184
	ds_read_b32 v246, v255 offset:15200
	ds_read_b32 v247, v255 offset:15216
	ds_read_b32 v248, v255 offset:15232
	ds_read_b32 v249, v255 offset:15248
	ds_read_b32 v250, v255 offset:15264
	ds_read_b32 v251, v255 offset:15280
	v_add_f32_e32 v79, v79, v96
	v_add_f32_e32 v80, v97, v98
	v_add_f32_e32 v79, v80, v79
	v_sub_f32_e32 v78, v78, v79
	v_lshlrev_b32_e32 v79, 16, v238
	v_mul_f32_e32 v79, v239, v79
	s_cmp_eq_u64 s[16:17], 0
	s_cbranch_scc1 .LBB0_923
	v_mul_f32_e32 v79, v79, v254
.LBB0_923:
	ds_read_u16 v238, v18 offset:16320
	ds_read_b32 v239, v16 offset:240
	ds_read_b32 v254, v15 offset:240
	s_waitcnt lgkmcnt(14)
	v_mul_f32_dpp v96, v240, v2 quad_perm:[0,0,0,0] row_mask:0xf bank_mask:0xf
	v_mul_f32_dpp v97, v240, v3 quad_perm:[1,1,1,1] row_mask:0xf bank_mask:0xf
	v_mul_f32_dpp v98, v240, v4 quad_perm:[2,2,2,2] row_mask:0xf bank_mask:0xf
	v_mul_f32_dpp v99, v240, v5 quad_perm:[3,3,3,3] row_mask:0xf bank_mask:0xf
	ds_read_b32 v240, v255 offset:15296
	s_waitcnt lgkmcnt(14)
	v_fmac_f32_dpp v96, v241, v6 quad_perm:[0,0,0,0] row_mask:0xf bank_mask:0xf
	v_fmac_f32_dpp v97, v241, v7 quad_perm:[1,1,1,1] row_mask:0xf bank_mask:0xf
	v_fmac_f32_dpp v98, v241, v8 quad_perm:[2,2,2,2] row_mask:0xf bank_mask:0xf
	v_fmac_f32_dpp v99, v241, v9 quad_perm:[3,3,3,3] row_mask:0xf bank_mask:0xf
	ds_read_b32 v241, v255 offset:15312
	s_waitcnt lgkmcnt(14)
	v_fmac_f32_dpp v96, v242, v10 quad_perm:[0,0,0,0] row_mask:0xf bank_mask:0xf
	v_fmac_f32_dpp v97, v242, v12 quad_perm:[1,1,1,1] row_mask:0xf bank_mask:0xf
	v_fmac_f32_dpp v98, v242, v13 quad_perm:[2,2,2,2] row_mask:0xf bank_mask:0xf
	v_fmac_f32_dpp v99, v242, v14 quad_perm:[3,3,3,3] row_mask:0xf bank_mask:0xf
	ds_read_b32 v242, v255 offset:15328
	s_waitcnt lgkmcnt(14)
	v_fmac_f32_dpp v96, v243, v17 quad_perm:[0,0,0,0] row_mask:0xf bank_mask:0xf
	v_fmac_f32_dpp v97, v243, v19 quad_perm:[1,1,1,1] row_mask:0xf bank_mask:0xf
	v_fmac_f32_dpp v98, v243, v28 quad_perm:[2,2,2,2] row_mask:0xf bank_mask:0xf
	v_fmac_f32_dpp v99, v243, v35 quad_perm:[3,3,3,3] row_mask:0xf bank_mask:0xf
	s_waitcnt lgkmcnt(13)
	v_fmac_f32_dpp v96, v244, v36 quad_perm:[0,0,0,0] row_mask:0xf bank_mask:0xf
	v_fmac_f32_dpp v97, v244, v37 quad_perm:[1,1,1,1] row_mask:0xf bank_mask:0xf
	v_fmac_f32_dpp v98, v244, v38 quad_perm:[2,2,2,2] row_mask:0xf bank_mask:0xf
	v_fmac_f32_dpp v99, v244, v39 quad_perm:[3,3,3,3] row_mask:0xf bank_mask:0xf
	s_waitcnt lgkmcnt(12)
	v_fmac_f32_dpp v96, v245, v40 quad_perm:[0,0,0,0] row_mask:0xf bank_mask:0xf
	v_fmac_f32_dpp v97, v245, v41 quad_perm:[1,1,1,1] row_mask:0xf bank_mask:0xf
	v_fmac_f32_dpp v98, v245, v42 quad_perm:[2,2,2,2] row_mask:0xf bank_mask:0xf
	v_fmac_f32_dpp v99, v245, v43 quad_perm:[3,3,3,3] row_mask:0xf bank_mask:0xf
	s_waitcnt lgkmcnt(11)
	v_fmac_f32_dpp v96, v246, v44 quad_perm:[0,0,0,0] row_mask:0xf bank_mask:0xf
	v_fmac_f32_dpp v97, v246, v45 quad_perm:[1,1,1,1] row_mask:0xf bank_mask:0xf
	v_fmac_f32_dpp v98, v246, v46 quad_perm:[2,2,2,2] row_mask:0xf bank_mask:0xf
	v_fmac_f32_dpp v99, v246, v47 quad_perm:[3,3,3,3] row_mask:0xf bank_mask:0xf
	s_waitcnt lgkmcnt(10)
	v_fmac_f32_dpp v96, v247, v48 quad_perm:[0,0,0,0] row_mask:0xf bank_mask:0xf
	v_fmac_f32_dpp v97, v247, v49 quad_perm:[1,1,1,1] row_mask:0xf bank_mask:0xf
	v_fmac_f32_dpp v98, v247, v50 quad_perm:[2,2,2,2] row_mask:0xf bank_mask:0xf
	v_fmac_f32_dpp v99, v247, v51 quad_perm:[3,3,3,3] row_mask:0xf bank_mask:0xf
	s_waitcnt lgkmcnt(9)
	v_fmac_f32_dpp v96, v248, v52 quad_perm:[0,0,0,0] row_mask:0xf bank_mask:0xf
	v_fmac_f32_dpp v97, v248, v53 quad_perm:[1,1,1,1] row_mask:0xf bank_mask:0xf
	v_fmac_f32_dpp v98, v248, v54 quad_perm:[2,2,2,2] row_mask:0xf bank_mask:0xf
	v_fmac_f32_dpp v99, v248, v55 quad_perm:[3,3,3,3] row_mask:0xf bank_mask:0xf
	s_waitcnt lgkmcnt(8)
	v_fmac_f32_dpp v96, v249, v56 quad_perm:[0,0,0,0] row_mask:0xf bank_mask:0xf
	v_fmac_f32_dpp v97, v249, v57 quad_perm:[1,1,1,1] row_mask:0xf bank_mask:0xf
	v_fmac_f32_dpp v98, v249, v58 quad_perm:[2,2,2,2] row_mask:0xf bank_mask:0xf
	v_fmac_f32_dpp v99, v249, v59 quad_perm:[3,3,3,3] row_mask:0xf bank_mask:0xf
	s_waitcnt lgkmcnt(7)
	v_fmac_f32_dpp v96, v250, v60 quad_perm:[0,0,0,0] row_mask:0xf bank_mask:0xf
	v_fmac_f32_dpp v97, v250, v61 quad_perm:[1,1,1,1] row_mask:0xf bank_mask:0xf
	v_fmac_f32_dpp v98, v250, v62 quad_perm:[2,2,2,2] row_mask:0xf bank_mask:0xf
	v_fmac_f32_dpp v99, v250, v63 quad_perm:[3,3,3,3] row_mask:0xf bank_mask:0xf
	s_waitcnt lgkmcnt(6)
	v_fmac_f32_dpp v96, v251, v64 quad_perm:[0,0,0,0] row_mask:0xf bank_mask:0xf
	v_fmac_f32_dpp v97, v251, v65 quad_perm:[1,1,1,1] row_mask:0xf bank_mask:0xf
	v_fmac_f32_dpp v98, v251, v66 quad_perm:[2,2,2,2] row_mask:0xf bank_mask:0xf
	v_fmac_f32_dpp v99, v251, v67 quad_perm:[3,3,3,3] row_mask:0xf bank_mask:0xf
	s_waitcnt lgkmcnt(2)
	v_fmac_f32_dpp v96, v240, v68 quad_perm:[0,0,0,0] row_mask:0xf bank_mask:0xf
	v_fmac_f32_dpp v97, v240, v69 quad_perm:[1,1,1,1] row_mask:0xf bank_mask:0xf
	v_fmac_f32_dpp v98, v240, v70 quad_perm:[2,2,2,2] row_mask:0xf bank_mask:0xf
	v_fmac_f32_dpp v99, v240, v71 quad_perm:[3,3,3,3] row_mask:0xf bank_mask:0xf
	s_waitcnt lgkmcnt(1)
	v_fmac_f32_dpp v96, v241, v72 quad_perm:[0,0,0,0] row_mask:0xf bank_mask:0xf
	v_fmac_f32_dpp v97, v241, v73 quad_perm:[1,1,1,1] row_mask:0xf bank_mask:0xf
	v_fmac_f32_dpp v98, v241, v74 quad_perm:[2,2,2,2] row_mask:0xf bank_mask:0xf
	v_fmac_f32_dpp v99, v241, v75 quad_perm:[3,3,3,3] row_mask:0xf bank_mask:0xf
	s_waitcnt lgkmcnt(0)
	v_fmac_f32_dpp v96, v242, v76 quad_perm:[0,0,0,0] row_mask:0xf bank_mask:0xf
	v_fmac_f32_dpp v97, v242, v77 quad_perm:[1,1,1,1] row_mask:0xf bank_mask:0xf
	v_fmac_f32_dpp v98, v242, v78 quad_perm:[2,2,2,2] row_mask:0xf bank_mask:0xf
	ds_read_b32 v240, v255 offset:15360
	ds_read_b32 v241, v255 offset:15376
	ds_read_b32 v242, v255 offset:15392
	ds_read_b32 v243, v255 offset:15408
	ds_read_b32 v244, v255 offset:15424
	ds_read_b32 v245, v255 offset:15440
	ds_read_b32 v246, v255 offset:15456
	ds_read_b32 v247, v255 offset:15472
	ds_read_b32 v248, v255 offset:15488
	ds_read_b32 v249, v255 offset:15504
	ds_read_b32 v250, v255 offset:15520
	ds_read_b32 v251, v255 offset:15536
	v_add_f32_e32 v80, v96, v97
	v_add_f32_e32 v81, v99, v98
	v_add_f32_e32 v80, v80, v81
	v_sub_f32_e32 v79, v79, v80
	v_lshlrev_b32_e32 v80, 16, v238
	v_mul_f32_e32 v80, v239, v80
	s_cmp_eq_u64 s[16:17], 0
	s_cbranch_scc1 .LBB0_925
	v_mul_f32_e32 v80, v80, v254
.LBB0_925:
	ds_read_u16 v238, v18 offset:16592
	ds_read_b32 v239, v16 offset:244
	ds_read_b32 v254, v15 offset:244
	s_waitcnt lgkmcnt(14)
	v_mul_f32_dpp v81, v240, v2 quad_perm:[0,0,0,0] row_mask:0xf bank_mask:0xf
	v_mul_f32_dpp v98, v240, v3 quad_perm:[1,1,1,1] row_mask:0xf bank_mask:0xf
	v_mul_f32_dpp v99, v240, v4 quad_perm:[2,2,2,2] row_mask:0xf bank_mask:0xf
	v_mul_f32_dpp v100, v240, v5 quad_perm:[3,3,3,3] row_mask:0xf bank_mask:0xf
	ds_read_b32 v240, v255 offset:15552
	s_waitcnt lgkmcnt(14)
	v_fmac_f32_dpp v81, v241, v6 quad_perm:[0,0,0,0] row_mask:0xf bank_mask:0xf
	v_fmac_f32_dpp v98, v241, v7 quad_perm:[1,1,1,1] row_mask:0xf bank_mask:0xf
	v_fmac_f32_dpp v99, v241, v8 quad_perm:[2,2,2,2] row_mask:0xf bank_mask:0xf
	v_fmac_f32_dpp v100, v241, v9 quad_perm:[3,3,3,3] row_mask:0xf bank_mask:0xf
	ds_read_b32 v241, v255 offset:15568
	s_waitcnt lgkmcnt(14)
	v_fmac_f32_dpp v81, v242, v10 quad_perm:[0,0,0,0] row_mask:0xf bank_mask:0xf
	v_fmac_f32_dpp v98, v242, v12 quad_perm:[1,1,1,1] row_mask:0xf bank_mask:0xf
	v_fmac_f32_dpp v99, v242, v13 quad_perm:[2,2,2,2] row_mask:0xf bank_mask:0xf
	v_fmac_f32_dpp v100, v242, v14 quad_perm:[3,3,3,3] row_mask:0xf bank_mask:0xf
	ds_read_b32 v242, v255 offset:15584
	s_waitcnt lgkmcnt(14)
	v_fmac_f32_dpp v81, v243, v17 quad_perm:[0,0,0,0] row_mask:0xf bank_mask:0xf
	v_fmac_f32_dpp v98, v243, v19 quad_perm:[1,1,1,1] row_mask:0xf bank_mask:0xf
	v_fmac_f32_dpp v99, v243, v28 quad_perm:[2,2,2,2] row_mask:0xf bank_mask:0xf
	v_fmac_f32_dpp v100, v243, v35 quad_perm:[3,3,3,3] row_mask:0xf bank_mask:0xf
	s_waitcnt lgkmcnt(13)
	v_fmac_f32_dpp v81, v244, v36 quad_perm:[0,0,0,0] row_mask:0xf bank_mask:0xf
	v_fmac_f32_dpp v98, v244, v37 quad_perm:[1,1,1,1] row_mask:0xf bank_mask:0xf
	v_fmac_f32_dpp v99, v244, v38 quad_perm:[2,2,2,2] row_mask:0xf bank_mask:0xf
	v_fmac_f32_dpp v100, v244, v39 quad_perm:[3,3,3,3] row_mask:0xf bank_mask:0xf
	s_waitcnt lgkmcnt(12)
	v_fmac_f32_dpp v81, v245, v40 quad_perm:[0,0,0,0] row_mask:0xf bank_mask:0xf
	v_fmac_f32_dpp v98, v245, v41 quad_perm:[1,1,1,1] row_mask:0xf bank_mask:0xf
	v_fmac_f32_dpp v99, v245, v42 quad_perm:[2,2,2,2] row_mask:0xf bank_mask:0xf
	v_fmac_f32_dpp v100, v245, v43 quad_perm:[3,3,3,3] row_mask:0xf bank_mask:0xf
	s_waitcnt lgkmcnt(11)
	v_fmac_f32_dpp v81, v246, v44 quad_perm:[0,0,0,0] row_mask:0xf bank_mask:0xf
	v_fmac_f32_dpp v98, v246, v45 quad_perm:[1,1,1,1] row_mask:0xf bank_mask:0xf
	v_fmac_f32_dpp v99, v246, v46 quad_perm:[2,2,2,2] row_mask:0xf bank_mask:0xf
	v_fmac_f32_dpp v100, v246, v47 quad_perm:[3,3,3,3] row_mask:0xf bank_mask:0xf
	s_waitcnt lgkmcnt(10)
	v_fmac_f32_dpp v81, v247, v48 quad_perm:[0,0,0,0] row_mask:0xf bank_mask:0xf
	v_fmac_f32_dpp v98, v247, v49 quad_perm:[1,1,1,1] row_mask:0xf bank_mask:0xf
	v_fmac_f32_dpp v99, v247, v50 quad_perm:[2,2,2,2] row_mask:0xf bank_mask:0xf
	v_fmac_f32_dpp v100, v247, v51 quad_perm:[3,3,3,3] row_mask:0xf bank_mask:0xf
	s_waitcnt lgkmcnt(9)
	v_fmac_f32_dpp v81, v248, v52 quad_perm:[0,0,0,0] row_mask:0xf bank_mask:0xf
	v_fmac_f32_dpp v98, v248, v53 quad_perm:[1,1,1,1] row_mask:0xf bank_mask:0xf
	v_fmac_f32_dpp v99, v248, v54 quad_perm:[2,2,2,2] row_mask:0xf bank_mask:0xf
	v_fmac_f32_dpp v100, v248, v55 quad_perm:[3,3,3,3] row_mask:0xf bank_mask:0xf
	s_waitcnt lgkmcnt(8)
	v_fmac_f32_dpp v81, v249, v56 quad_perm:[0,0,0,0] row_mask:0xf bank_mask:0xf
	v_fmac_f32_dpp v98, v249, v57 quad_perm:[1,1,1,1] row_mask:0xf bank_mask:0xf
	v_fmac_f32_dpp v99, v249, v58 quad_perm:[2,2,2,2] row_mask:0xf bank_mask:0xf
	v_fmac_f32_dpp v100, v249, v59 quad_perm:[3,3,3,3] row_mask:0xf bank_mask:0xf
	s_waitcnt lgkmcnt(7)
	v_fmac_f32_dpp v81, v250, v60 quad_perm:[0,0,0,0] row_mask:0xf bank_mask:0xf
	v_fmac_f32_dpp v98, v250, v61 quad_perm:[1,1,1,1] row_mask:0xf bank_mask:0xf
	v_fmac_f32_dpp v99, v250, v62 quad_perm:[2,2,2,2] row_mask:0xf bank_mask:0xf
	v_fmac_f32_dpp v100, v250, v63 quad_perm:[3,3,3,3] row_mask:0xf bank_mask:0xf
	s_waitcnt lgkmcnt(6)
	v_fmac_f32_dpp v81, v251, v64 quad_perm:[0,0,0,0] row_mask:0xf bank_mask:0xf
	v_fmac_f32_dpp v98, v251, v65 quad_perm:[1,1,1,1] row_mask:0xf bank_mask:0xf
	v_fmac_f32_dpp v99, v251, v66 quad_perm:[2,2,2,2] row_mask:0xf bank_mask:0xf
	v_fmac_f32_dpp v100, v251, v67 quad_perm:[3,3,3,3] row_mask:0xf bank_mask:0xf
	s_waitcnt lgkmcnt(2)
	v_fmac_f32_dpp v81, v240, v68 quad_perm:[0,0,0,0] row_mask:0xf bank_mask:0xf
	v_fmac_f32_dpp v98, v240, v69 quad_perm:[1,1,1,1] row_mask:0xf bank_mask:0xf
	v_fmac_f32_dpp v99, v240, v70 quad_perm:[2,2,2,2] row_mask:0xf bank_mask:0xf
	v_fmac_f32_dpp v100, v240, v71 quad_perm:[3,3,3,3] row_mask:0xf bank_mask:0xf
	s_waitcnt lgkmcnt(1)
	v_fmac_f32_dpp v81, v241, v72 quad_perm:[0,0,0,0] row_mask:0xf bank_mask:0xf
	v_fmac_f32_dpp v98, v241, v73 quad_perm:[1,1,1,1] row_mask:0xf bank_mask:0xf
	v_fmac_f32_dpp v99, v241, v74 quad_perm:[2,2,2,2] row_mask:0xf bank_mask:0xf
	v_fmac_f32_dpp v100, v241, v75 quad_perm:[3,3,3,3] row_mask:0xf bank_mask:0xf
	s_waitcnt lgkmcnt(0)
	v_fmac_f32_dpp v81, v242, v76 quad_perm:[0,0,0,0] row_mask:0xf bank_mask:0xf
	v_fmac_f32_dpp v98, v242, v77 quad_perm:[1,1,1,1] row_mask:0xf bank_mask:0xf
	v_fmac_f32_dpp v99, v242, v78 quad_perm:[2,2,2,2] row_mask:0xf bank_mask:0xf
	v_fmac_f32_dpp v100, v242, v79 quad_perm:[3,3,3,3] row_mask:0xf bank_mask:0xf
	ds_read_b32 v240, v255 offset:15616
	ds_read_b32 v241, v255 offset:15632
	ds_read_b32 v242, v255 offset:15648
	ds_read_b32 v243, v255 offset:15664
	ds_read_b32 v244, v255 offset:15680
	ds_read_b32 v245, v255 offset:15696
	ds_read_b32 v246, v255 offset:15712
	ds_read_b32 v247, v255 offset:15728
	ds_read_b32 v248, v255 offset:15744
	ds_read_b32 v249, v255 offset:15760
	ds_read_b32 v250, v255 offset:15776
	ds_read_b32 v251, v255 offset:15792
	v_add_f32_e32 v81, v81, v98
	v_add_f32_e32 v82, v99, v100
	v_add_f32_e32 v81, v81, v82
	v_sub_f32_e32 v80, v80, v81
	v_lshlrev_b32_e32 v81, 16, v238
	v_mul_f32_e32 v81, v239, v81
	s_cmp_eq_u64 s[16:17], 0
	s_cbranch_scc1 .LBB0_927
	v_mul_f32_e32 v81, v81, v254
.LBB0_927:
	ds_read_u16 v238, v18 offset:16864
	ds_read_b32 v239, v16 offset:248
	ds_read_b32 v254, v15 offset:248
	s_waitcnt lgkmcnt(14)
	v_mul_f32_dpp v98, v240, v2 quad_perm:[0,0,0,0] row_mask:0xf bank_mask:0xf
	v_mul_f32_dpp v99, v240, v3 quad_perm:[1,1,1,1] row_mask:0xf bank_mask:0xf
	v_mul_f32_dpp v100, v240, v4 quad_perm:[2,2,2,2] row_mask:0xf bank_mask:0xf
	v_mul_f32_dpp v101, v240, v5 quad_perm:[3,3,3,3] row_mask:0xf bank_mask:0xf
	ds_read_b32 v240, v255 offset:15808
	s_waitcnt lgkmcnt(14)
	v_fmac_f32_dpp v98, v241, v6 quad_perm:[0,0,0,0] row_mask:0xf bank_mask:0xf
	v_fmac_f32_dpp v99, v241, v7 quad_perm:[1,1,1,1] row_mask:0xf bank_mask:0xf
	v_fmac_f32_dpp v100, v241, v8 quad_perm:[2,2,2,2] row_mask:0xf bank_mask:0xf
	v_fmac_f32_dpp v101, v241, v9 quad_perm:[3,3,3,3] row_mask:0xf bank_mask:0xf
	ds_read_b32 v241, v255 offset:15824
	s_waitcnt lgkmcnt(14)
	v_fmac_f32_dpp v98, v242, v10 quad_perm:[0,0,0,0] row_mask:0xf bank_mask:0xf
	v_fmac_f32_dpp v99, v242, v12 quad_perm:[1,1,1,1] row_mask:0xf bank_mask:0xf
	v_fmac_f32_dpp v100, v242, v13 quad_perm:[2,2,2,2] row_mask:0xf bank_mask:0xf
	v_fmac_f32_dpp v101, v242, v14 quad_perm:[3,3,3,3] row_mask:0xf bank_mask:0xf
	ds_read_b32 v242, v255 offset:15840
	s_waitcnt lgkmcnt(14)
	v_fmac_f32_dpp v98, v243, v17 quad_perm:[0,0,0,0] row_mask:0xf bank_mask:0xf
	v_fmac_f32_dpp v99, v243, v19 quad_perm:[1,1,1,1] row_mask:0xf bank_mask:0xf
	v_fmac_f32_dpp v100, v243, v28 quad_perm:[2,2,2,2] row_mask:0xf bank_mask:0xf
	v_fmac_f32_dpp v101, v243, v35 quad_perm:[3,3,3,3] row_mask:0xf bank_mask:0xf
	ds_read_b32 v243, v255 offset:15856
	s_waitcnt lgkmcnt(14)
	v_fmac_f32_dpp v98, v244, v36 quad_perm:[0,0,0,0] row_mask:0xf bank_mask:0xf
	v_fmac_f32_dpp v99, v244, v37 quad_perm:[1,1,1,1] row_mask:0xf bank_mask:0xf
	v_fmac_f32_dpp v100, v244, v38 quad_perm:[2,2,2,2] row_mask:0xf bank_mask:0xf
	v_fmac_f32_dpp v101, v244, v39 quad_perm:[3,3,3,3] row_mask:0xf bank_mask:0xf
	s_waitcnt lgkmcnt(13)
	v_fmac_f32_dpp v98, v245, v40 quad_perm:[0,0,0,0] row_mask:0xf bank_mask:0xf
	v_fmac_f32_dpp v99, v245, v41 quad_perm:[1,1,1,1] row_mask:0xf bank_mask:0xf
	v_fmac_f32_dpp v100, v245, v42 quad_perm:[2,2,2,2] row_mask:0xf bank_mask:0xf
	v_fmac_f32_dpp v101, v245, v43 quad_perm:[3,3,3,3] row_mask:0xf bank_mask:0xf
	s_waitcnt lgkmcnt(12)
	v_fmac_f32_dpp v98, v246, v44 quad_perm:[0,0,0,0] row_mask:0xf bank_mask:0xf
	v_fmac_f32_dpp v99, v246, v45 quad_perm:[1,1,1,1] row_mask:0xf bank_mask:0xf
	v_fmac_f32_dpp v100, v246, v46 quad_perm:[2,2,2,2] row_mask:0xf bank_mask:0xf
	v_fmac_f32_dpp v101, v246, v47 quad_perm:[3,3,3,3] row_mask:0xf bank_mask:0xf
	s_waitcnt lgkmcnt(11)
	v_fmac_f32_dpp v98, v247, v48 quad_perm:[0,0,0,0] row_mask:0xf bank_mask:0xf
	v_fmac_f32_dpp v99, v247, v49 quad_perm:[1,1,1,1] row_mask:0xf bank_mask:0xf
	v_fmac_f32_dpp v100, v247, v50 quad_perm:[2,2,2,2] row_mask:0xf bank_mask:0xf
	v_fmac_f32_dpp v101, v247, v51 quad_perm:[3,3,3,3] row_mask:0xf bank_mask:0xf
	s_waitcnt lgkmcnt(10)
	v_fmac_f32_dpp v98, v248, v52 quad_perm:[0,0,0,0] row_mask:0xf bank_mask:0xf
	v_fmac_f32_dpp v99, v248, v53 quad_perm:[1,1,1,1] row_mask:0xf bank_mask:0xf
	v_fmac_f32_dpp v100, v248, v54 quad_perm:[2,2,2,2] row_mask:0xf bank_mask:0xf
	v_fmac_f32_dpp v101, v248, v55 quad_perm:[3,3,3,3] row_mask:0xf bank_mask:0xf
	s_waitcnt lgkmcnt(9)
	v_fmac_f32_dpp v98, v249, v56 quad_perm:[0,0,0,0] row_mask:0xf bank_mask:0xf
	v_fmac_f32_dpp v99, v249, v57 quad_perm:[1,1,1,1] row_mask:0xf bank_mask:0xf
	v_fmac_f32_dpp v100, v249, v58 quad_perm:[2,2,2,2] row_mask:0xf bank_mask:0xf
	v_fmac_f32_dpp v101, v249, v59 quad_perm:[3,3,3,3] row_mask:0xf bank_mask:0xf
	s_waitcnt lgkmcnt(8)
	v_fmac_f32_dpp v98, v250, v60 quad_perm:[0,0,0,0] row_mask:0xf bank_mask:0xf
	v_fmac_f32_dpp v99, v250, v61 quad_perm:[1,1,1,1] row_mask:0xf bank_mask:0xf
	v_fmac_f32_dpp v100, v250, v62 quad_perm:[2,2,2,2] row_mask:0xf bank_mask:0xf
	v_fmac_f32_dpp v101, v250, v63 quad_perm:[3,3,3,3] row_mask:0xf bank_mask:0xf
	s_waitcnt lgkmcnt(7)
	v_fmac_f32_dpp v98, v251, v64 quad_perm:[0,0,0,0] row_mask:0xf bank_mask:0xf
	v_fmac_f32_dpp v99, v251, v65 quad_perm:[1,1,1,1] row_mask:0xf bank_mask:0xf
	v_fmac_f32_dpp v100, v251, v66 quad_perm:[2,2,2,2] row_mask:0xf bank_mask:0xf
	v_fmac_f32_dpp v101, v251, v67 quad_perm:[3,3,3,3] row_mask:0xf bank_mask:0xf
	s_waitcnt lgkmcnt(3)
	v_fmac_f32_dpp v98, v240, v68 quad_perm:[0,0,0,0] row_mask:0xf bank_mask:0xf
	v_fmac_f32_dpp v99, v240, v69 quad_perm:[1,1,1,1] row_mask:0xf bank_mask:0xf
	v_fmac_f32_dpp v100, v240, v70 quad_perm:[2,2,2,2] row_mask:0xf bank_mask:0xf
	v_fmac_f32_dpp v101, v240, v71 quad_perm:[3,3,3,3] row_mask:0xf bank_mask:0xf
	s_waitcnt lgkmcnt(2)
	v_fmac_f32_dpp v98, v241, v72 quad_perm:[0,0,0,0] row_mask:0xf bank_mask:0xf
	v_fmac_f32_dpp v99, v241, v73 quad_perm:[1,1,1,1] row_mask:0xf bank_mask:0xf
	v_fmac_f32_dpp v100, v241, v74 quad_perm:[2,2,2,2] row_mask:0xf bank_mask:0xf
	v_fmac_f32_dpp v101, v241, v75 quad_perm:[3,3,3,3] row_mask:0xf bank_mask:0xf
	s_waitcnt lgkmcnt(1)
	v_fmac_f32_dpp v98, v242, v76 quad_perm:[0,0,0,0] row_mask:0xf bank_mask:0xf
	v_fmac_f32_dpp v99, v242, v77 quad_perm:[1,1,1,1] row_mask:0xf bank_mask:0xf
	v_fmac_f32_dpp v100, v242, v78 quad_perm:[2,2,2,2] row_mask:0xf bank_mask:0xf
	v_fmac_f32_dpp v101, v242, v79 quad_perm:[3,3,3,3] row_mask:0xf bank_mask:0xf
	s_waitcnt lgkmcnt(0)
	v_fmac_f32_dpp v98, v243, v80 quad_perm:[0,0,0,0] row_mask:0xf bank_mask:0xf
	ds_read_b32 v240, v255 offset:15872
	ds_read_b32 v241, v255 offset:15888
	ds_read_b32 v242, v255 offset:15904
	ds_read_b32 v243, v255 offset:15920
	ds_read_b32 v244, v255 offset:15936
	ds_read_b32 v245, v255 offset:15952
	ds_read_b32 v246, v255 offset:15968
	ds_read_b32 v247, v255 offset:15984
	ds_read_b32 v248, v255 offset:16000
	ds_read_b32 v249, v255 offset:16016
	ds_read_b32 v250, v255 offset:16032
	ds_read_b32 v251, v255 offset:16048
	v_add_f32_e32 v82, v99, v98
	v_add_f32_e32 v83, v100, v101
	v_add_f32_e32 v82, v83, v82
	v_sub_f32_e32 v81, v81, v82
	v_lshlrev_b32_e32 v82, 16, v238
	v_mul_f32_e32 v82, v239, v82
	s_cmp_eq_u64 s[16:17], 0
	s_cbranch_scc1 .LBB0_929
	v_mul_f32_e32 v82, v82, v254
.LBB0_929:
	ds_read_u16 v238, v18 offset:17136
	ds_read_b32 v239, v16 offset:252
	ds_read_b32 v254, v15 offset:252
	s_waitcnt lgkmcnt(14)
	v_mul_f32_dpp v83, v240, v2 quad_perm:[0,0,0,0] row_mask:0xf bank_mask:0xf
	v_mul_f32_dpp v100, v240, v3 quad_perm:[1,1,1,1] row_mask:0xf bank_mask:0xf
	v_mul_f32_dpp v101, v240, v4 quad_perm:[2,2,2,2] row_mask:0xf bank_mask:0xf
	v_mul_f32_dpp v102, v240, v5 quad_perm:[3,3,3,3] row_mask:0xf bank_mask:0xf
	ds_read_b32 v240, v255 offset:16064
	s_waitcnt lgkmcnt(14)
	v_fmac_f32_dpp v83, v241, v6 quad_perm:[0,0,0,0] row_mask:0xf bank_mask:0xf
	v_fmac_f32_dpp v100, v241, v7 quad_perm:[1,1,1,1] row_mask:0xf bank_mask:0xf
	v_fmac_f32_dpp v101, v241, v8 quad_perm:[2,2,2,2] row_mask:0xf bank_mask:0xf
	v_fmac_f32_dpp v102, v241, v9 quad_perm:[3,3,3,3] row_mask:0xf bank_mask:0xf
	ds_read_b32 v241, v255 offset:16080
	s_waitcnt lgkmcnt(14)
	v_fmac_f32_dpp v83, v242, v10 quad_perm:[0,0,0,0] row_mask:0xf bank_mask:0xf
	v_fmac_f32_dpp v100, v242, v12 quad_perm:[1,1,1,1] row_mask:0xf bank_mask:0xf
	v_fmac_f32_dpp v101, v242, v13 quad_perm:[2,2,2,2] row_mask:0xf bank_mask:0xf
	v_fmac_f32_dpp v102, v242, v14 quad_perm:[3,3,3,3] row_mask:0xf bank_mask:0xf
	ds_read_b32 v242, v255 offset:16096
	s_waitcnt lgkmcnt(14)
	v_fmac_f32_dpp v83, v243, v17 quad_perm:[0,0,0,0] row_mask:0xf bank_mask:0xf
	v_fmac_f32_dpp v100, v243, v19 quad_perm:[1,1,1,1] row_mask:0xf bank_mask:0xf
	v_fmac_f32_dpp v101, v243, v28 quad_perm:[2,2,2,2] row_mask:0xf bank_mask:0xf
	v_fmac_f32_dpp v102, v243, v35 quad_perm:[3,3,3,3] row_mask:0xf bank_mask:0xf
	ds_read_b32 v243, v255 offset:16112
	s_waitcnt lgkmcnt(14)
	v_fmac_f32_dpp v83, v244, v36 quad_perm:[0,0,0,0] row_mask:0xf bank_mask:0xf
	v_fmac_f32_dpp v100, v244, v37 quad_perm:[1,1,1,1] row_mask:0xf bank_mask:0xf
	v_fmac_f32_dpp v101, v244, v38 quad_perm:[2,2,2,2] row_mask:0xf bank_mask:0xf
	v_fmac_f32_dpp v102, v244, v39 quad_perm:[3,3,3,3] row_mask:0xf bank_mask:0xf
	s_waitcnt lgkmcnt(13)
	v_fmac_f32_dpp v83, v245, v40 quad_perm:[0,0,0,0] row_mask:0xf bank_mask:0xf
	v_fmac_f32_dpp v100, v245, v41 quad_perm:[1,1,1,1] row_mask:0xf bank_mask:0xf
	v_fmac_f32_dpp v101, v245, v42 quad_perm:[2,2,2,2] row_mask:0xf bank_mask:0xf
	v_fmac_f32_dpp v102, v245, v43 quad_perm:[3,3,3,3] row_mask:0xf bank_mask:0xf
	s_waitcnt lgkmcnt(12)
	v_fmac_f32_dpp v83, v246, v44 quad_perm:[0,0,0,0] row_mask:0xf bank_mask:0xf
	v_fmac_f32_dpp v100, v246, v45 quad_perm:[1,1,1,1] row_mask:0xf bank_mask:0xf
	v_fmac_f32_dpp v101, v246, v46 quad_perm:[2,2,2,2] row_mask:0xf bank_mask:0xf
	v_fmac_f32_dpp v102, v246, v47 quad_perm:[3,3,3,3] row_mask:0xf bank_mask:0xf
	s_waitcnt lgkmcnt(11)
	v_fmac_f32_dpp v83, v247, v48 quad_perm:[0,0,0,0] row_mask:0xf bank_mask:0xf
	v_fmac_f32_dpp v100, v247, v49 quad_perm:[1,1,1,1] row_mask:0xf bank_mask:0xf
	v_fmac_f32_dpp v101, v247, v50 quad_perm:[2,2,2,2] row_mask:0xf bank_mask:0xf
	v_fmac_f32_dpp v102, v247, v51 quad_perm:[3,3,3,3] row_mask:0xf bank_mask:0xf
	s_waitcnt lgkmcnt(10)
	v_fmac_f32_dpp v83, v248, v52 quad_perm:[0,0,0,0] row_mask:0xf bank_mask:0xf
	v_fmac_f32_dpp v100, v248, v53 quad_perm:[1,1,1,1] row_mask:0xf bank_mask:0xf
	v_fmac_f32_dpp v101, v248, v54 quad_perm:[2,2,2,2] row_mask:0xf bank_mask:0xf
	v_fmac_f32_dpp v102, v248, v55 quad_perm:[3,3,3,3] row_mask:0xf bank_mask:0xf
	s_waitcnt lgkmcnt(9)
	v_fmac_f32_dpp v83, v249, v56 quad_perm:[0,0,0,0] row_mask:0xf bank_mask:0xf
	v_fmac_f32_dpp v100, v249, v57 quad_perm:[1,1,1,1] row_mask:0xf bank_mask:0xf
	v_fmac_f32_dpp v101, v249, v58 quad_perm:[2,2,2,2] row_mask:0xf bank_mask:0xf
	v_fmac_f32_dpp v102, v249, v59 quad_perm:[3,3,3,3] row_mask:0xf bank_mask:0xf
	s_waitcnt lgkmcnt(8)
	v_fmac_f32_dpp v83, v250, v60 quad_perm:[0,0,0,0] row_mask:0xf bank_mask:0xf
	v_fmac_f32_dpp v100, v250, v61 quad_perm:[1,1,1,1] row_mask:0xf bank_mask:0xf
	v_fmac_f32_dpp v101, v250, v62 quad_perm:[2,2,2,2] row_mask:0xf bank_mask:0xf
	v_fmac_f32_dpp v102, v250, v63 quad_perm:[3,3,3,3] row_mask:0xf bank_mask:0xf
	s_waitcnt lgkmcnt(7)
	v_fmac_f32_dpp v83, v251, v64 quad_perm:[0,0,0,0] row_mask:0xf bank_mask:0xf
	v_fmac_f32_dpp v100, v251, v65 quad_perm:[1,1,1,1] row_mask:0xf bank_mask:0xf
	v_fmac_f32_dpp v101, v251, v66 quad_perm:[2,2,2,2] row_mask:0xf bank_mask:0xf
	v_fmac_f32_dpp v102, v251, v67 quad_perm:[3,3,3,3] row_mask:0xf bank_mask:0xf
	s_waitcnt lgkmcnt(3)
	v_fmac_f32_dpp v83, v240, v68 quad_perm:[0,0,0,0] row_mask:0xf bank_mask:0xf
	v_fmac_f32_dpp v100, v240, v69 quad_perm:[1,1,1,1] row_mask:0xf bank_mask:0xf
	v_fmac_f32_dpp v101, v240, v70 quad_perm:[2,2,2,2] row_mask:0xf bank_mask:0xf
	v_fmac_f32_dpp v102, v240, v71 quad_perm:[3,3,3,3] row_mask:0xf bank_mask:0xf
	s_waitcnt lgkmcnt(2)
	v_fmac_f32_dpp v83, v241, v72 quad_perm:[0,0,0,0] row_mask:0xf bank_mask:0xf
	v_fmac_f32_dpp v100, v241, v73 quad_perm:[1,1,1,1] row_mask:0xf bank_mask:0xf
	v_fmac_f32_dpp v101, v241, v74 quad_perm:[2,2,2,2] row_mask:0xf bank_mask:0xf
	v_fmac_f32_dpp v102, v241, v75 quad_perm:[3,3,3,3] row_mask:0xf bank_mask:0xf
	s_waitcnt lgkmcnt(1)
	v_fmac_f32_dpp v83, v242, v76 quad_perm:[0,0,0,0] row_mask:0xf bank_mask:0xf
	v_fmac_f32_dpp v100, v242, v77 quad_perm:[1,1,1,1] row_mask:0xf bank_mask:0xf
	v_fmac_f32_dpp v101, v242, v78 quad_perm:[2,2,2,2] row_mask:0xf bank_mask:0xf
	v_fmac_f32_dpp v102, v242, v79 quad_perm:[3,3,3,3] row_mask:0xf bank_mask:0xf
	s_waitcnt lgkmcnt(0)
	v_fmac_f32_dpp v83, v243, v80 quad_perm:[0,0,0,0] row_mask:0xf bank_mask:0xf
	v_fmac_f32_dpp v100, v243, v81 quad_perm:[1,1,1,1] row_mask:0xf bank_mask:0xf
	ds_read_b32 v240, v255 offset:16128
	ds_read_b32 v241, v255 offset:16144
	ds_read_b32 v242, v255 offset:16160
	ds_read_b32 v243, v255 offset:16176
	ds_read_b32 v244, v255 offset:16192
	ds_read_b32 v245, v255 offset:16208
	ds_read_b32 v246, v255 offset:16224
	ds_read_b32 v247, v255 offset:16240
	ds_read_b32 v248, v255 offset:16256
	ds_read_b32 v249, v255 offset:16272
	ds_read_b32 v250, v255 offset:16288
	ds_read_b32 v251, v255 offset:16304
	v_add_f32_e32 v83, v83, v100
	v_add_f32_e32 v84, v101, v102
	v_add_f32_e32 v83, v84, v83
	v_sub_f32_e32 v82, v82, v83
	v_lshlrev_b32_e32 v18, 16, v238
	v_mul_f32_e32 v16, v239, v18
	s_cmp_eq_u64 s[16:17], 0
	s_cbranch_scc1 .LBB0_931
	v_mul_f32_e32 v16, v16, v254
.LBB0_931:
	s_waitcnt lgkmcnt(11)
	v_mul_f32_dpp v15, v240, v2 quad_perm:[0,0,0,0] row_mask:0xf bank_mask:0xf
	v_mul_f32_dpp v18, v240, v3 quad_perm:[1,1,1,1] row_mask:0xf bank_mask:0xf
	v_mul_f32_dpp v83, v240, v4 quad_perm:[2,2,2,2] row_mask:0xf bank_mask:0xf
	v_mul_f32_dpp v100, v240, v5 quad_perm:[3,3,3,3] row_mask:0xf bank_mask:0xf
	ds_read_b32 v240, v255 offset:16320
	s_waitcnt lgkmcnt(11)
	v_fmac_f32_dpp v15, v241, v6 quad_perm:[0,0,0,0] row_mask:0xf bank_mask:0xf
	v_fmac_f32_dpp v18, v241, v7 quad_perm:[1,1,1,1] row_mask:0xf bank_mask:0xf
	v_fmac_f32_dpp v83, v241, v8 quad_perm:[2,2,2,2] row_mask:0xf bank_mask:0xf
	v_fmac_f32_dpp v100, v241, v9 quad_perm:[3,3,3,3] row_mask:0xf bank_mask:0xf
	ds_read_b32 v241, v255 offset:16336
	s_waitcnt lgkmcnt(11)
	v_fmac_f32_dpp v15, v242, v10 quad_perm:[0,0,0,0] row_mask:0xf bank_mask:0xf
	v_fmac_f32_dpp v18, v242, v12 quad_perm:[1,1,1,1] row_mask:0xf bank_mask:0xf
	v_fmac_f32_dpp v83, v242, v13 quad_perm:[2,2,2,2] row_mask:0xf bank_mask:0xf
	v_fmac_f32_dpp v100, v242, v14 quad_perm:[3,3,3,3] row_mask:0xf bank_mask:0xf
	ds_read_b32 v242, v255 offset:16352
	s_waitcnt lgkmcnt(11)
	v_fmac_f32_dpp v15, v243, v17 quad_perm:[0,0,0,0] row_mask:0xf bank_mask:0xf
	v_fmac_f32_dpp v18, v243, v19 quad_perm:[1,1,1,1] row_mask:0xf bank_mask:0xf
	v_fmac_f32_dpp v83, v243, v28 quad_perm:[2,2,2,2] row_mask:0xf bank_mask:0xf
	v_fmac_f32_dpp v100, v243, v35 quad_perm:[3,3,3,3] row_mask:0xf bank_mask:0xf
	ds_read_b32 v243, v255 offset:16368
	s_waitcnt lgkmcnt(11)
	v_fmac_f32_dpp v15, v244, v36 quad_perm:[0,0,0,0] row_mask:0xf bank_mask:0xf
	v_fmac_f32_dpp v18, v244, v37 quad_perm:[1,1,1,1] row_mask:0xf bank_mask:0xf
	v_fmac_f32_dpp v83, v244, v38 quad_perm:[2,2,2,2] row_mask:0xf bank_mask:0xf
	v_fmac_f32_dpp v100, v244, v39 quad_perm:[3,3,3,3] row_mask:0xf bank_mask:0xf
	s_waitcnt lgkmcnt(10)
	v_fmac_f32_dpp v15, v245, v40 quad_perm:[0,0,0,0] row_mask:0xf bank_mask:0xf
	v_fmac_f32_dpp v18, v245, v41 quad_perm:[1,1,1,1] row_mask:0xf bank_mask:0xf
	v_fmac_f32_dpp v83, v245, v42 quad_perm:[2,2,2,2] row_mask:0xf bank_mask:0xf
	v_fmac_f32_dpp v100, v245, v43 quad_perm:[3,3,3,3] row_mask:0xf bank_mask:0xf
	s_waitcnt lgkmcnt(9)
	v_fmac_f32_dpp v15, v246, v44 quad_perm:[0,0,0,0] row_mask:0xf bank_mask:0xf
	v_fmac_f32_dpp v18, v246, v45 quad_perm:[1,1,1,1] row_mask:0xf bank_mask:0xf
	v_fmac_f32_dpp v83, v246, v46 quad_perm:[2,2,2,2] row_mask:0xf bank_mask:0xf
	v_fmac_f32_dpp v100, v246, v47 quad_perm:[3,3,3,3] row_mask:0xf bank_mask:0xf
	s_waitcnt lgkmcnt(8)
	v_fmac_f32_dpp v15, v247, v48 quad_perm:[0,0,0,0] row_mask:0xf bank_mask:0xf
	v_fmac_f32_dpp v18, v247, v49 quad_perm:[1,1,1,1] row_mask:0xf bank_mask:0xf
	v_fmac_f32_dpp v83, v247, v50 quad_perm:[2,2,2,2] row_mask:0xf bank_mask:0xf
	v_fmac_f32_dpp v100, v247, v51 quad_perm:[3,3,3,3] row_mask:0xf bank_mask:0xf
	s_waitcnt lgkmcnt(7)
	v_fmac_f32_dpp v15, v248, v52 quad_perm:[0,0,0,0] row_mask:0xf bank_mask:0xf
	v_fmac_f32_dpp v18, v248, v53 quad_perm:[1,1,1,1] row_mask:0xf bank_mask:0xf
	v_fmac_f32_dpp v83, v248, v54 quad_perm:[2,2,2,2] row_mask:0xf bank_mask:0xf
	v_fmac_f32_dpp v100, v248, v55 quad_perm:[3,3,3,3] row_mask:0xf bank_mask:0xf
	s_waitcnt lgkmcnt(6)
	v_fmac_f32_dpp v15, v249, v56 quad_perm:[0,0,0,0] row_mask:0xf bank_mask:0xf
	v_fmac_f32_dpp v18, v249, v57 quad_perm:[1,1,1,1] row_mask:0xf bank_mask:0xf
	v_fmac_f32_dpp v83, v249, v58 quad_perm:[2,2,2,2] row_mask:0xf bank_mask:0xf
	v_fmac_f32_dpp v100, v249, v59 quad_perm:[3,3,3,3] row_mask:0xf bank_mask:0xf
	s_waitcnt lgkmcnt(5)
	v_fmac_f32_dpp v15, v250, v60 quad_perm:[0,0,0,0] row_mask:0xf bank_mask:0xf
	v_fmac_f32_dpp v18, v250, v61 quad_perm:[1,1,1,1] row_mask:0xf bank_mask:0xf
	v_fmac_f32_dpp v83, v250, v62 quad_perm:[2,2,2,2] row_mask:0xf bank_mask:0xf
	v_fmac_f32_dpp v100, v250, v63 quad_perm:[3,3,3,3] row_mask:0xf bank_mask:0xf
	s_waitcnt lgkmcnt(4)
	v_fmac_f32_dpp v15, v251, v64 quad_perm:[0,0,0,0] row_mask:0xf bank_mask:0xf
	v_fmac_f32_dpp v18, v251, v65 quad_perm:[1,1,1,1] row_mask:0xf bank_mask:0xf
	v_fmac_f32_dpp v83, v251, v66 quad_perm:[2,2,2,2] row_mask:0xf bank_mask:0xf
	v_fmac_f32_dpp v100, v251, v67 quad_perm:[3,3,3,3] row_mask:0xf bank_mask:0xf
	s_waitcnt lgkmcnt(3)
	v_fmac_f32_dpp v15, v240, v68 quad_perm:[0,0,0,0] row_mask:0xf bank_mask:0xf
	v_fmac_f32_dpp v18, v240, v69 quad_perm:[1,1,1,1] row_mask:0xf bank_mask:0xf
	v_fmac_f32_dpp v83, v240, v70 quad_perm:[2,2,2,2] row_mask:0xf bank_mask:0xf
	v_fmac_f32_dpp v100, v240, v71 quad_perm:[3,3,3,3] row_mask:0xf bank_mask:0xf
	s_waitcnt lgkmcnt(2)
	v_fmac_f32_dpp v15, v241, v72 quad_perm:[0,0,0,0] row_mask:0xf bank_mask:0xf
	v_fmac_f32_dpp v18, v241, v73 quad_perm:[1,1,1,1] row_mask:0xf bank_mask:0xf
	v_fmac_f32_dpp v83, v241, v74 quad_perm:[2,2,2,2] row_mask:0xf bank_mask:0xf
	v_fmac_f32_dpp v100, v241, v75 quad_perm:[3,3,3,3] row_mask:0xf bank_mask:0xf
	s_waitcnt lgkmcnt(1)
	v_fmac_f32_dpp v15, v242, v76 quad_perm:[0,0,0,0] row_mask:0xf bank_mask:0xf
	v_fmac_f32_dpp v18, v242, v77 quad_perm:[1,1,1,1] row_mask:0xf bank_mask:0xf
	v_fmac_f32_dpp v83, v242, v78 quad_perm:[2,2,2,2] row_mask:0xf bank_mask:0xf
	v_fmac_f32_dpp v100, v242, v79 quad_perm:[3,3,3,3] row_mask:0xf bank_mask:0xf
	s_waitcnt lgkmcnt(0)
	v_fmac_f32_dpp v15, v243, v80 quad_perm:[0,0,0,0] row_mask:0xf bank_mask:0xf
	v_fmac_f32_dpp v18, v243, v81 quad_perm:[1,1,1,1] row_mask:0xf bank_mask:0xf
	v_fmac_f32_dpp v83, v243, v82 quad_perm:[2,2,2,2] row_mask:0xf bank_mask:0xf
	v_add_f32_e32 v11, v15, v18
	v_add_f32_e32 v15, v100, v83
	v_add_f32_e32 v11, v11, v15
	v_sub_f32_e32 v11, v16, v11
	s_and_saveexec_b64 s[0:1], s[16:17]
	s_xor_b64 s[0:1], exec, s[0:1]
	s_cbranch_execz .LBB0_941
	v_lshl_add_u64 v[84:85], v[22:23], 1, s[70:71]
	v_add_co_u32_e32 v88, vcc, 0x4000, v84
	v_cvt_pk_bf16_f32 v2, v2, s0
	s_mov_b64 s[24:25], 0x4000
	v_addc_co_u32_e32 v89, vcc, 0, v85, vcc
	v_lshl_add_u64 v[86:87], v[84:85], 0, s[24:25]
	global_store_short v[88:89], v2, off
	v_cvt_pk_bf16_f32 v2, v3, s0
	global_store_short v[86:87], v2, off offset:256
	v_cvt_pk_bf16_f32 v2, v4, s0
	global_store_short v[86:87], v2, off offset:512
	v_cvt_pk_bf16_f32 v2, v5, s0
	global_store_short v[86:87], v2, off offset:768
	v_cvt_pk_bf16_f32 v2, v6, s0
	global_store_short v[86:87], v2, off offset:1024
	v_cvt_pk_bf16_f32 v2, v7, s0
	global_store_short v[86:87], v2, off offset:1280
	v_cvt_pk_bf16_f32 v2, v8, s0
	global_store_short v[86:87], v2, off offset:1536
	v_cvt_pk_bf16_f32 v2, v9, s0
	global_store_short v[86:87], v2, off offset:1792
	v_cvt_pk_bf16_f32 v2, v10, s0
	global_store_short v[86:87], v2, off offset:2048
	v_cvt_pk_bf16_f32 v2, v12, s0
	global_store_short v[86:87], v2, off offset:2304
	v_cvt_pk_bf16_f32 v2, v13, s0
	global_store_short v[86:87], v2, off offset:2560
	v_cvt_pk_bf16_f32 v2, v14, s0
	global_store_short v[86:87], v2, off offset:2816
	v_cvt_pk_bf16_f32 v2, v17, s0
	global_store_short v[86:87], v2, off offset:3072
	v_cvt_pk_bf16_f32 v2, v19, s0
	global_store_short v[86:87], v2, off offset:3328
	v_cvt_pk_bf16_f32 v2, v28, s0
	global_store_short v[86:87], v2, off offset:3584
	v_cvt_pk_bf16_f32 v2, v35, s0
	s_movk_i32 s24, 0x5000
	global_store_short v[86:87], v2, off offset:3840
	v_add_co_u32_e32 v2, vcc, s24, v84
	s_movk_i32 s24, 0x6000
	s_nop 0
	v_addc_co_u32_e32 v3, vcc, 0, v85, vcc
	v_add_co_u32_e32 v4, vcc, s24, v84
	v_cvt_pk_bf16_f32 v6, v36, s0
	s_nop 0
	v_addc_co_u32_e32 v5, vcc, 0, v85, vcc
	global_store_short v[4:5], v6, off offset:-4096
	v_cvt_pk_bf16_f32 v6, v37, s0
	global_store_short v[2:3], v6, off offset:256
	v_cvt_pk_bf16_f32 v6, v38, s0
	global_store_short v[2:3], v6, off offset:512
	v_cvt_pk_bf16_f32 v6, v39, s0
	global_store_short v[2:3], v6, off offset:768
	v_cvt_pk_bf16_f32 v6, v40, s0
	global_store_short v[2:3], v6, off offset:1024
	v_cvt_pk_bf16_f32 v6, v41, s0
	global_store_short v[2:3], v6, off offset:1280
	v_cvt_pk_bf16_f32 v6, v42, s0
	global_store_short v[2:3], v6, off offset:1536
	v_cvt_pk_bf16_f32 v6, v43, s0
	global_store_short v[2:3], v6, off offset:1792
	v_cvt_pk_bf16_f32 v6, v44, s0
	global_store_short v[2:3], v6, off offset:2048
	v_cvt_pk_bf16_f32 v6, v45, s0
	global_store_short v[2:3], v6, off offset:2304
	v_cvt_pk_bf16_f32 v6, v46, s0
	global_store_short v[2:3], v6, off offset:2560
	v_cvt_pk_bf16_f32 v6, v47, s0
	global_store_short v[2:3], v6, off offset:2816
	v_cvt_pk_bf16_f32 v6, v48, s0
	global_store_short v[2:3], v6, off offset:3072
	v_cvt_pk_bf16_f32 v6, v49, s0
	global_store_short v[2:3], v6, off offset:3328
	v_cvt_pk_bf16_f32 v6, v50, s0
	global_store_short v[2:3], v6, off offset:3584
	v_cvt_pk_bf16_f32 v6, v51, s0
	global_store_short v[2:3], v6, off offset:3840
	v_cvt_pk_bf16_f32 v2, v52, s0
	global_store_short v[4:5], v2, off
	v_cvt_pk_bf16_f32 v2, v53, s0
	global_store_short v[4:5], v2, off offset:256
	v_cvt_pk_bf16_f32 v2, v54, s0
	global_store_short v[4:5], v2, off offset:512
	v_cvt_pk_bf16_f32 v2, v55, s0
	global_store_short v[4:5], v2, off offset:768
	v_cvt_pk_bf16_f32 v2, v56, s0
	global_store_short v[4:5], v2, off offset:1024
	v_cvt_pk_bf16_f32 v2, v57, s0
	global_store_short v[4:5], v2, off offset:1280
	v_cvt_pk_bf16_f32 v2, v58, s0
	global_store_short v[4:5], v2, off offset:1536
	v_cvt_pk_bf16_f32 v2, v59, s0
	global_store_short v[4:5], v2, off offset:1792
	v_cvt_pk_bf16_f32 v2, v60, s0
	global_store_short v[4:5], v2, off offset:2048
	v_cvt_pk_bf16_f32 v2, v61, s0
	global_store_short v[4:5], v2, off offset:2304
	v_cvt_pk_bf16_f32 v2, v62, s0
	global_store_short v[4:5], v2, off offset:2560
	v_cvt_pk_bf16_f32 v2, v63, s0
	global_store_short v[4:5], v2, off offset:2816
	v_cvt_pk_bf16_f32 v2, v64, s0
	global_store_short v[4:5], v2, off offset:3072
	v_cvt_pk_bf16_f32 v2, v65, s0
	global_store_short v[4:5], v2, off offset:3328
	v_cvt_pk_bf16_f32 v2, v66, s0
	global_store_short v[4:5], v2, off offset:3584
	v_cvt_pk_bf16_f32 v2, v67, s0
	s_movk_i32 s24, 0x7000
	global_store_short v[4:5], v2, off offset:3840
	v_add_co_u32_e32 v2, vcc, s24, v84
	v_cvt_pk_bf16_f32 v4, v68, s0
	s_nop 0
	v_addc_co_u32_e32 v3, vcc, 0, v85, vcc
	global_store_short v[2:3], v4, off
	v_cvt_pk_bf16_f32 v4, v69, s0
	global_store_short v[2:3], v4, off offset:256
	v_cvt_pk_bf16_f32 v4, v70, s0
	global_store_short v[2:3], v4, off offset:512
	v_cvt_pk_bf16_f32 v4, v71, s0
	global_store_short v[2:3], v4, off offset:768
	v_cvt_pk_bf16_f32 v4, v72, s0
	global_store_short v[2:3], v4, off offset:1024
	v_cvt_pk_bf16_f32 v4, v73, s0
	global_store_short v[2:3], v4, off offset:1280
	v_cvt_pk_bf16_f32 v4, v74, s0
	global_store_short v[2:3], v4, off offset:1536
	v_cvt_pk_bf16_f32 v4, v75, s0
	global_store_short v[2:3], v4, off offset:1792
	v_cvt_pk_bf16_f32 v4, v76, s0
	global_store_short v[2:3], v4, off offset:2048
	v_cvt_pk_bf16_f32 v4, v77, s0
	global_store_short v[2:3], v4, off offset:2304
	v_cvt_pk_bf16_f32 v4, v78, s0
	global_store_short v[2:3], v4, off offset:2560
	v_cvt_pk_bf16_f32 v4, v79, s0
	global_store_short v[2:3], v4, off offset:2816
	v_cvt_pk_bf16_f32 v4, v80, s0
	global_store_short v[2:3], v4, off offset:3072
	v_cvt_pk_bf16_f32 v4, v81, s0
	global_store_short v[2:3], v4, off offset:3328
	v_cvt_pk_bf16_f32 v4, v82, s0
	global_store_short v[2:3], v4, off offset:3584
	v_cvt_pk_bf16_f32 v4, v11, s0
	global_store_short v[2:3], v4, off offset:3840
	s_andn2_saveexec_b64 s[0:1], s[0:1]
	s_cbranch_execnz .LBB0_942
